# SSM pass 2: u rows prefetched (it 0 before the carry step, it 1 during it 0) into dead registers and copied at the iteration top; in-loop vmcnt waits removed; on top of v155
# speedup vs baseline: 1.0001x; 1.0001x over previous
; __device__ __forceinline__ f2v fma2(f2v a, f2v b, f2v c) { return __builtin_elementwise_fma(a, b, c); }
; __device__ __forceinline__ void ssm_phase(Frame& F) {
;     ...
; #pragma unroll 1
;         for (int it = 0; it < 2; ++it) {
;             f2v Sre0 = {0.f, 0.f}, Sim0 = {0.f, 0.f}, Sre1 = {0.f, 0.f}, Sim1 = {0.f, 0.f};
; #pragma unroll
;             for (int s = 0; s < 8; ++s) {
;                 const f32x16 D0 = __builtin_amdgcn_mfma_f32_32x32x16_bf16(afr[s], bfrag[0], z, 0, 0, 0), D1 = __builtin_amdgcn_mfma_f32_32x32x16_bf16(afr[s], bfrag[1], z, 0, 0, 0),
;                              D2 = __builtin_amdgcn_mfma_f32_32x32x16_bf16(afr[s], bfrag[2], z, 0, 0, 0), D3 = __builtin_amdgcn_mfma_f32_32x32x16_bf16(afr[s], bfrag[3], z, 0, 0, 0);
; #pragma unroll
;                 for (int t = 0; t < 8; ++t) {
;                     const f2v d0 = {D0[2 * t], D0[2 * t + 1]}, d1 = {D1[2 * t], D1[2 * t + 1]}, d2 = {D2[2 * t], D2[2 * t + 1]}, d3 = {D3[2 * t], D3[2 * t + 1]};
;                     const f2v nr0 = fma2(AR0, Sre0, fma2(NAI0, Sim0, d0)), ni0 = fma2(AR0, Sim0, fma2(AI0, Sre0, d2));
;                     const f2v nr1 = fma2(AR1, Sre1, fma2(NAI1, Sim1, d1)), ni1 = fma2(AR1, Sim1, fma2(AI1, Sre1, d3));
;                     Sre0 = nr0; Sim0 = ni0; Sre1 = nr1; Sim1 = ni1; }
;             }
.LBB0_324:
	s_waitcnt vmcnt(15)
	v_mfma_f32_32x32x16_bf16 v[32:47], v[16:19], v[64:67], 0
	s_and_b64 vcc, exec, s[24:25]
	s_mov_b64 s[24:25], 0
	v_mfma_f32_32x32x16_bf16 v[0:15], v[16:19], v[68:71], 0
	s_nop 8
	v_fma_f32 v32, v178, 0, v32
	v_fma_f32 v33, v179, 0, v33
	v_fma_f32 v32, v168, 0, v32
	v_fma_f32 v33, v169, 0, v33
	v_mfma_f32_32x32x16_bf16 v[48:63], v[16:19], v[72:75], 0
	v_fma_f32 v0, v180, 0, v0
	v_fma_f32 v1, v181, 0, v1
	v_fma_f32 v0, v170, 0, v0
	v_fma_f32 v1, v171, 0, v1
	v_mfma_f32_32x32x16_bf16 v[16:31], v[16:19], v[76:79], 0
	s_nop 6
	v_fma_f32 v48, v172, 0, v48
	v_fma_f32 v49, v173, 0, v49
	v_fma_f32 v48, v168, 0, v48
	v_fma_f32 v49, v169, 0, v49
	v_fma_f32 v34, v178, v48, v34
	v_fma_f32 v35, v179, v49, v35
	v_pk_fma_f32 v[16:17], v[174:175], 0, v[16:17] op_sel_hi:[1,0,1]
	s_nop 0
	v_pk_fma_f32 v[16:17], v[170:171], 0, v[16:17] op_sel_hi:[1,0,1]
	v_pk_fma_f32 v[34:35], v[168:169], v[32:33], v[34:35]
	v_pk_fma_f32 v[2:3], v[180:181], v[16:17], v[2:3]
	v_pk_fma_f32 v[32:33], v[172:173], v[32:33], v[50:51]
	v_pk_fma_f32 v[2:3], v[170:171], v[0:1], v[2:3]
	v_pk_fma_f32 v[0:1], v[174:175], v[0:1], v[18:19]
	v_pk_fma_f32 v[32:33], v[168:169], v[48:49], v[32:33]
	v_pk_fma_f32 v[0:1], v[170:171], v[16:17], v[0:1]
	v_pk_fma_f32 v[18:19], v[172:173], v[34:35], v[52:53]
	v_pk_fma_f32 v[4:5], v[180:181], v[0:1], v[4:5]
	v_pk_fma_f32 v[16:17], v[178:179], v[32:33], v[36:37]
	v_pk_fma_f32 v[18:19], v[168:169], v[32:33], v[18:19]
	v_pk_fma_f32 v[4:5], v[170:171], v[2:3], v[4:5]
	v_pk_fma_f32 v[2:3], v[174:175], v[2:3], v[20:21]
	v_pk_fma_f32 v[16:17], v[168:169], v[34:35], v[16:17]
	v_pk_fma_f32 v[0:1], v[170:171], v[0:1], v[2:3]
	v_pk_fma_f32 v[2:3], v[178:179], v[18:19], v[38:39]
	v_pk_fma_f32 v[6:7], v[180:181], v[0:1], v[6:7]
	v_pk_fma_f32 v[2:3], v[168:169], v[16:17], v[2:3]
	v_pk_fma_f32 v[16:17], v[172:173], v[16:17], v[54:55]
	v_pk_fma_f32 v[6:7], v[170:171], v[4:5], v[6:7]
	v_pk_fma_f32 v[16:17], v[168:169], v[18:19], v[16:17]
	v_pk_fma_f32 v[4:5], v[174:175], v[4:5], v[22:23]
	s_nop 0
	v_pk_fma_f32 v[0:1], v[170:171], v[0:1], v[4:5]
	v_pk_fma_f32 v[4:5], v[178:179], v[16:17], v[40:41]
	v_pk_fma_f32 v[8:9], v[180:181], v[0:1], v[8:9]
	v_pk_fma_f32 v[4:5], v[168:169], v[2:3], v[4:5]
	v_pk_fma_f32 v[2:3], v[172:173], v[2:3], v[56:57]
	v_pk_fma_f32 v[8:9], v[170:171], v[6:7], v[8:9]
	v_pk_fma_f32 v[2:3], v[168:169], v[16:17], v[2:3]
	v_pk_fma_f32 v[6:7], v[174:175], v[6:7], v[24:25]
	s_nop 0
	v_pk_fma_f32 v[0:1], v[170:171], v[0:1], v[6:7]
	v_pk_fma_f32 v[6:7], v[178:179], v[2:3], v[42:43]
	s_nop 0
	v_pk_fma_f32 v[6:7], v[168:169], v[4:5], v[6:7]
	v_pk_fma_f32 v[4:5], v[172:173], v[4:5], v[58:59]
	s_nop 0
	v_pk_fma_f32 v[2:3], v[168:169], v[2:3], v[4:5]
	v_pk_fma_f32 v[4:5], v[180:181], v[0:1], v[10:11]
	s_nop 0
	v_pk_fma_f32 v[4:5], v[170:171], v[8:9], v[4:5]
	v_pk_fma_f32 v[8:9], v[174:175], v[8:9], v[26:27]
	s_nop 0
	v_pk_fma_f32 v[0:1], v[170:171], v[0:1], v[8:9]
	v_pk_fma_f32 v[8:9], v[178:179], v[2:3], v[44:45]
	s_nop 0
	v_pk_fma_f32 v[8:9], v[168:169], v[6:7], v[8:9]
	v_pk_fma_f32 v[6:7], v[172:173], v[6:7], v[60:61]
	s_nop 0
	v_pk_fma_f32 v[2:3], v[168:169], v[2:3], v[6:7]
	v_pk_fma_f32 v[6:7], v[180:181], v[0:1], v[12:13]
	s_nop 0
	v_pk_fma_f32 v[6:7], v[170:171], v[4:5], v[6:7]
	v_pk_fma_f32 v[4:5], v[174:175], v[4:5], v[28:29]
	s_nop 0
	v_pk_fma_f32 v[0:1], v[170:171], v[0:1], v[4:5]
	v_pk_fma_f32 v[4:5], v[178:179], v[2:3], v[46:47]
	s_waitcnt vmcnt(14)
	v_mfma_f32_32x32x16_bf16 v[32:47], v[152:155], v[64:67], 0
	v_fma_f32 v182, v168, v8, v4
	v_fma_f32 v183, v169, v9, v5
	v_fma_f32 v4, v172, v8, v62
	v_fma_f32 v5, v173, v9, v63
	v_fma_f32 v186, v168, v2, v4
	v_fma_f32 v187, v169, v3, v5
	v_pk_fma_f32 v[2:3], v[180:181], v[0:1], v[14:15]
	s_nop 4
	v_pk_fma_f32 v[32:33], v[178:179], v[186:187], v[32:33]
	v_pk_fma_f32 v[184:185], v[170:171], v[6:7], v[2:3]
	v_pk_fma_f32 v[2:3], v[174:175], v[6:7], v[30:31]
	v_mfma_f32_32x32x16_bf16 v[16:31], v[152:155], v[76:79], 0
	v_fma_f32 v188, v170, v0, v2
	v_fma_f32 v189, v171, v1, v3
	v_fma_f32 v32, v168, v182, v32
	v_fma_f32 v33, v169, v183, v33
	v_mfma_f32_32x32x16_bf16 v[0:15], v[152:155], v[68:71], 0
	s_nop 6
	v_fma_f32 v16, v174, v184, v16
	v_fma_f32 v17, v175, v185, v17
	v_fma_f32 v16, v170, v188, v16
	v_fma_f32 v17, v171, v189, v17
	v_mfma_f32_32x32x16_bf16 v[48:63], v[152:155], v[72:75], 0
	v_fma_f32 v0, v180, v188, v0
	v_fma_f32 v1, v181, v189, v1
	v_fma_f32 v2, v180, v16, v2
	v_fma_f32 v3, v181, v17, v3
	v_fma_f32 v0, v170, v184, v0
	v_fma_f32 v1, v171, v185, v1
	v_pk_fma_f32 v[2:3], v[170:171], v[0:1], v[2:3]
	v_pk_fma_f32 v[0:1], v[174:175], v[0:1], v[18:19]
	s_nop 3
	v_pk_fma_f32 v[48:49], v[172:173], v[182:183], v[48:49]
	s_nop 0
	v_pk_fma_f32 v[48:49], v[168:169], v[186:187], v[48:49]
	v_pk_fma_f32 v[0:1], v[170:171], v[16:17], v[0:1]
	v_pk_fma_f32 v[34:35], v[178:179], v[48:49], v[34:35]
	v_pk_fma_f32 v[4:5], v[180:181], v[0:1], v[4:5]
	v_pk_fma_f32 v[34:35], v[168:169], v[32:33], v[34:35]
	v_pk_fma_f32 v[32:33], v[172:173], v[32:33], v[50:51]
	v_pk_fma_f32 v[18:19], v[172:173], v[34:35], v[52:53]
	v_pk_fma_f32 v[32:33], v[168:169], v[48:49], v[32:33]
	v_pk_fma_f32 v[4:5], v[170:171], v[2:3], v[4:5]
	v_pk_fma_f32 v[16:17], v[178:179], v[32:33], v[36:37]
	v_pk_fma_f32 v[18:19], v[168:169], v[32:33], v[18:19]
	v_pk_fma_f32 v[2:3], v[174:175], v[2:3], v[20:21]
	v_pk_fma_f32 v[16:17], v[168:169], v[34:35], v[16:17]
	v_pk_fma_f32 v[0:1], v[170:171], v[0:1], v[2:3]
	v_pk_fma_f32 v[2:3], v[178:179], v[18:19], v[38:39]
	v_pk_fma_f32 v[6:7], v[180:181], v[0:1], v[6:7]
	v_pk_fma_f32 v[2:3], v[168:169], v[16:17], v[2:3]
	v_pk_fma_f32 v[16:17], v[172:173], v[16:17], v[54:55]
; __device__ __forceinline__ f2v fma2(f2v a, f2v b, f2v c) { return __builtin_elementwise_fma(a, b, c); }
; __device__ __forceinline__ void ssm_phase(Frame& F) {
;     ...
;             for (int s = 0; s < 8; ++s) {
;                 const f32x16 D0 = __builtin_amdgcn_mfma_f32_32x32x16_bf16(afr[s], bfrag[0], z, 0, 0, 0), D1 = __builtin_amdgcn_mfma_f32_32x32x16_bf16(afr[s], bfrag[1], z, 0, 0, 0),
;                              D2 = __builtin_amdgcn_mfma_f32_32x32x16_bf16(afr[s], bfrag[2], z, 0, 0, 0), D3 = __builtin_amdgcn_mfma_f32_32x32x16_bf16(afr[s], bfrag[3], z, 0, 0, 0);
; #pragma unroll
;                 for (int t = 0; t < 8; ++t) {
;                     const f2v d0 = {D0[2 * t], D0[2 * t + 1]}, d1 = {D1[2 * t], D1[2 * t + 1]}, d2 = {D2[2 * t], D2[2 * t + 1]}, d3 = {D3[2 * t], D3[2 * t + 1]};
;                     const f2v nr0 = fma2(AR0, Sre0, fma2(NAI0, Sim0, d0)), ni0 = fma2(AR0, Sim0, fma2(AI0, Sre0, d2));
;                     const f2v nr1 = fma2(AR1, Sre1, fma2(NAI1, Sim1, d1)), ni1 = fma2(AR1, Sim1, fma2(AI1, Sre1, d3));
;                     Sre0 = nr0; Sim0 = ni0; Sre1 = nr1; Sim1 = ni1; }
;             }
	v_pk_fma_f32 v[6:7], v[170:171], v[4:5], v[6:7]
	v_pk_fma_f32 v[16:17], v[168:169], v[18:19], v[16:17]
	v_pk_fma_f32 v[4:5], v[174:175], v[4:5], v[22:23]
	s_nop 0
	v_pk_fma_f32 v[0:1], v[170:171], v[0:1], v[4:5]
	v_pk_fma_f32 v[4:5], v[178:179], v[16:17], v[40:41]
	v_pk_fma_f32 v[8:9], v[180:181], v[0:1], v[8:9]
	v_pk_fma_f32 v[4:5], v[168:169], v[2:3], v[4:5]
	v_pk_fma_f32 v[2:3], v[172:173], v[2:3], v[56:57]
	v_pk_fma_f32 v[8:9], v[170:171], v[6:7], v[8:9]
	v_pk_fma_f32 v[2:3], v[168:169], v[16:17], v[2:3]
	v_pk_fma_f32 v[6:7], v[174:175], v[6:7], v[24:25]
	s_nop 0
	v_pk_fma_f32 v[0:1], v[170:171], v[0:1], v[6:7]
	v_pk_fma_f32 v[6:7], v[178:179], v[2:3], v[42:43]
	s_nop 0
	v_pk_fma_f32 v[6:7], v[168:169], v[4:5], v[6:7]
	v_pk_fma_f32 v[4:5], v[172:173], v[4:5], v[58:59]
	s_nop 0
	v_pk_fma_f32 v[2:3], v[168:169], v[2:3], v[4:5]
	v_pk_fma_f32 v[4:5], v[180:181], v[0:1], v[10:11]
	s_nop 0
	v_pk_fma_f32 v[4:5], v[170:171], v[8:9], v[4:5]
	v_pk_fma_f32 v[8:9], v[174:175], v[8:9], v[26:27]
	s_nop 0
	v_pk_fma_f32 v[0:1], v[170:171], v[0:1], v[8:9]
	v_pk_fma_f32 v[8:9], v[178:179], v[2:3], v[44:45]
	s_nop 0
	v_pk_fma_f32 v[8:9], v[168:169], v[6:7], v[8:9]
	v_pk_fma_f32 v[6:7], v[172:173], v[6:7], v[60:61]
	s_nop 0
	v_pk_fma_f32 v[2:3], v[168:169], v[2:3], v[6:7]
	v_pk_fma_f32 v[6:7], v[180:181], v[0:1], v[12:13]
	s_nop 0
	v_pk_fma_f32 v[6:7], v[170:171], v[4:5], v[6:7]
	v_pk_fma_f32 v[4:5], v[174:175], v[4:5], v[28:29]
	s_nop 0
	v_pk_fma_f32 v[0:1], v[170:171], v[0:1], v[4:5]
	v_pk_fma_f32 v[4:5], v[178:179], v[2:3], v[46:47]
	s_waitcnt vmcnt(13)
	v_mfma_f32_32x32x16_bf16 v[32:47], v[148:151], v[72:75], 0
	v_fma_f32 v152, v168, v8, v4
	v_fma_f32 v153, v169, v9, v5
	v_fma_f32 v4, v172, v8, v62
	v_fma_f32 v5, v173, v9, v63
	v_fma_f32 v182, v168, v2, v4
	v_fma_f32 v183, v169, v3, v5
	v_pk_fma_f32 v[2:3], v[180:181], v[0:1], v[14:15]
	s_nop 4
	v_pk_fma_f32 v[32:33], v[172:173], v[152:153], v[32:33]
	v_pk_fma_f32 v[154:155], v[170:171], v[6:7], v[2:3]
	v_pk_fma_f32 v[2:3], v[174:175], v[6:7], v[30:31]
	v_mfma_f32_32x32x16_bf16 v[48:63], v[148:151], v[76:79], 0
	v_fma_f32 v184, v170, v0, v2
	v_fma_f32 v185, v171, v1, v3
	v_fma_f32 v32, v168, v182, v32
	v_fma_f32 v33, v169, v183, v33
	v_mfma_f32_32x32x16_bf16 v[0:15], v[148:151], v[64:67], 0
	s_nop 6
	v_fma_f32 v48, v174, v154, v48
	v_fma_f32 v49, v175, v155, v49
	v_fma_f32 v48, v170, v184, v48
	v_fma_f32 v49, v171, v185, v49
	v_mfma_f32_32x32x16_bf16 v[16:31], v[148:151], v[68:71], 0
	v_fma_f32 v0, v178, v182, v0
	v_fma_f32 v1, v179, v183, v1
	v_fma_f32 v2, v178, v32, v2
	v_fma_f32 v3, v179, v33, v3
	v_fma_f32 v0, v168, v152, v0
	v_fma_f32 v1, v169, v153, v1
	v_pk_fma_f32 v[2:3], v[168:169], v[0:1], v[2:3]
	v_pk_fma_f32 v[0:1], v[172:173], v[0:1], v[34:35]
	s_nop 3
	v_pk_fma_f32 v[16:17], v[180:181], v[184:185], v[16:17]
	s_nop 0
	v_pk_fma_f32 v[16:17], v[170:171], v[154:155], v[16:17]
	v_pk_fma_f32 v[0:1], v[168:169], v[32:33], v[0:1]
	v_pk_fma_f32 v[18:19], v[180:181], v[48:49], v[18:19]
	v_pk_fma_f32 v[4:5], v[178:179], v[0:1], v[4:5]
	v_pk_fma_f32 v[18:19], v[170:171], v[16:17], v[18:19]
	v_pk_fma_f32 v[16:17], v[174:175], v[16:17], v[50:51]
	v_pk_fma_f32 v[4:5], v[168:169], v[2:3], v[4:5]
	v_pk_fma_f32 v[16:17], v[170:171], v[48:49], v[16:17]
	v_pk_fma_f32 v[2:3], v[172:173], v[2:3], v[36:37]
	s_nop 0
	v_pk_fma_f32 v[0:1], v[168:169], v[0:1], v[2:3]
	v_pk_fma_f32 v[2:3], v[180:181], v[16:17], v[20:21]
	v_pk_fma_f32 v[6:7], v[178:179], v[0:1], v[6:7]
	v_pk_fma_f32 v[2:3], v[170:171], v[18:19], v[2:3]
	v_pk_fma_f32 v[18:19], v[174:175], v[18:19], v[52:53]
	v_pk_fma_f32 v[6:7], v[168:169], v[4:5], v[6:7]
	v_pk_fma_f32 v[16:17], v[170:171], v[16:17], v[18:19]
	v_pk_fma_f32 v[4:5], v[172:173], v[4:5], v[38:39]
	s_nop 0
	v_pk_fma_f32 v[0:1], v[168:169], v[0:1], v[4:5]
	v_pk_fma_f32 v[4:5], v[180:181], v[16:17], v[22:23]
	v_pk_fma_f32 v[8:9], v[178:179], v[0:1], v[8:9]
	v_pk_fma_f32 v[4:5], v[170:171], v[2:3], v[4:5]
	v_pk_fma_f32 v[2:3], v[174:175], v[2:3], v[54:55]
	v_pk_fma_f32 v[8:9], v[168:169], v[6:7], v[8:9]
	v_pk_fma_f32 v[2:3], v[170:171], v[16:17], v[2:3]
	v_pk_fma_f32 v[6:7], v[172:173], v[6:7], v[40:41]
	s_nop 0
	v_pk_fma_f32 v[0:1], v[168:169], v[0:1], v[6:7]
	v_pk_fma_f32 v[6:7], v[180:181], v[2:3], v[24:25]
	s_nop 0
	v_pk_fma_f32 v[6:7], v[170:171], v[4:5], v[6:7]
	v_pk_fma_f32 v[4:5], v[174:175], v[4:5], v[56:57]
	s_nop 0
	v_pk_fma_f32 v[2:3], v[170:171], v[2:3], v[4:5]
	v_pk_fma_f32 v[4:5], v[178:179], v[0:1], v[10:11]
	s_nop 0
	v_pk_fma_f32 v[4:5], v[168:169], v[8:9], v[4:5]
	v_pk_fma_f32 v[8:9], v[172:173], v[8:9], v[42:43]
	s_nop 0
	v_pk_fma_f32 v[0:1], v[168:169], v[0:1], v[8:9]
	v_pk_fma_f32 v[8:9], v[180:181], v[2:3], v[26:27]
	s_nop 0
	v_pk_fma_f32 v[8:9], v[170:171], v[6:7], v[8:9]
	v_pk_fma_f32 v[6:7], v[174:175], v[6:7], v[58:59]
	s_nop 0
	v_pk_fma_f32 v[2:3], v[170:171], v[2:3], v[6:7]
	v_pk_fma_f32 v[6:7], v[178:179], v[0:1], v[12:13]
	s_nop 0
	v_pk_fma_f32 v[6:7], v[168:169], v[4:5], v[6:7]
	v_pk_fma_f32 v[4:5], v[172:173], v[4:5], v[44:45]
	s_nop 0
	v_pk_fma_f32 v[0:1], v[168:169], v[0:1], v[4:5]
	v_pk_fma_f32 v[4:5], v[180:181], v[2:3], v[28:29]
	s_nop 0
	v_pk_fma_f32 v[4:5], v[170:171], v[8:9], v[4:5]
	v_pk_fma_f32 v[8:9], v[174:175], v[8:9], v[60:61]
	s_nop 0
	v_pk_fma_f32 v[2:3], v[170:171], v[2:3], v[8:9]
	v_pk_fma_f32 v[8:9], v[178:179], v[0:1], v[14:15]
	s_nop 0
	v_pk_fma_f32 v[148:149], v[168:169], v[6:7], v[8:9]
	v_pk_fma_f32 v[6:7], v[172:173], v[6:7], v[46:47]
	s_waitcnt vmcnt(12)
; #define LAS __attribute__((address_space(3)))
; __device__ __forceinline__ f2v fma2(f2v a, f2v b, f2v c) { return __builtin_elementwise_fma(a, b, c); }
; __device__ __forceinline__ void ssm_phase(Frame& F) {
;     ...
;             for (int s = 0; s < 8; ++s) {
;                 const f32x16 D0 = __builtin_amdgcn_mfma_f32_32x32x16_bf16(afr[s], bfrag[0], z, 0, 0, 0), D1 = __builtin_amdgcn_mfma_f32_32x32x16_bf16(afr[s], bfrag[1], z, 0, 0, 0),
;                              D2 = __builtin_amdgcn_mfma_f32_32x32x16_bf16(afr[s], bfrag[2], z, 0, 0, 0), D3 = __builtin_amdgcn_mfma_f32_32x32x16_bf16(afr[s], bfrag[3], z, 0, 0, 0);
; #pragma unroll
;                 for (int t = 0; t < 8; ++t) {
;                     const f2v d0 = {D0[2 * t], D0[2 * t + 1]}, d1 = {D1[2 * t], D1[2 * t + 1]}, d2 = {D2[2 * t], D2[2 * t + 1]}, d3 = {D3[2 * t], D3[2 * t + 1]};
;                     const f2v nr0 = fma2(AR0, Sre0, fma2(NAI0, Sim0, d0)), ni0 = fma2(AR0, Sim0, fma2(AI0, Sre0, d2));
;                     const f2v nr1 = fma2(AR1, Sre1, fma2(NAI1, Sim1, d1)), ni1 = fma2(AR1, Sim1, fma2(AI1, Sre1, d3));
;                     Sre0 = nr0; Sim0 = ni0; Sre1 = nr1; Sim1 = ni1; }
;             }
; #pragma unroll
;             for (int e = 0; e < 2; ++e) { LAS float* fo = FS + (F.wave + 8 * (2 * h + e) + 32 * it) * 128 + l31; fo[0] = Sre0[e]; fo[32] = Sre1[e]; fo[64] = Sim0[e]; fo[96] = Sim1[e]; }
; #pragma unroll
;             for (int s = 0; s < 8; ++s) afr[s] = anx[s];
	v_mfma_f32_32x32x16_bf16 v[32:47], v[144:147], v[72:75], 0
	v_fma_f32 v152, v168, v0, v6
	v_fma_f32 v153, v169, v1, v7
	v_fma_f32 v0, v180, v2, v30
	v_fma_f32 v1, v181, v3, v31
	v_fma_f32 v150, v170, v4, v0
	v_fma_f32 v151, v171, v5, v1
	v_pk_fma_f32 v[0:1], v[174:175], v[4:5], v[62:63]
	s_nop 4
	v_pk_fma_f32 v[32:33], v[172:173], v[148:149], v[32:33]
	v_pk_fma_f32 v[154:155], v[170:171], v[2:3], v[0:1]
	v_mfma_f32_32x32x16_bf16 v[0:15], v[144:147], v[64:67], 0
	v_fma_f32 v32, v168, v152, v32
	v_fma_f32 v33, v169, v153, v33
	v_mfma_f32_32x32x16_bf16 v[48:63], v[144:147], v[76:79], 0
	s_nop 8
	v_fma_f32 v0, v178, v152, v0
	v_fma_f32 v1, v179, v153, v1
	v_fma_f32 v2, v178, v32, v2
	v_fma_f32 v3, v179, v33, v3
	v_fma_f32 v0, v168, v148, v0
	v_fma_f32 v1, v169, v149, v1
	v_pk_fma_f32 v[2:3], v[168:169], v[0:1], v[2:3]
	v_pk_fma_f32 v[0:1], v[172:173], v[0:1], v[34:35]
	v_pk_fma_f32 v[48:49], v[174:175], v[150:151], v[48:49]
	v_mfma_f32_32x32x16_bf16 v[16:31], v[144:147], v[68:71], 0
	v_fma_f32 v48, v170, v154, v48
	v_fma_f32 v49, v171, v155, v49
	v_fma_f32 v0, v168, v32, v0
	v_fma_f32 v1, v169, v33, v1
	v_fma_f32 v4, v178, v0, v4
	v_fma_f32 v5, v179, v1, v5
	v_pk_fma_f32 v[4:5], v[168:169], v[2:3], v[4:5]
	v_pk_fma_f32 v[2:3], v[172:173], v[2:3], v[36:37]
	s_nop 3
	v_pk_fma_f32 v[16:17], v[180:181], v[154:155], v[16:17]
	v_pk_fma_f32 v[18:19], v[180:181], v[48:49], v[18:19]
	v_pk_fma_f32 v[16:17], v[170:171], v[150:151], v[16:17]
	v_pk_fma_f32 v[0:1], v[168:169], v[0:1], v[2:3]
	v_pk_fma_f32 v[18:19], v[170:171], v[16:17], v[18:19]
	v_pk_fma_f32 v[16:17], v[174:175], v[16:17], v[50:51]
	v_pk_fma_f32 v[6:7], v[178:179], v[0:1], v[6:7]
	v_pk_fma_f32 v[16:17], v[170:171], v[48:49], v[16:17]
	v_pk_fma_f32 v[6:7], v[168:169], v[4:5], v[6:7]
	v_pk_fma_f32 v[2:3], v[180:181], v[16:17], v[20:21]
	v_pk_fma_f32 v[4:5], v[172:173], v[4:5], v[38:39]
	v_pk_fma_f32 v[2:3], v[170:171], v[18:19], v[2:3]
	v_pk_fma_f32 v[18:19], v[174:175], v[18:19], v[52:53]
	v_pk_fma_f32 v[0:1], v[168:169], v[0:1], v[4:5]
	v_pk_fma_f32 v[16:17], v[170:171], v[16:17], v[18:19]
	v_pk_fma_f32 v[8:9], v[178:179], v[0:1], v[8:9]
	v_pk_fma_f32 v[4:5], v[180:181], v[16:17], v[22:23]
	v_pk_fma_f32 v[8:9], v[168:169], v[6:7], v[8:9]
	v_pk_fma_f32 v[4:5], v[170:171], v[2:3], v[4:5]
	v_pk_fma_f32 v[2:3], v[174:175], v[2:3], v[54:55]
	v_pk_fma_f32 v[6:7], v[172:173], v[6:7], v[40:41]
	v_pk_fma_f32 v[2:3], v[170:171], v[16:17], v[2:3]
	v_pk_fma_f32 v[0:1], v[168:169], v[0:1], v[6:7]
	v_pk_fma_f32 v[6:7], v[180:181], v[2:3], v[24:25]
	s_waitcnt vmcnt(6)
	v_mov_b64_e32 v[154:155], v[102:103]
	v_pk_fma_f32 v[6:7], v[170:171], v[4:5], v[6:7]
	v_pk_fma_f32 v[4:5], v[174:175], v[4:5], v[56:57]
	v_mov_b64_e32 v[152:153], v[100:101]
	v_pk_fma_f32 v[2:3], v[170:171], v[2:3], v[4:5]
	v_pk_fma_f32 v[4:5], v[178:179], v[0:1], v[10:11]
	s_nop 0
	v_pk_fma_f32 v[4:5], v[168:169], v[8:9], v[4:5]
	v_pk_fma_f32 v[8:9], v[172:173], v[8:9], v[42:43]
	s_nop 0
	v_pk_fma_f32 v[0:1], v[168:169], v[0:1], v[8:9]
	v_pk_fma_f32 v[8:9], v[180:181], v[2:3], v[26:27]
	s_nop 0
	v_pk_fma_f32 v[8:9], v[170:171], v[6:7], v[8:9]
	v_pk_fma_f32 v[6:7], v[174:175], v[6:7], v[58:59]
	s_nop 0
	v_pk_fma_f32 v[2:3], v[170:171], v[2:3], v[6:7]
	v_pk_fma_f32 v[6:7], v[178:179], v[0:1], v[12:13]
	s_nop 0
	v_pk_fma_f32 v[6:7], v[168:169], v[4:5], v[6:7]
	v_pk_fma_f32 v[4:5], v[172:173], v[4:5], v[44:45]
	s_nop 0
	v_pk_fma_f32 v[0:1], v[168:169], v[0:1], v[4:5]
	v_pk_fma_f32 v[4:5], v[180:181], v[2:3], v[28:29]
	s_nop 0
	v_pk_fma_f32 v[4:5], v[170:171], v[8:9], v[4:5]
	v_pk_fma_f32 v[8:9], v[174:175], v[8:9], v[60:61]
	s_nop 0
	v_pk_fma_f32 v[2:3], v[170:171], v[2:3], v[8:9]
	v_pk_fma_f32 v[8:9], v[178:179], v[0:1], v[14:15]
	s_nop 0
	v_pk_fma_f32 v[144:145], v[168:169], v[6:7], v[8:9]
	v_pk_fma_f32 v[6:7], v[172:173], v[6:7], v[46:47]
	v_mfma_f32_32x32x16_bf16 v[32:47], v[140:143], v[72:75], 0
	v_fma_f32 v148, v168, v0, v6
	v_fma_f32 v149, v169, v1, v7
	v_fma_f32 v0, v180, v2, v30
	v_fma_f32 v1, v181, v3, v31
	v_fma_f32 v146, v170, v4, v0
	v_fma_f32 v147, v171, v5, v1
	v_pk_fma_f32 v[0:1], v[174:175], v[4:5], v[62:63]
	s_nop 4
	v_pk_fma_f32 v[32:33], v[172:173], v[144:145], v[32:33]
	v_pk_fma_f32 v[150:151], v[170:171], v[2:3], v[0:1]
	v_mfma_f32_32x32x16_bf16 v[0:15], v[140:143], v[64:67], 0
	v_fma_f32 v32, v168, v148, v32
	v_fma_f32 v33, v169, v149, v33
	v_mfma_f32_32x32x16_bf16 v[48:63], v[140:143], v[76:79], 0
	s_nop 8
	v_fma_f32 v0, v178, v148, v0
	v_fma_f32 v1, v179, v149, v1
	v_fma_f32 v2, v178, v32, v2
	v_fma_f32 v3, v179, v33, v3
	v_fma_f32 v0, v168, v144, v0
	v_fma_f32 v1, v169, v145, v1
	v_pk_fma_f32 v[2:3], v[168:169], v[0:1], v[2:3]
	v_pk_fma_f32 v[0:1], v[172:173], v[0:1], v[34:35]
	v_pk_fma_f32 v[48:49], v[174:175], v[146:147], v[48:49]
	v_mfma_f32_32x32x16_bf16 v[16:31], v[140:143], v[68:71], 0
	v_fma_f32 v48, v170, v150, v48
	v_fma_f32 v49, v171, v151, v49
	v_fma_f32 v0, v168, v32, v0
	v_fma_f32 v1, v169, v33, v1
	v_fma_f32 v4, v178, v0, v4
	v_fma_f32 v5, v179, v1, v5
	v_pk_fma_f32 v[4:5], v[168:169], v[2:3], v[4:5]
	v_pk_fma_f32 v[2:3], v[172:173], v[2:3], v[36:37]
	s_nop 3
	v_pk_fma_f32 v[16:17], v[180:181], v[150:151], v[16:17]
	v_pk_fma_f32 v[18:19], v[180:181], v[48:49], v[18:19]
	v_pk_fma_f32 v[16:17], v[170:171], v[146:147], v[16:17]
	v_pk_fma_f32 v[0:1], v[168:169], v[0:1], v[2:3]
	v_pk_fma_f32 v[18:19], v[170:171], v[16:17], v[18:19]
	v_pk_fma_f32 v[16:17], v[174:175], v[16:17], v[50:51]
	v_pk_fma_f32 v[6:7], v[178:179], v[0:1], v[6:7]
	v_pk_fma_f32 v[16:17], v[170:171], v[48:49], v[16:17]
	v_pk_fma_f32 v[6:7], v[168:169], v[4:5], v[6:7]
	v_pk_fma_f32 v[2:3], v[180:181], v[16:17], v[20:21]
	v_pk_fma_f32 v[4:5], v[172:173], v[4:5], v[38:39]
	v_pk_fma_f32 v[2:3], v[170:171], v[18:19], v[2:3]
	v_pk_fma_f32 v[18:19], v[174:175], v[18:19], v[52:53]
	v_pk_fma_f32 v[0:1], v[168:169], v[0:1], v[4:5]
	v_pk_fma_f32 v[16:17], v[170:171], v[16:17], v[18:19]
	v_pk_fma_f32 v[8:9], v[178:179], v[0:1], v[8:9]
	v_pk_fma_f32 v[4:5], v[180:181], v[16:17], v[22:23]
	v_pk_fma_f32 v[8:9], v[168:169], v[6:7], v[8:9]
	v_pk_fma_f32 v[4:5], v[170:171], v[2:3], v[4:5]
	v_pk_fma_f32 v[2:3], v[174:175], v[2:3], v[54:55]
	v_pk_fma_f32 v[6:7], v[172:173], v[6:7], v[40:41]
	v_pk_fma_f32 v[2:3], v[170:171], v[16:17], v[2:3]
	v_pk_fma_f32 v[0:1], v[168:169], v[0:1], v[6:7]
	v_pk_fma_f32 v[6:7], v[180:181], v[2:3], v[24:25]
	s_waitcnt vmcnt(5)
; #define LAS __attribute__((address_space(3)))
; __device__ __forceinline__ f2v fma2(f2v a, f2v b, f2v c) { return __builtin_elementwise_fma(a, b, c); }
; __device__ __forceinline__ void ssm_phase(Frame& F) {
;     ...
;             for (int s = 0; s < 8; ++s) {
;                 const f32x16 D0 = __builtin_amdgcn_mfma_f32_32x32x16_bf16(afr[s], bfrag[0], z, 0, 0, 0), D1 = __builtin_amdgcn_mfma_f32_32x32x16_bf16(afr[s], bfrag[1], z, 0, 0, 0),
;                              D2 = __builtin_amdgcn_mfma_f32_32x32x16_bf16(afr[s], bfrag[2], z, 0, 0, 0), D3 = __builtin_amdgcn_mfma_f32_32x32x16_bf16(afr[s], bfrag[3], z, 0, 0, 0);
; #pragma unroll
;                 for (int t = 0; t < 8; ++t) {
;                     const f2v d0 = {D0[2 * t], D0[2 * t + 1]}, d1 = {D1[2 * t], D1[2 * t + 1]}, d2 = {D2[2 * t], D2[2 * t + 1]}, d3 = {D3[2 * t], D3[2 * t + 1]};
;                     const f2v nr0 = fma2(AR0, Sre0, fma2(NAI0, Sim0, d0)), ni0 = fma2(AR0, Sim0, fma2(AI0, Sre0, d2));
;                     const f2v nr1 = fma2(AR1, Sre1, fma2(NAI1, Sim1, d1)), ni1 = fma2(AR1, Sim1, fma2(AI1, Sre1, d3));
;                     Sre0 = nr0; Sim0 = ni0; Sre1 = nr1; Sim1 = ni1; }
;             }
; #pragma unroll
;             for (int e = 0; e < 2; ++e) { LAS float* fo = FS + (F.wave + 8 * (2 * h + e) + 32 * it) * 128 + l31; fo[0] = Sre0[e]; fo[32] = Sre1[e]; fo[64] = Sim0[e]; fo[96] = Sim1[e]; }
; #pragma unroll
;             for (int s = 0; s < 8; ++s) afr[s] = anx[s];
	v_mov_b64_e32 v[150:151], v[106:107]
	v_pk_fma_f32 v[6:7], v[170:171], v[4:5], v[6:7]
	v_pk_fma_f32 v[4:5], v[174:175], v[4:5], v[56:57]
	v_mov_b64_e32 v[148:149], v[104:105]
	v_pk_fma_f32 v[2:3], v[170:171], v[2:3], v[4:5]
	v_pk_fma_f32 v[4:5], v[178:179], v[0:1], v[10:11]
	s_nop 0
	v_pk_fma_f32 v[4:5], v[168:169], v[8:9], v[4:5]
	v_pk_fma_f32 v[8:9], v[172:173], v[8:9], v[42:43]
	s_nop 0
	v_pk_fma_f32 v[0:1], v[168:169], v[0:1], v[8:9]
	v_pk_fma_f32 v[8:9], v[180:181], v[2:3], v[26:27]
	s_nop 0
	v_pk_fma_f32 v[8:9], v[170:171], v[6:7], v[8:9]
	v_pk_fma_f32 v[6:7], v[174:175], v[6:7], v[58:59]
	s_nop 0
	v_pk_fma_f32 v[2:3], v[170:171], v[2:3], v[6:7]
	v_pk_fma_f32 v[6:7], v[178:179], v[0:1], v[12:13]
	s_nop 0
	v_pk_fma_f32 v[6:7], v[168:169], v[4:5], v[6:7]
	v_pk_fma_f32 v[4:5], v[172:173], v[4:5], v[44:45]
	s_nop 0
	v_pk_fma_f32 v[0:1], v[168:169], v[0:1], v[4:5]
	v_pk_fma_f32 v[4:5], v[180:181], v[2:3], v[28:29]
	s_nop 0
	v_pk_fma_f32 v[4:5], v[170:171], v[8:9], v[4:5]
	v_pk_fma_f32 v[8:9], v[174:175], v[8:9], v[60:61]
	s_nop 0
	v_pk_fma_f32 v[2:3], v[170:171], v[2:3], v[8:9]
	v_pk_fma_f32 v[8:9], v[178:179], v[0:1], v[14:15]
	s_nop 0
	v_pk_fma_f32 v[140:141], v[168:169], v[6:7], v[8:9]
	v_pk_fma_f32 v[6:7], v[172:173], v[6:7], v[46:47]
	v_mfma_f32_32x32x16_bf16 v[32:47], v[136:139], v[72:75], 0
	v_fma_f32 v144, v168, v0, v6
	v_fma_f32 v145, v169, v1, v7
	v_fma_f32 v0, v180, v2, v30
	v_fma_f32 v1, v181, v3, v31
	v_fma_f32 v142, v170, v4, v0
	v_fma_f32 v143, v171, v5, v1
	v_pk_fma_f32 v[0:1], v[174:175], v[4:5], v[62:63]
	s_nop 4
	v_pk_fma_f32 v[32:33], v[172:173], v[140:141], v[32:33]
	v_pk_fma_f32 v[146:147], v[170:171], v[2:3], v[0:1]
	v_mfma_f32_32x32x16_bf16 v[0:15], v[136:139], v[64:67], 0
	v_fma_f32 v32, v168, v144, v32
	v_fma_f32 v33, v169, v145, v33
	v_mfma_f32_32x32x16_bf16 v[48:63], v[136:139], v[76:79], 0
	s_nop 8
	v_fma_f32 v0, v178, v144, v0
	v_fma_f32 v1, v179, v145, v1
	v_fma_f32 v2, v178, v32, v2
	v_fma_f32 v3, v179, v33, v3
	v_fma_f32 v0, v168, v140, v0
	v_fma_f32 v1, v169, v141, v1
	v_pk_fma_f32 v[2:3], v[168:169], v[0:1], v[2:3]
	v_pk_fma_f32 v[0:1], v[172:173], v[0:1], v[34:35]
	v_pk_fma_f32 v[48:49], v[174:175], v[142:143], v[48:49]
	v_mfma_f32_32x32x16_bf16 v[16:31], v[136:139], v[68:71], 0
	v_fma_f32 v48, v170, v146, v48
	v_fma_f32 v49, v171, v147, v49
	v_fma_f32 v0, v168, v32, v0
	v_fma_f32 v1, v169, v33, v1
	v_fma_f32 v4, v178, v0, v4
	v_fma_f32 v5, v179, v1, v5
	v_pk_fma_f32 v[4:5], v[168:169], v[2:3], v[4:5]
	v_pk_fma_f32 v[2:3], v[172:173], v[2:3], v[36:37]
	s_nop 3
	v_pk_fma_f32 v[16:17], v[180:181], v[146:147], v[16:17]
	v_pk_fma_f32 v[18:19], v[180:181], v[48:49], v[18:19]
	v_pk_fma_f32 v[16:17], v[170:171], v[142:143], v[16:17]
	v_pk_fma_f32 v[0:1], v[168:169], v[0:1], v[2:3]
	v_pk_fma_f32 v[18:19], v[170:171], v[16:17], v[18:19]
	v_pk_fma_f32 v[16:17], v[174:175], v[16:17], v[50:51]
	v_pk_fma_f32 v[6:7], v[178:179], v[0:1], v[6:7]
	v_pk_fma_f32 v[16:17], v[170:171], v[48:49], v[16:17]
	v_pk_fma_f32 v[6:7], v[168:169], v[4:5], v[6:7]
	v_pk_fma_f32 v[2:3], v[180:181], v[16:17], v[20:21]
	v_pk_fma_f32 v[4:5], v[172:173], v[4:5], v[38:39]
	v_pk_fma_f32 v[2:3], v[170:171], v[18:19], v[2:3]
	v_pk_fma_f32 v[18:19], v[174:175], v[18:19], v[52:53]
	v_pk_fma_f32 v[0:1], v[168:169], v[0:1], v[4:5]
	v_pk_fma_f32 v[16:17], v[170:171], v[16:17], v[18:19]
	v_pk_fma_f32 v[8:9], v[178:179], v[0:1], v[8:9]
	v_pk_fma_f32 v[4:5], v[180:181], v[16:17], v[22:23]
	v_pk_fma_f32 v[8:9], v[168:169], v[6:7], v[8:9]
	v_pk_fma_f32 v[4:5], v[170:171], v[2:3], v[4:5]
	v_pk_fma_f32 v[2:3], v[174:175], v[2:3], v[54:55]
	v_pk_fma_f32 v[6:7], v[172:173], v[6:7], v[40:41]
	v_pk_fma_f32 v[2:3], v[170:171], v[16:17], v[2:3]
	v_pk_fma_f32 v[0:1], v[168:169], v[0:1], v[6:7]
	v_pk_fma_f32 v[6:7], v[180:181], v[2:3], v[24:25]
	s_waitcnt vmcnt(4)
	v_mov_b64_e32 v[146:147], v[110:111]
	v_pk_fma_f32 v[6:7], v[170:171], v[4:5], v[6:7]
	v_pk_fma_f32 v[4:5], v[174:175], v[4:5], v[56:57]
	v_mov_b64_e32 v[144:145], v[108:109]
	v_pk_fma_f32 v[2:3], v[170:171], v[2:3], v[4:5]
	v_pk_fma_f32 v[4:5], v[178:179], v[0:1], v[10:11]
	s_nop 0
	v_pk_fma_f32 v[4:5], v[168:169], v[8:9], v[4:5]
	v_pk_fma_f32 v[8:9], v[172:173], v[8:9], v[42:43]
	s_nop 0
	v_pk_fma_f32 v[0:1], v[168:169], v[0:1], v[8:9]
	v_pk_fma_f32 v[8:9], v[180:181], v[2:3], v[26:27]
	s_nop 0
	v_pk_fma_f32 v[8:9], v[170:171], v[6:7], v[8:9]
	v_pk_fma_f32 v[6:7], v[174:175], v[6:7], v[58:59]
	s_nop 0
	v_pk_fma_f32 v[2:3], v[170:171], v[2:3], v[6:7]
	v_pk_fma_f32 v[6:7], v[178:179], v[0:1], v[12:13]
	s_nop 0
	v_pk_fma_f32 v[6:7], v[168:169], v[4:5], v[6:7]
	v_pk_fma_f32 v[4:5], v[172:173], v[4:5], v[44:45]
	s_nop 0
	v_pk_fma_f32 v[0:1], v[168:169], v[0:1], v[4:5]
	v_pk_fma_f32 v[4:5], v[180:181], v[2:3], v[28:29]
	s_nop 0
	v_pk_fma_f32 v[4:5], v[170:171], v[8:9], v[4:5]
	v_pk_fma_f32 v[8:9], v[174:175], v[8:9], v[60:61]
	s_nop 0
	v_pk_fma_f32 v[2:3], v[170:171], v[2:3], v[8:9]
	v_pk_fma_f32 v[8:9], v[178:179], v[0:1], v[14:15]
	s_nop 0
	v_pk_fma_f32 v[136:137], v[168:169], v[6:7], v[8:9]
	v_pk_fma_f32 v[6:7], v[172:173], v[6:7], v[46:47]
	v_mfma_f32_32x32x16_bf16 v[32:47], v[132:135], v[72:75], 0
	v_fma_f32 v140, v168, v0, v6
	v_fma_f32 v141, v169, v1, v7
	v_fma_f32 v0, v180, v2, v30
	v_fma_f32 v1, v181, v3, v31
	v_fma_f32 v138, v170, v4, v0
	v_fma_f32 v139, v171, v5, v1
	v_pk_fma_f32 v[0:1], v[174:175], v[4:5], v[62:63]
	s_nop 4
	v_pk_fma_f32 v[32:33], v[172:173], v[136:137], v[32:33]
	v_pk_fma_f32 v[142:143], v[170:171], v[2:3], v[0:1]
	v_mfma_f32_32x32x16_bf16 v[0:15], v[132:135], v[64:67], 0
	v_fma_f32 v32, v168, v140, v32
	v_fma_f32 v33, v169, v141, v33
	v_mfma_f32_32x32x16_bf16 v[48:63], v[132:135], v[76:79], 0
; #define LAS __attribute__((address_space(3)))
; __device__ __forceinline__ f2v fma2(f2v a, f2v b, f2v c) { return __builtin_elementwise_fma(a, b, c); }
; __device__ __forceinline__ void ssm_phase(Frame& F) {
;     ...
;             for (int s = 0; s < 8; ++s) {
;                 const f32x16 D0 = __builtin_amdgcn_mfma_f32_32x32x16_bf16(afr[s], bfrag[0], z, 0, 0, 0), D1 = __builtin_amdgcn_mfma_f32_32x32x16_bf16(afr[s], bfrag[1], z, 0, 0, 0),
;                              D2 = __builtin_amdgcn_mfma_f32_32x32x16_bf16(afr[s], bfrag[2], z, 0, 0, 0), D3 = __builtin_amdgcn_mfma_f32_32x32x16_bf16(afr[s], bfrag[3], z, 0, 0, 0);
; #pragma unroll
;                 for (int t = 0; t < 8; ++t) {
;                     const f2v d0 = {D0[2 * t], D0[2 * t + 1]}, d1 = {D1[2 * t], D1[2 * t + 1]}, d2 = {D2[2 * t], D2[2 * t + 1]}, d3 = {D3[2 * t], D3[2 * t + 1]};
;                     const f2v nr0 = fma2(AR0, Sre0, fma2(NAI0, Sim0, d0)), ni0 = fma2(AR0, Sim0, fma2(AI0, Sre0, d2));
;                     const f2v nr1 = fma2(AR1, Sre1, fma2(NAI1, Sim1, d1)), ni1 = fma2(AR1, Sim1, fma2(AI1, Sre1, d3));
;                     Sre0 = nr0; Sim0 = ni0; Sre1 = nr1; Sim1 = ni1; }
;             }
; #pragma unroll
;             for (int e = 0; e < 2; ++e) { LAS float* fo = FS + (F.wave + 8 * (2 * h + e) + 32 * it) * 128 + l31; fo[0] = Sre0[e]; fo[32] = Sre1[e]; fo[64] = Sim0[e]; fo[96] = Sim1[e]; }
; #pragma unroll
;             for (int s = 0; s < 8; ++s) afr[s] = anx[s];
	s_nop 8
	v_fma_f32 v0, v178, v140, v0
	v_fma_f32 v1, v179, v141, v1
	v_fma_f32 v2, v178, v32, v2
	v_fma_f32 v3, v179, v33, v3
	v_fma_f32 v0, v168, v136, v0
	v_fma_f32 v1, v169, v137, v1
	v_pk_fma_f32 v[2:3], v[168:169], v[0:1], v[2:3]
	v_pk_fma_f32 v[0:1], v[172:173], v[0:1], v[34:35]
	v_pk_fma_f32 v[48:49], v[174:175], v[138:139], v[48:49]
	v_mfma_f32_32x32x16_bf16 v[16:31], v[132:135], v[68:71], 0
	v_fma_f32 v48, v170, v142, v48
	v_fma_f32 v49, v171, v143, v49
	v_fma_f32 v0, v168, v32, v0
	v_fma_f32 v1, v169, v33, v1
	v_fma_f32 v4, v178, v0, v4
	v_fma_f32 v5, v179, v1, v5
	v_pk_fma_f32 v[4:5], v[168:169], v[2:3], v[4:5]
	v_pk_fma_f32 v[2:3], v[172:173], v[2:3], v[36:37]
	s_nop 3
	v_pk_fma_f32 v[16:17], v[180:181], v[142:143], v[16:17]
	v_pk_fma_f32 v[18:19], v[180:181], v[48:49], v[18:19]
	v_pk_fma_f32 v[16:17], v[170:171], v[138:139], v[16:17]
	v_pk_fma_f32 v[0:1], v[168:169], v[0:1], v[2:3]
	v_pk_fma_f32 v[18:19], v[170:171], v[16:17], v[18:19]
	v_pk_fma_f32 v[16:17], v[174:175], v[16:17], v[50:51]
	v_pk_fma_f32 v[6:7], v[178:179], v[0:1], v[6:7]
	v_pk_fma_f32 v[16:17], v[170:171], v[48:49], v[16:17]
	v_pk_fma_f32 v[6:7], v[168:169], v[4:5], v[6:7]
	v_pk_fma_f32 v[2:3], v[180:181], v[16:17], v[20:21]
	v_pk_fma_f32 v[4:5], v[172:173], v[4:5], v[38:39]
	v_pk_fma_f32 v[2:3], v[170:171], v[18:19], v[2:3]
	v_pk_fma_f32 v[18:19], v[174:175], v[18:19], v[52:53]
	v_pk_fma_f32 v[0:1], v[168:169], v[0:1], v[4:5]
	v_pk_fma_f32 v[16:17], v[170:171], v[16:17], v[18:19]
	v_pk_fma_f32 v[8:9], v[178:179], v[0:1], v[8:9]
	v_pk_fma_f32 v[4:5], v[180:181], v[16:17], v[22:23]
	v_pk_fma_f32 v[8:9], v[168:169], v[6:7], v[8:9]
	v_pk_fma_f32 v[4:5], v[170:171], v[2:3], v[4:5]
	v_pk_fma_f32 v[2:3], v[174:175], v[2:3], v[54:55]
	v_pk_fma_f32 v[6:7], v[172:173], v[6:7], v[40:41]
	v_pk_fma_f32 v[2:3], v[170:171], v[16:17], v[2:3]
	v_pk_fma_f32 v[0:1], v[168:169], v[0:1], v[6:7]
	v_pk_fma_f32 v[6:7], v[180:181], v[2:3], v[24:25]
	s_waitcnt vmcnt(3)
	v_mov_b64_e32 v[142:143], v[114:115]
	v_pk_fma_f32 v[6:7], v[170:171], v[4:5], v[6:7]
	v_pk_fma_f32 v[4:5], v[174:175], v[4:5], v[56:57]
	v_mov_b64_e32 v[140:141], v[112:113]
	v_pk_fma_f32 v[2:3], v[170:171], v[2:3], v[4:5]
	v_pk_fma_f32 v[4:5], v[178:179], v[0:1], v[10:11]
	s_nop 0
	v_pk_fma_f32 v[4:5], v[168:169], v[8:9], v[4:5]
	v_pk_fma_f32 v[8:9], v[172:173], v[8:9], v[42:43]
	s_nop 0
	v_pk_fma_f32 v[0:1], v[168:169], v[0:1], v[8:9]
	v_pk_fma_f32 v[8:9], v[180:181], v[2:3], v[26:27]
	s_nop 0
	v_pk_fma_f32 v[8:9], v[170:171], v[6:7], v[8:9]
	v_pk_fma_f32 v[6:7], v[174:175], v[6:7], v[58:59]
	s_nop 0
	v_pk_fma_f32 v[2:3], v[170:171], v[2:3], v[6:7]
	v_pk_fma_f32 v[6:7], v[178:179], v[0:1], v[12:13]
	s_nop 0
	v_pk_fma_f32 v[6:7], v[168:169], v[4:5], v[6:7]
	v_pk_fma_f32 v[4:5], v[172:173], v[4:5], v[44:45]
	s_nop 0
	v_pk_fma_f32 v[0:1], v[168:169], v[0:1], v[4:5]
	v_pk_fma_f32 v[4:5], v[180:181], v[2:3], v[28:29]
	s_nop 0
	v_pk_fma_f32 v[4:5], v[170:171], v[8:9], v[4:5]
	v_pk_fma_f32 v[8:9], v[174:175], v[8:9], v[60:61]
	s_nop 0
	v_pk_fma_f32 v[2:3], v[170:171], v[2:3], v[8:9]
	v_pk_fma_f32 v[8:9], v[178:179], v[0:1], v[14:15]
	s_nop 0
	v_pk_fma_f32 v[132:133], v[168:169], v[6:7], v[8:9]
	v_pk_fma_f32 v[6:7], v[172:173], v[6:7], v[46:47]
	v_mfma_f32_32x32x16_bf16 v[32:47], v[128:131], v[72:75], 0
	v_fma_f32 v136, v168, v0, v6
	v_fma_f32 v137, v169, v1, v7
	v_fma_f32 v0, v180, v2, v30
	v_fma_f32 v1, v181, v3, v31
	v_fma_f32 v134, v170, v4, v0
	v_fma_f32 v135, v171, v5, v1
	v_pk_fma_f32 v[0:1], v[174:175], v[4:5], v[62:63]
	s_nop 4
	v_pk_fma_f32 v[32:33], v[172:173], v[132:133], v[32:33]
	v_pk_fma_f32 v[138:139], v[170:171], v[2:3], v[0:1]
	v_mfma_f32_32x32x16_bf16 v[0:15], v[128:131], v[64:67], 0
	v_fma_f32 v32, v168, v136, v32
	v_fma_f32 v33, v169, v137, v33
	v_mfma_f32_32x32x16_bf16 v[48:63], v[128:131], v[76:79], 0
	s_nop 8
	v_fma_f32 v0, v178, v136, v0
	v_fma_f32 v1, v179, v137, v1
	v_fma_f32 v2, v178, v32, v2
	v_fma_f32 v3, v179, v33, v3
	v_fma_f32 v0, v168, v132, v0
	v_fma_f32 v1, v169, v133, v1
	v_pk_fma_f32 v[2:3], v[168:169], v[0:1], v[2:3]
	v_pk_fma_f32 v[0:1], v[172:173], v[0:1], v[34:35]
	v_pk_fma_f32 v[48:49], v[174:175], v[134:135], v[48:49]
	v_mfma_f32_32x32x16_bf16 v[16:31], v[128:131], v[68:71], 0
	v_fma_f32 v48, v170, v138, v48
	v_fma_f32 v49, v171, v139, v49
	v_fma_f32 v0, v168, v32, v0
	v_fma_f32 v1, v169, v33, v1
	s_waitcnt vmcnt(0)
; #define GAS __attribute__((address_space(1)))
; #define LAS __attribute__((address_space(3)))
; __device__ __forceinline__ void ssm_phase(Frame& F) {
;     ...
;             for (int e = 0; e < 2; ++e) { LAS float* fo = FS + (F.wave + 8 * (2 * h + e) + 32 * it) * 128 + l31; fo[0] = Sre0[e]; fo[32] = Sre1[e]; fo[64] = Sim0[e]; fo[96] = Sim1[e]; }
; #pragma unroll
;             for (int s = 0; s < 8; ++s) afr[s] = anx[s];
;         }
;         __syncthreads();
;         if (F.wave == 0) {
;             const float a_r = sp[8192 + g * 64 + lane], a_i = sp[12288 + g * 64 + lane];
;     ...
;             const int cA = F.wave + 8 * aq + 32 * it;
;             const bf16* arow = ubase + (size_t)(cA * 64 + atk) * SG + 8 * h;
;             bf16x8 afr[8];
; #pragma unroll
;             for (int s = 0; s < 8; ++s) afr[s] = __builtin_nontemporal_load((const GAS bf16x8*)(arow + (size_t)(8 * s) * SG));
	v_mov_b64_e32 v[130:131], v[126:127]
	v_pk_fma_f32 v[4:5], v[178:179], v[0:1], v[4:5]
	v_mov_b64_e32 v[128:129], v[124:125]
	v_pk_fma_f32 v[4:5], v[168:169], v[2:3], v[4:5]
	v_pk_fma_f32 v[2:3], v[172:173], v[2:3], v[36:37]
	s_nop 1
	v_pk_fma_f32 v[16:17], v[180:181], v[138:139], v[16:17]
	v_pk_fma_f32 v[18:19], v[180:181], v[48:49], v[18:19]
	v_pk_fma_f32 v[16:17], v[170:171], v[134:135], v[16:17]
	v_pk_fma_f32 v[0:1], v[168:169], v[0:1], v[2:3]
	v_pk_fma_f32 v[18:19], v[170:171], v[16:17], v[18:19]
	v_pk_fma_f32 v[16:17], v[174:175], v[16:17], v[50:51]
	v_pk_fma_f32 v[6:7], v[178:179], v[0:1], v[6:7]
	v_pk_fma_f32 v[16:17], v[170:171], v[48:49], v[16:17]
	v_pk_fma_f32 v[6:7], v[168:169], v[4:5], v[6:7]
	v_pk_fma_f32 v[2:3], v[180:181], v[16:17], v[20:21]
	v_pk_fma_f32 v[4:5], v[172:173], v[4:5], v[38:39]
	v_pk_fma_f32 v[2:3], v[170:171], v[18:19], v[2:3]
	v_pk_fma_f32 v[18:19], v[174:175], v[18:19], v[52:53]
	v_pk_fma_f32 v[0:1], v[168:169], v[0:1], v[4:5]
	v_pk_fma_f32 v[16:17], v[170:171], v[16:17], v[18:19]
	v_pk_fma_f32 v[8:9], v[178:179], v[0:1], v[8:9]
	v_pk_fma_f32 v[4:5], v[180:181], v[16:17], v[22:23]
	v_pk_fma_f32 v[8:9], v[168:169], v[6:7], v[8:9]
	v_pk_fma_f32 v[4:5], v[170:171], v[2:3], v[4:5]
	v_pk_fma_f32 v[2:3], v[174:175], v[2:3], v[54:55]
	v_pk_fma_f32 v[6:7], v[172:173], v[6:7], v[40:41]
	v_pk_fma_f32 v[2:3], v[170:171], v[16:17], v[2:3]
	v_pk_fma_f32 v[0:1], v[168:169], v[0:1], v[6:7]
	v_pk_fma_f32 v[6:7], v[180:181], v[2:3], v[24:25]
	v_mov_b64_e32 v[16:17], v[96:97]
	v_pk_fma_f32 v[6:7], v[170:171], v[4:5], v[6:7]
	v_pk_fma_f32 v[4:5], v[174:175], v[4:5], v[56:57]
	v_mov_b64_e32 v[138:139], v[118:119]
	v_pk_fma_f32 v[2:3], v[170:171], v[2:3], v[4:5]
	v_pk_fma_f32 v[4:5], v[178:179], v[0:1], v[10:11]
	v_mov_b64_e32 v[134:135], v[122:123]
	v_pk_fma_f32 v[4:5], v[168:169], v[8:9], v[4:5]
	v_pk_fma_f32 v[8:9], v[172:173], v[8:9], v[42:43]
	v_mov_b64_e32 v[18:19], v[98:99]
	v_pk_fma_f32 v[0:1], v[168:169], v[0:1], v[8:9]
	v_pk_fma_f32 v[8:9], v[180:181], v[2:3], v[26:27]
	v_mov_b64_e32 v[136:137], v[116:117]
	v_pk_fma_f32 v[8:9], v[170:171], v[6:7], v[8:9]
	v_pk_fma_f32 v[6:7], v[174:175], v[6:7], v[58:59]
	v_mov_b64_e32 v[132:133], v[120:121]
	v_pk_fma_f32 v[2:3], v[170:171], v[2:3], v[6:7]
	v_pk_fma_f32 v[6:7], v[178:179], v[0:1], v[12:13]
	s_nop 0
	v_pk_fma_f32 v[6:7], v[168:169], v[4:5], v[6:7]
	v_pk_fma_f32 v[4:5], v[172:173], v[4:5], v[44:45]
	s_nop 0
	v_pk_fma_f32 v[4:5], v[168:169], v[0:1], v[4:5]
	v_pk_fma_f32 v[0:1], v[180:181], v[2:3], v[28:29]
	s_nop 0
	v_pk_fma_f32 v[10:11], v[170:171], v[8:9], v[0:1]
	v_pk_fma_f32 v[0:1], v[174:175], v[8:9], v[60:61]
	s_nop 0
	v_pk_fma_f32 v[8:9], v[170:171], v[2:3], v[0:1]
	v_pk_fma_f32 v[0:1], v[178:179], v[4:5], v[14:15]
	v_pk_fma_f32 v[2:3], v[172:173], v[6:7], v[46:47]
	v_pk_fma_f32 v[0:1], v[168:169], v[6:7], v[0:1]
	v_pk_fma_f32 v[2:3], v[168:169], v[4:5], v[2:3]
	v_pk_fma_f32 v[4:5], v[180:181], v[8:9], v[30:31]
	v_pk_fma_f32 v[6:7], v[174:175], v[10:11], v[62:63]
	v_pk_fma_f32 v[4:5], v[170:171], v[10:11], v[4:5]
	v_pk_fma_f32 v[6:7], v[170:171], v[8:9], v[6:7]
	v_add_u32_e32 v8, s27, v210
	ds_write2_b32 v8, v0, v4 offset1:32
	ds_write2_b32 v8, v2, v6 offset0:64 offset1:96
	v_add_u32_e32 v0, 0x1000, v8
	s_movk_i32 s27, 0x4000
	ds_write2_b32 v0, v1, v5 offset1:32
	ds_write2_b32 v0, v3, v7 offset0:64 offset1:96
	s_cbranch_vccnz .LBB0_324
	s_andn2_b64 vcc, exec, s[16:17]
	s_waitcnt lgkmcnt(0)
	s_barrier
	s_cbranch_vccnz .Lssm_pf_others
	v_add_u32_e32 v0, s26, v195
	v_ashrrev_i32_e32 v1, 31, v0
	v_lshl_add_u64 v[2:3], v[0:1], 2, s[58:59]
	v_add_u32_e32 v0, s26, v196
	v_ashrrev_i32_e32 v1, 31, v0
	v_lshl_add_u64 v[0:1], v[0:1], 2, s[58:59]
	global_load_dword v1, v[0:1], off
	s_nop 0
	global_load_dword v2, v[2:3], off
	v_lshl_add_u64 v[252:253], v[156:157], 1, s[2:3]
	v_add_u32_e32 v246, s33, v194
	v_lshl_or_b32 v246, v246, 6, v192
	v_mov_b32_e32 v247, 0
	v_lshlrev_b64 v[246:247], 5, v[246:247]
	v_lshl_add_u64 v[246:247], v[252:253], 0, v[246:247]
	global_load_dwordx4 v[216:219], v[246:247], off nt
	global_load_dwordx4 v[220:223], v[246:247], off offset:256 nt
	global_load_dwordx4 v[224:227], v[246:247], off offset:512 nt
	global_load_dwordx4 v[228:231], v[246:247], off offset:768 nt
	global_load_dwordx4 v[232:235], v[246:247], off offset:1024 nt
	global_load_dwordx4 v[236:239], v[246:247], off offset:1280 nt
	global_load_dwordx4 v[240:243], v[246:247], off offset:1536 nt
	global_load_dwordx4 v[248:251], v[246:247], off offset:1792 nt
	v_mov_b32_e32 v6, 0
	s_mov_b32 s0, -16
	v_mov_b32_e32 v8, v211
	v_mov_b32_e32 v7, v6
	s_waitcnt vmcnt(9)
	v_xor_b32_e32 v0, 0x80000000, v1
	s_waitcnt vmcnt(8)
	v_mov_b32_e32 v3, v2
	v_pk_mov_b32 v[4:5], v[0:1], v[0:1] op_sel:[1,0]
; #define GAS __attribute__((address_space(1)))
; __device__ __forceinline__ void ssm_phase(Frame& F) {
;     ...
;         if (F.wave == 0) {
;             const float a_r = sp[8192 + g * 64 + lane], a_i = sp[12288 + g * 64 + lane];
;             float cr = 0.f, ci = 0.f;
; #pragma unroll 1
;             for (int c0 = 0; c0 < 64; c0 += 16) {
;                 float fr[16], fi[16];
; #pragma unroll
;                 for (int k = 0; k < 16; ++k) { fr[k] = FS[(c0 + k) * 128 + lane]; fi[k] = FS[(c0 + k) * 128 + 64 + lane]; }
; #pragma unroll
;                 for (int k = 0; k < 16; ++k) { FS[(c0 + k) * 128 + lane] = cr; FS[(c0 + k) * 128 + 64 + lane] = ci;
;                     const float nr = fmaf(a_r, cr, fmaf(-a_i, ci, fr[k])), ni = fmaf(a_r, ci, fmaf(a_i, cr, fi[k])); cr = nr; ci = ni; }
;             }
;     ...
;             const int cA = F.wave + 8 * aq + 32 * it;
;             const bf16* arow = ubase + (size_t)(cA * 64 + atk) * SG + 8 * h;
;             bf16x8 afr[8];
; #pragma unroll
;             for (int s = 0; s < 8; ++s) afr[s] = __builtin_nontemporal_load((const GAS bf16x8*)(arow + (size_t)(8 * s) * SG));
.LBB0_327:
	ds_read2st64_b32 v[10:11], v8 offset1:1
	ds_read2st64_b32 v[12:13], v8 offset0:2 offset1:3
	ds_read2st64_b32 v[14:15], v8 offset0:4 offset1:5
	ds_read2st64_b32 v[16:17], v8 offset0:6 offset1:7
	ds_read2st64_b32 v[18:19], v8 offset0:8 offset1:9
	ds_read2st64_b32 v[20:21], v8 offset0:10 offset1:11
	ds_read2st64_b32 v[22:23], v8 offset0:12 offset1:13
	ds_read2st64_b32 v[24:25], v8 offset0:14 offset1:15
	ds_read2st64_b32 v[26:27], v8 offset0:16 offset1:17
	ds_read2st64_b32 v[28:29], v8 offset0:18 offset1:19
	ds_read2st64_b32 v[30:31], v8 offset0:20 offset1:21
	ds_read2st64_b32 v[32:33], v8 offset0:22 offset1:23
	ds_read2st64_b32 v[34:35], v8 offset0:24 offset1:25
	ds_read2st64_b32 v[36:37], v8 offset0:26 offset1:27
	ds_read2st64_b32 v[38:39], v8 offset0:28 offset1:29
	ds_read2st64_b32 v[40:41], v8 offset0:30 offset1:31
	s_waitcnt lgkmcnt(14)
	v_pk_fma_f32 v[10:11], v[0:1], v[6:7], v[10:11]
	ds_write2st64_b32 v8, v7, v6 offset1:1
	v_pk_fma_f32 v[6:7], v[2:3], v[6:7], v[10:11] op_sel:[0,0,1] op_sel_hi:[1,1,0]
	v_mov_b32_e32 v10, v13
	v_mov_b32_e32 v11, v12
	v_pk_fma_f32 v[10:11], v[4:5], v[6:7], v[10:11] op_sel:[0,1,0] op_sel_hi:[1,0,1]
	ds_write2st64_b32 v8, v7, v6 offset0:2 offset1:3
	v_pk_fma_f32 v[6:7], v[2:3], v[6:7], v[10:11]
	s_waitcnt lgkmcnt(14)
	v_mov_b32_e32 v10, v15
	v_mov_b32_e32 v11, v14
	v_pk_fma_f32 v[10:11], v[4:5], v[6:7], v[10:11] op_sel:[0,1,0] op_sel_hi:[1,0,1]
	ds_write2st64_b32 v8, v7, v6 offset0:4 offset1:5
	v_pk_fma_f32 v[6:7], v[2:3], v[6:7], v[10:11]
	v_mov_b32_e32 v10, v17
	v_mov_b32_e32 v11, v16
	v_pk_fma_f32 v[10:11], v[4:5], v[6:7], v[10:11] op_sel:[0,1,0] op_sel_hi:[1,0,1]
	ds_write2st64_b32 v8, v7, v6 offset0:6 offset1:7
	v_pk_fma_f32 v[6:7], v[2:3], v[6:7], v[10:11]
	s_waitcnt lgkmcnt(14)
	v_mov_b32_e32 v10, v19
	v_mov_b32_e32 v11, v18
	v_pk_fma_f32 v[10:11], v[4:5], v[6:7], v[10:11] op_sel:[0,1,0] op_sel_hi:[1,0,1]
	ds_write2st64_b32 v8, v7, v6 offset0:8 offset1:9
	v_pk_fma_f32 v[6:7], v[2:3], v[6:7], v[10:11]
	ds_write2st64_b32 v8, v7, v6 offset0:10 offset1:11
	v_pk_fma_f32 v[10:11], v[0:1], v[6:7], v[20:21]
	s_add_i32 s0, s0, 16
	v_pk_fma_f32 v[6:7], v[2:3], v[6:7], v[10:11] op_sel:[0,0,1] op_sel_hi:[1,1,0]
	ds_write2st64_b32 v8, v7, v6 offset0:12 offset1:13
	s_waitcnt lgkmcnt(14)
	v_pk_fma_f32 v[10:11], v[0:1], v[6:7], v[22:23]
	s_cmp_lt_u32 s0, 48
	v_pk_fma_f32 v[6:7], v[2:3], v[6:7], v[10:11] op_sel:[0,0,1] op_sel_hi:[1,1,0]
	v_mov_b32_e32 v10, v25
	v_mov_b32_e32 v11, v24
	v_pk_fma_f32 v[10:11], v[4:5], v[6:7], v[10:11] op_sel:[0,1,0] op_sel_hi:[1,0,1]
	ds_write2st64_b32 v8, v7, v6 offset0:14 offset1:15
	v_pk_fma_f32 v[6:7], v[2:3], v[6:7], v[10:11]
	v_mov_b32_e32 v10, v27
	v_mov_b32_e32 v11, v26
	v_pk_fma_f32 v[10:11], v[4:5], v[6:7], v[10:11] op_sel:[0,1,0] op_sel_hi:[1,0,1]
	ds_write2st64_b32 v8, v7, v6 offset0:16 offset1:17
	v_pk_fma_f32 v[6:7], v[2:3], v[6:7], v[10:11]
	s_waitcnt lgkmcnt(14)
	v_mov_b32_e32 v10, v29
	v_mov_b32_e32 v11, v28
	v_pk_fma_f32 v[10:11], v[4:5], v[6:7], v[10:11] op_sel:[0,1,0] op_sel_hi:[1,0,1]
	ds_write2st64_b32 v8, v7, v6 offset0:18 offset1:19
	v_pk_fma_f32 v[6:7], v[2:3], v[6:7], v[10:11]
	v_mov_b32_e32 v10, v31
	v_mov_b32_e32 v11, v30
	v_pk_fma_f32 v[10:11], v[4:5], v[6:7], v[10:11] op_sel:[0,1,0] op_sel_hi:[1,0,1]
	ds_write2st64_b32 v8, v7, v6 offset0:20 offset1:21
	v_pk_fma_f32 v[6:7], v[2:3], v[6:7], v[10:11]
	s_waitcnt lgkmcnt(14)
	v_mov_b32_e32 v10, v33
	v_mov_b32_e32 v11, v32
	v_pk_fma_f32 v[10:11], v[4:5], v[6:7], v[10:11] op_sel:[0,1,0] op_sel_hi:[1,0,1]
	ds_write2st64_b32 v8, v7, v6 offset0:22 offset1:23
	v_pk_fma_f32 v[6:7], v[2:3], v[6:7], v[10:11]
	v_mov_b32_e32 v10, v35
	v_mov_b32_e32 v11, v34
	v_pk_fma_f32 v[10:11], v[4:5], v[6:7], v[10:11] op_sel:[0,1,0] op_sel_hi:[1,0,1]
	ds_write2st64_b32 v8, v7, v6 offset0:24 offset1:25
	v_pk_fma_f32 v[6:7], v[2:3], v[6:7], v[10:11]
	s_waitcnt lgkmcnt(14)
	v_mov_b32_e32 v10, v37
	v_mov_b32_e32 v11, v36
	v_pk_fma_f32 v[10:11], v[4:5], v[6:7], v[10:11] op_sel:[0,1,0] op_sel_hi:[1,0,1]
	ds_write2st64_b32 v8, v7, v6 offset0:26 offset1:27
	v_pk_fma_f32 v[6:7], v[2:3], v[6:7], v[10:11]
	v_mov_b32_e32 v10, v39
	v_mov_b32_e32 v11, v38
	v_pk_fma_f32 v[10:11], v[4:5], v[6:7], v[10:11] op_sel:[0,1,0] op_sel_hi:[1,0,1]
	ds_write2st64_b32 v8, v7, v6 offset0:28 offset1:29
	v_pk_fma_f32 v[6:7], v[2:3], v[6:7], v[10:11]
	s_waitcnt lgkmcnt(14)
	v_mov_b32_e32 v10, v41
	v_mov_b32_e32 v11, v40
	v_pk_fma_f32 v[10:11], v[4:5], v[6:7], v[10:11] op_sel:[0,1,0] op_sel_hi:[1,0,1]
	ds_write2st64_b32 v8, v7, v6 offset0:30 offset1:31
	v_pk_fma_f32 v[6:7], v[2:3], v[6:7], v[10:11]
	v_add_u32_e32 v8, 0x2000, v8
	s_cbranch_scc1 .LBB0_327
	s_branch .LBB0_328
.Lssm_pf_others:
	v_lshl_add_u64 v[252:253], v[156:157], 1, s[2:3]
	v_add_u32_e32 v246, s33, v194
	v_lshl_or_b32 v246, v246, 6, v192
	v_mov_b32_e32 v247, 0
	v_lshlrev_b64 v[246:247], 5, v[246:247]
	v_lshl_add_u64 v[246:247], v[252:253], 0, v[246:247]
	global_load_dwordx4 v[216:219], v[246:247], off nt
	global_load_dwordx4 v[220:223], v[246:247], off offset:256 nt
	global_load_dwordx4 v[224:227], v[246:247], off offset:512 nt
	global_load_dwordx4 v[228:231], v[246:247], off offset:768 nt
	global_load_dwordx4 v[232:235], v[246:247], off offset:1024 nt
	global_load_dwordx4 v[236:239], v[246:247], off offset:1280 nt
	global_load_dwordx4 v[240:243], v[246:247], off offset:1536 nt
	global_load_dwordx4 v[248:251], v[246:247], off offset:1792 nt

; #define GAS __attribute__((address_space(1)))
; #define LAS __attribute__((address_space(3)))
; __device__ __forceinline__ unsigned cvt2(float lo, float hi) { const f2_t v = {lo, hi}; return __builtin_bit_cast(unsigned, __builtin_convertvector(v, bf2_t)); }
; __device__ __forceinline__ f2v fma2(f2v a, f2v b, f2v c) { return __builtin_elementwise_fma(a, b, c); }
; __device__ __forceinline__ void ssm_phase(Frame& F) {
;     ...
;         for (int it = 0; it < 2; ++it) {
;             const int cA = F.wave + 8 * aq + 32 * it;
;             const bf16* arow = ubase + (size_t)(cA * 64 + atk) * SG + 8 * h;
;             bf16x8 afr[8];
; #pragma unroll
;             for (int s = 0; s < 8; ++s) afr[s] = __builtin_nontemporal_load((const GAS bf16x8*)(arow + (size_t)(8 * s) * SG));
;             f2v Sre0, Sim0, Sre1, Sim1;
; #pragma unroll
;             for (int e = 0; e < 2; ++e) { const LAS float* fi_ = FS + (F.wave + 8 * (2 * h + e) + 32 * it) * 128 + l31; Sre0[e] = fi_[0]; Sre1[e] = fi_[32]; Sim0[e] = fi_[64]; Sim1[e] = fi_[96]; }
; #pragma unroll
;             for (int s = 0; s < 8; ++s) {
;                 *(LAS bf16x8*)(ut + l31 * 32 + 16 * h) = afr[s];
;                 const f32x16 D0 = __builtin_amdgcn_mfma_f32_32x32x16_bf16(afr[s], bfrag[0], z, 0, 0, 0), D1 = __builtin_amdgcn_mfma_f32_32x32x16_bf16(afr[s], bfrag[1], z, 0, 0, 0),
;                              D2 = __builtin_amdgcn_mfma_f32_32x32x16_bf16(afr[s], bfrag[2], z, 0, 0, 0), D3 = __builtin_amdgcn_mfma_f32_32x32x16_bf16(afr[s], bfrag[3], z, 0, 0, 0);
; #pragma unroll
;                 for (int t = 0; t < 8; ++t) {
;                     const f2v d0 = {D0[2 * t], D0[2 * t + 1]}, d1 = {D1[2 * t], D1[2 * t + 1]}, d2 = {D2[2 * t], D2[2 * t + 1]}, d3 = {D3[2 * t], D3[2 * t + 1]};
;                     const f2v nr0 = fma2(AR0, Sre0, fma2(NAI0, Sim0, d0)), ni0 = fma2(AR0, Sim0, fma2(AI0, Sre0, d2));
;                     const f2v nr1 = fma2(AR1, Sre1, fma2(NAI1, Sim1, d1)), ni1 = fma2(AR1, Sim1, fma2(AI1, Sre1, d3));
;                     Sre0 = nr0; Sim0 = ni0; Sre1 = nr1; Sim1 = ni1;
; #pragma unroll
;                     for (int e = 0; e < 2; ++e) { v2u w; w.x = cvt2(nr0[e], nr1[e]); w.y = cvt2(ni0[e], ni1[e]); *(LAS v2u*)(st + (16 * h + 2 * t + e) * 272 + 8 * l31) = w; }
.LBB0_329:
	s_nop 0
	v_cndmask_b32_e64 v0, 0, 1, s[2:3]
	s_add_i32 s0, s0, s33
	v_cmp_ne_u32_e32 vcc, 1, v0
	s_cmp_eq_u64 s[2:3], 0
	s_cbranch_scc1 .Lssm_it1
	s_waitcnt vmcnt(0)
	v_mov_b32_e32 v16, v216
	v_mov_b32_e32 v17, v217
	v_mov_b32_e32 v18, v218
	v_mov_b32_e32 v19, v219
	v_mov_b32_e32 v120, v220
	v_mov_b32_e32 v121, v221
	v_mov_b32_e32 v122, v222
	v_mov_b32_e32 v123, v223
	v_mov_b32_e32 v116, v224
	v_mov_b32_e32 v117, v225
	v_mov_b32_e32 v118, v226
	v_mov_b32_e32 v119, v227
	v_mov_b32_e32 v112, v228
	v_mov_b32_e32 v113, v229
	v_mov_b32_e32 v114, v230
	v_mov_b32_e32 v115, v231
	v_mov_b32_e32 v108, v232
	v_mov_b32_e32 v109, v233
	v_mov_b32_e32 v110, v234
	v_mov_b32_e32 v111, v235
	v_mov_b32_e32 v104, v236
	v_mov_b32_e32 v105, v237
	v_mov_b32_e32 v106, v238
	v_mov_b32_e32 v107, v239
	v_mov_b32_e32 v100, v240
	v_mov_b32_e32 v101, v241
	v_mov_b32_e32 v102, v242
	v_mov_b32_e32 v103, v243
	v_mov_b32_e32 v96, v248
	v_mov_b32_e32 v97, v249
	v_mov_b32_e32 v98, v250
	v_mov_b32_e32 v99, v251
	s_add_i32 s99, s0, 32
	v_add_u32_e32 v246, s99, v194
	v_lshl_or_b32 v246, v246, 6, v192
	v_mov_b32_e32 v247, 0
	v_lshlrev_b64 v[246:247], 5, v[246:247]
	v_lshl_add_u64 v[246:247], v[124:125], 0, v[246:247]
	global_load_dwordx4 v[216:219], v[246:247], off nt
	global_load_dwordx4 v[220:223], v[246:247], off offset:256 nt
	global_load_dwordx4 v[224:227], v[246:247], off offset:512 nt
	global_load_dwordx4 v[228:231], v[246:247], off offset:768 nt
	global_load_dwordx4 v[232:235], v[246:247], off offset:1024 nt
	global_load_dwordx4 v[236:239], v[246:247], off offset:1280 nt
	global_load_dwordx4 v[240:243], v[246:247], off offset:1536 nt
	global_load_dwordx4 v[248:251], v[246:247], off offset:1792 nt
	s_branch .Lssm_go
.Lssm_it1:
	s_waitcnt vmcnt(8)
	v_mov_b32_e32 v16, v216
	v_mov_b32_e32 v17, v217
	v_mov_b32_e32 v18, v218
	v_mov_b32_e32 v19, v219
	v_mov_b32_e32 v120, v220
	v_mov_b32_e32 v121, v221
	v_mov_b32_e32 v122, v222
	v_mov_b32_e32 v123, v223
	v_mov_b32_e32 v116, v224
	v_mov_b32_e32 v117, v225
	v_mov_b32_e32 v118, v226
	v_mov_b32_e32 v119, v227
	v_mov_b32_e32 v112, v228
	v_mov_b32_e32 v113, v229
	v_mov_b32_e32 v114, v230
	v_mov_b32_e32 v115, v231
	v_mov_b32_e32 v108, v232
	v_mov_b32_e32 v109, v233
	v_mov_b32_e32 v110, v234
	v_mov_b32_e32 v111, v235
	v_mov_b32_e32 v104, v236
	v_mov_b32_e32 v105, v237
	v_mov_b32_e32 v106, v238
	v_mov_b32_e32 v107, v239
	v_mov_b32_e32 v100, v240
	v_mov_b32_e32 v101, v241
	v_mov_b32_e32 v102, v242
	v_mov_b32_e32 v103, v243
	v_mov_b32_e32 v96, v248
	v_mov_b32_e32 v97, v249
	v_mov_b32_e32 v98, v250
	v_mov_b32_e32 v99, v251
.Lssm_go:
	v_lshl_add_u32 v4, s0, 9, v209
	ds_read2_b32 v[0:1], v4 offset1:32
	ds_read2_b32 v[2:3], v4 offset0:64 offset1:96
	v_add_u32_e32 v4, 0x1000, v4
	ds_read2_b32 v[128:129], v4 offset1:32
	ds_read2_b32 v[132:133], v4 offset0:64 offset1:96
	s_waitcnt lgkmcnt(3)
	v_mov_b32_e32 v130, v0
	s_waitcnt lgkmcnt(2)
	v_mov_b32_e32 v134, v2
	v_add_u32_e32 v149, 0x8000, v201
	s_waitcnt lgkmcnt(1)
	v_mov_b32_e32 v131, v128
	v_mov_b32_e32 v128, v1
	s_waitcnt lgkmcnt(0)
	v_mov_b32_e32 v135, v132
	v_mov_b32_e32 v132, v3
	v_add_u32_e32 v146, 0x8800, v201
	v_add_u32_e32 v147, s5, v197
	v_add_lshl_u32 v148, s0, v198, 6
	s_mov_b32 s0, 32
	s_mov_b64 s[2:3], 0
	s_and_b64 vcc, exec, vcc
	v_mfma_f32_32x32x16_bf16 v[32:47], v[16:19], v[64:67], 0
	ds_write_b128 v212, v[16:19]
	s_nop 10
	v_pk_fma_f32 v[32:33], v[178:179], v[134:135], v[32:33]
	v_mfma_f32_32x32x16_bf16 v[0:15], v[16:19], v[68:71], 0
	v_fma_f32 v32, v168, v130, v32
	v_fma_f32 v33, v169, v131, v33
	v_mfma_f32_32x32x16_bf16 v[48:63], v[16:19], v[72:75], 0
	s_nop 8
	v_fma_f32 v0, v180, v132, v0
	v_fma_f32 v1, v181, v133, v1
	v_fma_f32 v0, v170, v128, v0
	v_fma_f32 v1, v171, v129, v1
	v_mfma_f32_32x32x16_bf16 v[16:31], v[16:19], v[76:79], 0
	v_fma_f32 v48, v172, v130, v48
	v_fma_f32 v49, v173, v131, v49
	v_cvt_pk_bf16_f32 v130, v33, v1
	v_fma_f32 v48, v168, v134, v48
	v_fma_f32 v49, v169, v135, v49
	v_pk_fma_f32 v[34:35], v[178:179], v[48:49], v[34:35]
	s_nop 5
	v_pk_fma_f32 v[16:17], v[174:175], v[128:129], v[16:17]
	s_nop 0
	v_pk_fma_f32 v[16:17], v[170:171], v[132:133], v[16:17]
	v_cvt_pk_bf16_f32 v128, v32, v0
	v_pk_fma_f32 v[2:3], v[180:181], v[16:17], v[2:3]
	v_pk_fma_f32 v[34:35], v[168:169], v[32:33], v[34:35]
	v_pk_fma_f32 v[32:33], v[172:173], v[32:33], v[50:51]
	v_pk_fma_f32 v[2:3], v[170:171], v[0:1], v[2:3]
	v_pk_fma_f32 v[0:1], v[174:175], v[0:1], v[18:19]
	v_pk_fma_f32 v[32:33], v[168:169], v[48:49], v[32:33]
	v_pk_fma_f32 v[0:1], v[170:171], v[16:17], v[0:1]
	v_cvt_pk_bf16_f32 v129, v48, v16
	v_cvt_pk_bf16_f32 v131, v49, v17
	v_cvt_pk_bf16_f32 v16, v34, v2
	v_cvt_pk_bf16_f32 v17, v32, v0
	v_cvt_pk_bf16_f32 v18, v35, v3
	v_cvt_pk_bf16_f32 v19, v33, v1
	v_pk_fma_f32 v[4:5], v[180:181], v[0:1], v[4:5]
	ds_write2_b64 v149, v[16:17], v[18:19] offset0:68 offset1:102
	v_pk_fma_f32 v[16:17], v[178:179], v[32:33], v[36:37]
	v_pk_fma_f32 v[18:19], v[172:173], v[34:35], v[52:53]
	v_pk_fma_f32 v[4:5], v[170:171], v[2:3], v[4:5]
	v_pk_fma_f32 v[2:3], v[174:175], v[2:3], v[20:21]
	v_pk_fma_f32 v[16:17], v[168:169], v[34:35], v[16:17]
	v_pk_fma_f32 v[18:19], v[168:169], v[32:33], v[18:19]
	v_pk_fma_f32 v[0:1], v[170:171], v[0:1], v[2:3]
	v_cvt_pk_bf16_f32 v2, v16, v4
	v_cvt_pk_bf16_f32 v3, v18, v0
	v_cvt_pk_bf16_f32 v20, v17, v5
	v_cvt_pk_bf16_f32 v21, v19, v1
	ds_write2_b64 v149, v[2:3], v[20:21] offset0:136 offset1:170
	v_pk_fma_f32 v[2:3], v[178:179], v[18:19], v[38:39]
	v_pk_fma_f32 v[6:7], v[180:181], v[0:1], v[6:7]
	v_pk_fma_f32 v[2:3], v[168:169], v[16:17], v[2:3]
	v_pk_fma_f32 v[16:17], v[172:173], v[16:17], v[54:55]
	v_pk_fma_f32 v[6:7], v[170:171], v[4:5], v[6:7]
; __device__ __forceinline__ void ssm_phase(Frame& F) {
;     ...
;                 for (int t = 0; t < 8; ++t) {
;                     const f2v d0 = {D0[2 * t], D0[2 * t + 1]}, d1 = {D1[2 * t], D1[2 * t + 1]}, d2 = {D2[2 * t], D2[2 * t + 1]}, d3 = {D3[2 * t], D3[2 * t + 1]};
;                     const f2v nr0 = fma2(AR0, Sre0, fma2(NAI0, Sim0, d0)), ni0 = fma2(AR0, Sim0, fma2(AI0, Sre0, d2));
;                     const f2v nr1 = fma2(AR1, Sre1, fma2(NAI1, Sim1, d1)), ni1 = fma2(AR1, Sim1, fma2(AI1, Sre1, d3));
;                     Sre0 = nr0; Sim0 = ni0; Sre1 = nr1; Sim1 = ni1;
; #pragma unroll
;                     for (int e = 0; e < 2; ++e) { v2u w; w.x = cvt2(nr0[e], nr1[e]); w.y = cvt2(ni0[e], ni1[e]); *(LAS v2u*)(st + (16 * h + 2 * t + e) * 272 + 8 * l31) = w; }
;                 }
;                 LDS_WAIT(); asm volatile("" ::: "memory");
;                 f32x4 acc0 = (f32x4){0.f, 0.f, 0.f, 0.f}, acc1 = (f32x4){0.f, 0.f, 0.f, 0.f};
; #pragma unroll
;                 for (int ks = 0; ks < 4; ++ks) {
;                     const bf16x8 s0 = *(const LAS bf16x8*)(st + l15 * 272 + 64 * ks + 16 * qq), s1 = *(const LAS bf16x8*)(st + (16 + l15) * 272 + 64 * ks + 16 * qq);
;                     acc0 = __builtin_amdgcn_mfma_f32_16x16x32_bf16(s0, cfrag[ks], acc0, 0, 0, 0); acc1 = __builtin_amdgcn_mfma_f32_16x16x32_bf16(s1, cfrag[ks], acc1, 0, 0, 0); }
;                 float uu[2][4];
; #pragma unroll
;                 for (int rb = 0; rb < 2; ++rb)
; #pragma unroll
;                     for (int i2 = 0; i2 < 4; ++i2) uu[rb][i2] = bf1(*(const LAS bf16*)(ut + (i2 + 4 * rb + 8 * qq) * 32 + 2 * l15));
; #pragma unroll
;                 for (int rb = 0; rb < 2; ++rb)
; #pragma unroll
;                     for (int i2 = 0; i2 < 4; i2 += 2) {
;                         f2v y; y.x = (rb == 0 ? acc0[i2] : acc1[i2]) + dsk * uu[rb][i2]; y.y = (rb == 0 ? acc0[i2 + 1] : acc1[i2 + 1]) + dsk * uu[rb][i2 + 1];
;                         const f2v gq = gelu_tanh2(y); const unsigned w = cvt2(gq.x, gq.y);
;                         *(LAS bf16*)(yt + (16 * rb + 4 * qq + i2) * 32 + 2 * l15) = (bf16)(w & 0xffffu); *(LAS bf16*)(yt + (16 * rb + 4 * qq + i2 + 1) * 32 + 2 * l15) = (bf16)(w >> 16); }
;                 LDS_WAIT(); asm volatile("" ::: "memory");
;                 { const int R = lane >> 1, hf = lane & 1; const v4u yv = *(const LAS v4u*)(yt + lane * 16);
	v_pk_fma_f32 v[4:5], v[174:175], v[4:5], v[22:23]
	v_pk_fma_f32 v[16:17], v[168:169], v[18:19], v[16:17]
	v_pk_fma_f32 v[0:1], v[170:171], v[0:1], v[4:5]
	v_cvt_pk_bf16_f32 v4, v2, v6
	v_cvt_pk_bf16_f32 v5, v16, v0
	v_cvt_pk_bf16_f32 v18, v3, v7
	v_cvt_pk_bf16_f32 v19, v17, v1
	ds_write2_b64 v149, v[4:5], v[18:19] offset0:204 offset1:238
	v_pk_fma_f32 v[4:5], v[178:179], v[16:17], v[40:41]
	v_pk_fma_f32 v[8:9], v[180:181], v[0:1], v[8:9]
	v_pk_fma_f32 v[4:5], v[168:169], v[2:3], v[4:5]
	v_pk_fma_f32 v[2:3], v[172:173], v[2:3], v[56:57]
	v_pk_fma_f32 v[8:9], v[170:171], v[6:7], v[8:9]
	v_pk_fma_f32 v[6:7], v[174:175], v[6:7], v[24:25]
	v_pk_fma_f32 v[2:3], v[168:169], v[16:17], v[2:3]
	v_pk_fma_f32 v[0:1], v[170:171], v[0:1], v[6:7]
	v_cvt_pk_bf16_f32 v6, v4, v8
	v_cvt_pk_bf16_f32 v7, v2, v0
	v_cvt_pk_bf16_f32 v16, v5, v9
	v_cvt_pk_bf16_f32 v17, v3, v1
	ds_write2_b64 v146, v[6:7], v[16:17] offset0:16 offset1:50
	v_pk_fma_f32 v[6:7], v[178:179], v[2:3], v[42:43]
	ds_write2_b64 v149, v[128:129], v[130:131] offset1:34
	v_pk_fma_f32 v[6:7], v[168:169], v[4:5], v[6:7]
	v_pk_fma_f32 v[4:5], v[172:173], v[4:5], v[58:59]
	v_mov_b64_e32 v[128:129], s[22:23]
	v_pk_fma_f32 v[2:3], v[168:169], v[2:3], v[4:5]
	v_pk_fma_f32 v[4:5], v[180:181], v[0:1], v[10:11]
	s_nop 0
	v_pk_fma_f32 v[4:5], v[170:171], v[8:9], v[4:5]
	v_pk_fma_f32 v[8:9], v[174:175], v[8:9], v[26:27]
	v_cvt_pk_bf16_f32 v10, v7, v5
	v_pk_fma_f32 v[0:1], v[170:171], v[0:1], v[8:9]
	v_cvt_pk_bf16_f32 v8, v6, v4
	v_cvt_pk_bf16_f32 v9, v2, v0
	v_cvt_pk_bf16_f32 v11, v3, v1
	ds_write2_b64 v146, v[8:9], v[10:11] offset0:84 offset1:118
	v_pk_fma_f32 v[8:9], v[178:179], v[2:3], v[44:45]
	s_nop 0
	v_pk_fma_f32 v[8:9], v[168:169], v[6:7], v[8:9]
	v_pk_fma_f32 v[6:7], v[172:173], v[6:7], v[60:61]
	s_nop 0
	v_pk_fma_f32 v[2:3], v[168:169], v[2:3], v[6:7]
	v_pk_fma_f32 v[6:7], v[180:181], v[0:1], v[12:13]
	s_nop 0
	v_pk_fma_f32 v[6:7], v[170:171], v[4:5], v[6:7]
	v_pk_fma_f32 v[4:5], v[174:175], v[4:5], v[28:29]
	v_cvt_pk_bf16_f32 v10, v9, v7
	v_pk_fma_f32 v[0:1], v[170:171], v[0:1], v[4:5]
	v_cvt_pk_bf16_f32 v4, v8, v6
	v_cvt_pk_bf16_f32 v5, v2, v0
	v_cvt_pk_bf16_f32 v11, v3, v1
	ds_write2_b64 v146, v[4:5], v[10:11] offset0:152 offset1:186
	v_pk_fma_f32 v[4:5], v[178:179], v[2:3], v[46:47]
	v_mfma_f32_32x32x16_bf16 v[32:47], v[120:123], v[76:79], 0
	v_fma_f32 v134, v168, v8, v4
	v_fma_f32 v135, v169, v9, v5
	v_fma_f32 v4, v172, v8, v62
	v_fma_f32 v5, v173, v9, v63
	v_fma_f32 v136, v168, v2, v4
	v_fma_f32 v137, v169, v3, v5
	v_pk_fma_f32 v[2:3], v[180:181], v[0:1], v[14:15]
	s_nop 0
	v_pk_fma_f32 v[132:133], v[170:171], v[6:7], v[2:3]
	v_pk_fma_f32 v[2:3], v[174:175], v[6:7], v[30:31]
	v_mfma_f32_32x32x16_bf16 v[48:63], v[120:123], v[64:67], 0
	v_fma_f32 v130, v170, v0, v2
	v_fma_f32 v131, v171, v1, v3
	v_cvt_pk_bf16_f32 v0, v134, v132
	v_cvt_pk_bf16_f32 v1, v136, v130
	v_cvt_pk_bf16_f32 v2, v135, v133
	v_cvt_pk_bf16_f32 v3, v137, v131
	ds_write2_b64 v146, v[0:1], v[2:3] offset0:220 offset1:254
	s_waitcnt lgkmcnt(0)
	ds_read_b128 v[0:3], v213 offset:32768
	ds_read_b128 v[4:7], v213 offset:37120
	s_waitcnt lgkmcnt(1)
	v_mfma_f32_16x16x32_bf16 v[0:3], v[0:3], v[80:83], 0
	ds_read_b128 v[8:11], v213 offset:32832
	ds_read_b128 v[12:15], v213 offset:37184
	v_pk_fma_f32 v[32:33], v[174:175], v[132:133], v[32:33]
	v_pk_fma_f32 v[48:49], v[178:179], v[136:137], v[48:49]
	s_waitcnt lgkmcnt(1)
	v_mfma_f32_16x16x32_bf16 v[0:3], v[8:11], v[84:87], v[0:3]
	ds_read_b128 v[8:11], v213 offset:32896
	ds_read_b128 v[16:19], v213 offset:37248
	v_pk_fma_f32 v[32:33], v[170:171], v[130:131], v[32:33]
	v_pk_fma_f32 v[48:49], v[168:169], v[134:135], v[48:49]
	s_waitcnt lgkmcnt(1)
	v_mfma_f32_16x16x32_bf16 v[0:3], v[8:11], v[88:91], v[0:3]
	ds_read_b128 v[8:11], v213 offset:32960
	ds_read_b128 v[20:23], v213 offset:37312
	s_waitcnt lgkmcnt(1)
	v_mfma_f32_16x16x32_bf16 v[0:3], v[8:11], v[92:95], v[0:3]
	ds_read_u16 v8, v214
	ds_read_u16 v9, v214 offset:32
	s_waitcnt lgkmcnt(1)
	v_lshlrev_b32_e32 v8, 16, v8
	s_waitcnt lgkmcnt(0)
	v_lshlrev_b32_e32 v9, 16, v9
	s_nop 1
	v_pk_fma_f32 v[0:1], v[176:177], v[8:9], v[0:1]
	v_mfma_f32_16x16x32_bf16 v[4:7], v[4:7], v[80:83], 0
	v_mul_f32_e64 v8, v0, v0
	v_mul_f32_e64 v9, v1, v1
	v_pk_fma_f32 v[8:9], v[8:9], s[20:21], v[128:129] op_sel_hi:[1,0,0] neg_lo:[1,0,0] neg_hi:[1,0,0]
	v_mfma_f32_16x16x32_bf16 v[4:7], v[12:15], v[84:87], v[4:7]
	v_mul_f32_e64 v8, v0, v8
	v_mul_f32_e64 v9, v1, v9
	v_exp_f32_e32 v8, v8
	v_exp_f32_e32 v9, v9
	v_mfma_f32_16x16x32_bf16 v[4:7], v[16:19], v[88:91], v[4:7]
	v_add_f32_e64 v8, v8, 1.0
	v_add_f32_e64 v9, v9, 1.0
	v_rcp_f32_e32 v8, v8
	v_rcp_f32_e32 v9, v9
	v_mfma_f32_16x16x32_bf16 v[4:7], v[20:23], v[92:95], v[4:7]
	v_mul_f32_e64 v0, v0, v8
	v_mul_f32_e64 v1, v1, v9
	v_cvt_pk_bf16_f32 v0, v0, v1
	ds_read_u16 v8, v214 offset:128
	ds_read_u16 v9, v214 offset:160
	ds_write_b16 v215, v0
	ds_write_b16_d16_hi v215, v0 offset:32
	ds_read_u16 v0, v214 offset:64
	ds_read_u16 v1, v214 offset:96
	ds_read_u16 v10, v214 offset:192
	ds_read_u16 v11, v214 offset:224
	v_mfma_f32_32x32x16_bf16 v[16:31], v[120:123], v[72:75], 0
	s_waitcnt lgkmcnt(3)
	v_lshlrev_b32_e32 v0, 16, v0
	s_waitcnt lgkmcnt(2)
; #define LAS __attribute__((address_space(3)))
; #define LDS_WAIT() asm volatile("s_waitcnt lgkmcnt(0)" ::: "memory")
; __device__ __forceinline__ void ssm_phase(Frame& F) {
;     ...
; #pragma unroll
;             for (int s = 0; s < 8; ++s) {
;                 *(LAS bf16x8*)(ut + l31 * 32 + 16 * h) = afr[s];
;                 const f32x16 D0 = __builtin_amdgcn_mfma_f32_32x32x16_bf16(afr[s], bfrag[0], z, 0, 0, 0), D1 = __builtin_amdgcn_mfma_f32_32x32x16_bf16(afr[s], bfrag[1], z, 0, 0, 0),
;                              D2 = __builtin_amdgcn_mfma_f32_32x32x16_bf16(afr[s], bfrag[2], z, 0, 0, 0), D3 = __builtin_amdgcn_mfma_f32_32x32x16_bf16(afr[s], bfrag[3], z, 0, 0, 0);
; #pragma unroll
;                 for (int t = 0; t < 8; ++t) {
;                     const f2v d0 = {D0[2 * t], D0[2 * t + 1]}, d1 = {D1[2 * t], D1[2 * t + 1]}, d2 = {D2[2 * t], D2[2 * t + 1]}, d3 = {D3[2 * t], D3[2 * t + 1]};
;                     const f2v nr0 = fma2(AR0, Sre0, fma2(NAI0, Sim0, d0)), ni0 = fma2(AR0, Sim0, fma2(AI0, Sre0, d2));
;                     const f2v nr1 = fma2(AR1, Sre1, fma2(NAI1, Sim1, d1)), ni1 = fma2(AR1, Sim1, fma2(AI1, Sre1, d3));
;                     Sre0 = nr0; Sim0 = ni0; Sre1 = nr1; Sim1 = ni1;
; #pragma unroll
;                     for (int e = 0; e < 2; ++e) { v2u w; w.x = cvt2(nr0[e], nr1[e]); w.y = cvt2(ni0[e], ni1[e]); *(LAS v2u*)(st + (16 * h + 2 * t + e) * 272 + 8 * l31) = w; }
;                 }
;                 LDS_WAIT(); asm volatile("" ::: "memory");
;                 f32x4 acc0 = (f32x4){0.f, 0.f, 0.f, 0.f}, acc1 = (f32x4){0.f, 0.f, 0.f, 0.f};
; #pragma unroll
;                 for (int ks = 0; ks < 4; ++ks) {
;                     const bf16x8 s0 = *(const LAS bf16x8*)(st + l15 * 272 + 64 * ks + 16 * qq), s1 = *(const LAS bf16x8*)(st + (16 + l15) * 272 + 64 * ks + 16 * qq);
;                     acc0 = __builtin_amdgcn_mfma_f32_16x16x32_bf16(s0, cfrag[ks], acc0, 0, 0, 0); acc1 = __builtin_amdgcn_mfma_f32_16x16x32_bf16(s1, cfrag[ks], acc1, 0, 0, 0); }
;                 float uu[2][4];
; #pragma unroll
;                 for (int rb = 0; rb < 2; ++rb)
; #pragma unroll
;                     for (int i2 = 0; i2 < 4; ++i2) uu[rb][i2] = bf1(*(const LAS bf16*)(ut + (i2 + 4 * rb + 8 * qq) * 32 + 2 * l15));
; #pragma unroll
;                 for (int rb = 0; rb < 2; ++rb)
; #pragma unroll
;                     for (int i2 = 0; i2 < 4; i2 += 2) {
	v_lshlrev_b32_e32 v1, 16, v1
	v_fma_f32 v0, v176, v0, v2
	v_fma_f32 v1, v177, v1, v3
	v_pk_mul_f32 v[2:3], v[0:1], v[0:1]
	s_nop 4
	v_pk_fma_f32 v[16:17], v[172:173], v[134:135], v[16:17]
	v_pk_fma_f32 v[2:3], v[2:3], s[20:21], v[128:129] op_sel_hi:[1,0,0] neg_lo:[1,0,0] neg_hi:[1,0,0]
	v_pk_fma_f32 v[16:17], v[168:169], v[136:137], v[16:17]
	v_pk_mul_f32 v[2:3], v[0:1], v[2:3]
	v_pk_fma_f32 v[50:51], v[178:179], v[16:17], v[50:51]
	v_exp_f32_e32 v2, v2
	v_exp_f32_e32 v3, v3
	v_pk_fma_f32 v[18:19], v[172:173], v[48:49], v[18:19]
	v_pk_fma_f32 v[50:51], v[168:169], v[48:49], v[50:51]
	v_pk_add_f32 v[2:3], v[2:3], 1.0 op_sel_hi:[1,0]
	s_nop 0
	v_rcp_f32_e32 v2, v2
	v_rcp_f32_e32 v3, v3
	v_pk_fma_f32 v[20:21], v[172:173], v[50:51], v[20:21]
	v_pk_mul_f32 v[0:1], v[0:1], v[2:3]
	s_nop 0
	v_cvt_pk_bf16_f32 v0, v0, v1
	ds_write_b16 v215, v0 offset:64
	ds_write_b16_d16_hi v215, v0 offset:96
	v_lshlrev_b32_e32 v1, 16, v9
	v_lshlrev_b32_e32 v0, 16, v8
	v_pk_fma_f32 v[0:1], v[176:177], v[0:1], v[4:5]
	v_add_u32_e32 v4, v138, v148
	v_pk_mul_f32 v[2:3], v[0:1], v[0:1]
	v_ashrrev_i32_e32 v5, 31, v4
	v_pk_fma_f32 v[2:3], v[2:3], s[20:21], v[128:129] op_sel_hi:[1,0,0] neg_lo:[1,0,0] neg_hi:[1,0,0]
	v_lshlrev_b64 v[4:5], 11, v[4:5]
	v_pk_mul_f32 v[2:3], v[0:1], v[2:3]
	v_lshl_add_u64 v[4:5], v[126:127], 0, v[4:5]
	v_exp_f32_e32 v2, v2
	v_exp_f32_e32 v3, v3
	s_nop 0
	v_pk_add_f32 v[2:3], v[2:3], 1.0 op_sel_hi:[1,0]
	s_nop 0
	v_rcp_f32_e32 v2, v2
	v_rcp_f32_e32 v3, v3
	s_nop 0
	v_pk_mul_f32 v[0:1], v[0:1], v[2:3]
	s_nop 0
	v_cvt_pk_bf16_f32 v0, v0, v1
	ds_write_b16 v215, v0 offset:512
	ds_write_b16_d16_hi v215, v0 offset:544
	s_waitcnt lgkmcnt(4)
	v_lshlrev_b32_e32 v1, 16, v11
	v_lshlrev_b32_e32 v0, 16, v10
	v_pk_fma_f32 v[0:1], v[176:177], v[0:1], v[6:7]
	s_nop 0
	v_pk_mul_f32 v[2:3], v[0:1], v[0:1]
	s_nop 0
	v_pk_fma_f32 v[2:3], v[2:3], s[20:21], v[128:129] op_sel_hi:[1,0,0] neg_lo:[1,0,0] neg_hi:[1,0,0]
	s_nop 0
	v_pk_mul_f32 v[2:3], v[0:1], v[2:3]
	s_nop 0
	v_exp_f32_e32 v2, v2
	v_exp_f32_e32 v3, v3
	s_nop 0
	v_pk_add_f32 v[2:3], v[2:3], 1.0 op_sel_hi:[1,0]
	s_nop 0
	v_rcp_f32_e32 v2, v2
	v_rcp_f32_e32 v3, v3
	s_nop 0
	v_pk_mul_f32 v[0:1], v[0:1], v[2:3]
	s_nop 0
	v_cvt_pk_bf16_f32 v0, v0, v1
	ds_write_b16 v215, v0 offset:576
	ds_write_b16_d16_hi v215, v0 offset:608
	s_waitcnt lgkmcnt(0)
	ds_read_b128 v[0:3], v147
	s_waitcnt lgkmcnt(0)
	global_store_dwordx4 v[4:5], v[0:3], off
	s_nop 1
	v_mfma_f32_32x32x16_bf16 v[0:15], v[120:123], v[68:71], 0
	s_waitcnt lgkmcnt(0)
	ds_write_b128 v212, v[120:123]
	v_cvt_pk_bf16_f32 v121, v16, v32
	v_cvt_pk_bf16_f32 v123, v17, v33
	v_fma_f32 v16, v168, v16, v18
	v_fma_f32 v17, v169, v17, v19
	s_nop 6
	v_pk_fma_f32 v[0:1], v[180:181], v[130:131], v[0:1]
	s_nop 0
	v_pk_fma_f32 v[0:1], v[170:171], v[132:133], v[0:1]
	v_pk_fma_f32 v[2:3], v[180:181], v[32:33], v[2:3]
	v_cvt_pk_bf16_f32 v120, v48, v0
	v_cvt_pk_bf16_f32 v122, v49, v1
	v_pk_fma_f32 v[2:3], v[170:171], v[0:1], v[2:3]
	v_pk_fma_f32 v[0:1], v[174:175], v[0:1], v[34:35]
	v_cvt_pk_bf16_f32 v18, v50, v2
	v_pk_fma_f32 v[0:1], v[170:171], v[32:33], v[0:1]
	v_cvt_pk_bf16_f32 v32, v51, v3
	v_cvt_pk_bf16_f32 v19, v16, v0
	v_cvt_pk_bf16_f32 v33, v17, v1
	v_pk_fma_f32 v[4:5], v[180:181], v[0:1], v[4:5]
	ds_write2_b64 v149, v[18:19], v[32:33] offset0:68 offset1:102
	v_pk_fma_f32 v[18:19], v[178:179], v[16:17], v[52:53]
	v_pk_fma_f32 v[4:5], v[170:171], v[2:3], v[4:5]
	v_pk_fma_f32 v[2:3], v[174:175], v[2:3], v[36:37]
	v_pk_fma_f32 v[18:19], v[168:169], v[50:51], v[18:19]
	v_pk_fma_f32 v[16:17], v[168:169], v[16:17], v[20:21]
	v_pk_fma_f32 v[0:1], v[170:171], v[0:1], v[2:3]
	v_cvt_pk_bf16_f32 v2, v18, v4
	v_cvt_pk_bf16_f32 v3, v16, v0
	v_cvt_pk_bf16_f32 v20, v19, v5
	v_cvt_pk_bf16_f32 v21, v17, v1
	ds_write2_b64 v149, v[2:3], v[20:21] offset0:136 offset1:170
	v_pk_fma_f32 v[2:3], v[178:179], v[16:17], v[54:55]
	v_pk_fma_f32 v[6:7], v[180:181], v[0:1], v[6:7]
	v_pk_fma_f32 v[2:3], v[168:169], v[18:19], v[2:3]
	v_pk_fma_f32 v[18:19], v[172:173], v[18:19], v[22:23]
	v_pk_fma_f32 v[6:7], v[170:171], v[4:5], v[6:7]
	v_pk_fma_f32 v[4:5], v[174:175], v[4:5], v[38:39]
	v_pk_fma_f32 v[16:17], v[168:169], v[16:17], v[18:19]
	v_pk_fma_f32 v[0:1], v[170:171], v[0:1], v[4:5]
	v_cvt_pk_bf16_f32 v4, v2, v6
	v_cvt_pk_bf16_f32 v5, v16, v0
	v_cvt_pk_bf16_f32 v18, v3, v7
	v_cvt_pk_bf16_f32 v19, v17, v1
	ds_write2_b64 v149, v[4:5], v[18:19] offset0:204 offset1:238
	v_pk_fma_f32 v[4:5], v[178:179], v[16:17], v[56:57]
	v_pk_fma_f32 v[8:9], v[180:181], v[0:1], v[8:9]
	v_pk_fma_f32 v[4:5], v[168:169], v[2:3], v[4:5]
	v_pk_fma_f32 v[2:3], v[172:173], v[2:3], v[24:25]
	v_pk_fma_f32 v[8:9], v[170:171], v[6:7], v[8:9]
	v_pk_fma_f32 v[6:7], v[174:175], v[6:7], v[40:41]
	v_pk_fma_f32 v[2:3], v[168:169], v[16:17], v[2:3]
	v_pk_fma_f32 v[0:1], v[170:171], v[0:1], v[6:7]
	v_cvt_pk_bf16_f32 v6, v4, v8
	v_cvt_pk_bf16_f32 v7, v2, v0
	v_cvt_pk_bf16_f32 v16, v5, v9
	v_cvt_pk_bf16_f32 v17, v3, v1
	ds_write2_b64 v146, v[6:7], v[16:17] offset0:16 offset1:50
	v_pk_fma_f32 v[6:7], v[178:179], v[2:3], v[58:59]
	ds_write2_b64 v149, v[120:121], v[122:123] offset1:34
	v_pk_fma_f32 v[6:7], v[168:169], v[4:5], v[6:7]
	v_pk_fma_f32 v[4:5], v[172:173], v[4:5], v[26:27]
	s_nop 0
	v_pk_fma_f32 v[2:3], v[168:169], v[2:3], v[4:5]
	v_pk_fma_f32 v[4:5], v[180:181], v[0:1], v[10:11]
	s_nop 0
	v_pk_fma_f32 v[4:5], v[170:171], v[8:9], v[4:5]
	v_pk_fma_f32 v[8:9], v[174:175], v[8:9], v[42:43]
	v_cvt_pk_bf16_f32 v10, v7, v5
	v_pk_fma_f32 v[0:1], v[170:171], v[0:1], v[8:9]
	v_cvt_pk_bf16_f32 v8, v6, v4
	v_cvt_pk_bf16_f32 v9, v2, v0
	v_cvt_pk_bf16_f32 v11, v3, v1
	ds_write2_b64 v146, v[8:9], v[10:11] offset0:84 offset1:118
; #define LAS __attribute__((address_space(3)))
; #define LDS_WAIT() asm volatile("s_waitcnt lgkmcnt(0)" ::: "memory")
; __device__ __forceinline__ void ssm_phase(Frame& F) {
;     ...
; #pragma unroll
;             for (int s = 0; s < 8; ++s) {
;                 *(LAS bf16x8*)(ut + l31 * 32 + 16 * h) = afr[s];
;                 const f32x16 D0 = __builtin_amdgcn_mfma_f32_32x32x16_bf16(afr[s], bfrag[0], z, 0, 0, 0), D1 = __builtin_amdgcn_mfma_f32_32x32x16_bf16(afr[s], bfrag[1], z, 0, 0, 0),
;                              D2 = __builtin_amdgcn_mfma_f32_32x32x16_bf16(afr[s], bfrag[2], z, 0, 0, 0), D3 = __builtin_amdgcn_mfma_f32_32x32x16_bf16(afr[s], bfrag[3], z, 0, 0, 0);
; #pragma unroll
;                 for (int t = 0; t < 8; ++t) {
;                     const f2v d0 = {D0[2 * t], D0[2 * t + 1]}, d1 = {D1[2 * t], D1[2 * t + 1]}, d2 = {D2[2 * t], D2[2 * t + 1]}, d3 = {D3[2 * t], D3[2 * t + 1]};
;                     const f2v nr0 = fma2(AR0, Sre0, fma2(NAI0, Sim0, d0)), ni0 = fma2(AR0, Sim0, fma2(AI0, Sre0, d2));
;                     const f2v nr1 = fma2(AR1, Sre1, fma2(NAI1, Sim1, d1)), ni1 = fma2(AR1, Sim1, fma2(AI1, Sre1, d3));
;                     Sre0 = nr0; Sim0 = ni0; Sre1 = nr1; Sim1 = ni1;
; #pragma unroll
;                     for (int e = 0; e < 2; ++e) { v2u w; w.x = cvt2(nr0[e], nr1[e]); w.y = cvt2(ni0[e], ni1[e]); *(LAS v2u*)(st + (16 * h + 2 * t + e) * 272 + 8 * l31) = w; }
;                 }
;                 LDS_WAIT(); asm volatile("" ::: "memory");
;                 f32x4 acc0 = (f32x4){0.f, 0.f, 0.f, 0.f}, acc1 = (f32x4){0.f, 0.f, 0.f, 0.f};
; #pragma unroll
;                 for (int ks = 0; ks < 4; ++ks) {
;                     const bf16x8 s0 = *(const LAS bf16x8*)(st + l15 * 272 + 64 * ks + 16 * qq), s1 = *(const LAS bf16x8*)(st + (16 + l15) * 272 + 64 * ks + 16 * qq);
;                     acc0 = __builtin_amdgcn_mfma_f32_16x16x32_bf16(s0, cfrag[ks], acc0, 0, 0, 0); acc1 = __builtin_amdgcn_mfma_f32_16x16x32_bf16(s1, cfrag[ks], acc1, 0, 0, 0); }
;                 float uu[2][4];
; #pragma unroll
;                 for (int rb = 0; rb < 2; ++rb)
; #pragma unroll
;                     for (int i2 = 0; i2 < 4; ++i2) uu[rb][i2] = bf1(*(const LAS bf16*)(ut + (i2 + 4 * rb + 8 * qq) * 32 + 2 * l15));
; #pragma unroll
;                 for (int rb = 0; rb < 2; ++rb)
; #pragma unroll
;                     for (int i2 = 0; i2 < 4; i2 += 2) {
	v_pk_fma_f32 v[8:9], v[178:179], v[2:3], v[60:61]
	s_nop 0
	v_pk_fma_f32 v[8:9], v[168:169], v[6:7], v[8:9]
	v_pk_fma_f32 v[6:7], v[172:173], v[6:7], v[28:29]
	s_nop 0
	v_pk_fma_f32 v[2:3], v[168:169], v[2:3], v[6:7]
	v_pk_fma_f32 v[6:7], v[180:181], v[0:1], v[12:13]
	s_nop 0
	v_pk_fma_f32 v[6:7], v[170:171], v[4:5], v[6:7]
	v_pk_fma_f32 v[4:5], v[174:175], v[4:5], v[44:45]
	v_cvt_pk_bf16_f32 v10, v9, v7
	v_pk_fma_f32 v[0:1], v[170:171], v[0:1], v[4:5]
	v_cvt_pk_bf16_f32 v4, v8, v6
	v_cvt_pk_bf16_f32 v5, v2, v0
	v_cvt_pk_bf16_f32 v11, v3, v1
	ds_write2_b64 v146, v[4:5], v[10:11] offset0:152 offset1:186
	v_pk_fma_f32 v[4:5], v[178:179], v[2:3], v[62:63]
	v_mfma_f32_32x32x16_bf16 v[48:63], v[116:119], v[72:75], 0
	v_fma_f32 v120, v168, v8, v4
	v_fma_f32 v121, v169, v9, v5
	v_fma_f32 v4, v172, v8, v30
	v_fma_f32 v5, v173, v9, v31
	v_fma_f32 v130, v168, v2, v4
	v_fma_f32 v131, v169, v3, v5
	v_pk_fma_f32 v[2:3], v[180:181], v[0:1], v[14:15]
	s_nop 4
	v_pk_fma_f32 v[48:49], v[172:173], v[120:121], v[48:49]
	v_pk_fma_f32 v[122:123], v[170:171], v[6:7], v[2:3]
	v_pk_fma_f32 v[2:3], v[174:175], v[6:7], v[46:47]
	v_mfma_f32_32x32x16_bf16 v[32:47], v[116:119], v[64:67], 0
	v_fma_f32 v132, v170, v0, v2
	v_fma_f32 v133, v171, v1, v3
	v_cvt_pk_bf16_f32 v0, v120, v122
	v_cvt_pk_bf16_f32 v1, v130, v132
	v_cvt_pk_bf16_f32 v2, v121, v123
	v_cvt_pk_bf16_f32 v3, v131, v133
	ds_write2_b64 v146, v[0:1], v[2:3] offset0:220 offset1:254
	s_waitcnt lgkmcnt(0)
	ds_read_b128 v[0:3], v213 offset:32768
	ds_read_b128 v[4:7], v213 offset:37120
	s_waitcnt lgkmcnt(1)
	v_mfma_f32_16x16x32_bf16 v[0:3], v[0:3], v[80:83], 0
	ds_read_b128 v[8:11], v213 offset:32832
	ds_read_b128 v[12:15], v213 offset:37184
	v_pk_fma_f32 v[32:33], v[178:179], v[130:131], v[32:33]
	v_pk_fma_f32 v[48:49], v[168:169], v[130:131], v[48:49]
	s_waitcnt lgkmcnt(1)
	v_mfma_f32_16x16x32_bf16 v[0:3], v[8:11], v[84:87], v[0:3]
	ds_read_b128 v[8:11], v213 offset:32896
	ds_read_b128 v[16:19], v213 offset:37248
	v_pk_fma_f32 v[32:33], v[168:169], v[120:121], v[32:33]
	v_pk_fma_f32 v[34:35], v[178:179], v[48:49], v[34:35]
	s_waitcnt lgkmcnt(1)
	v_mfma_f32_16x16x32_bf16 v[0:3], v[8:11], v[88:91], v[0:3]
	ds_read_b128 v[8:11], v213 offset:32960
	ds_read_b128 v[20:23], v213 offset:37312
	v_pk_fma_f32 v[34:35], v[168:169], v[32:33], v[34:35]
	s_waitcnt lgkmcnt(1)
	v_mfma_f32_16x16x32_bf16 v[0:3], v[8:11], v[92:95], v[0:3]
	ds_read_u16 v8, v214
	ds_read_u16 v9, v214 offset:32
	s_waitcnt lgkmcnt(1)
	v_lshlrev_b32_e32 v8, 16, v8
	s_waitcnt lgkmcnt(0)
	v_lshlrev_b32_e32 v9, 16, v9
	s_nop 1
	v_pk_fma_f32 v[0:1], v[176:177], v[8:9], v[0:1]
	v_mfma_f32_16x16x32_bf16 v[4:7], v[4:7], v[80:83], 0
	v_mul_f32_e64 v8, v0, v0
	v_mul_f32_e64 v9, v1, v1
	v_pk_fma_f32 v[8:9], v[8:9], s[20:21], v[128:129] op_sel_hi:[1,0,0] neg_lo:[1,0,0] neg_hi:[1,0,0]
	v_mfma_f32_16x16x32_bf16 v[4:7], v[12:15], v[84:87], v[4:7]
	v_mul_f32_e64 v8, v0, v8
	v_mul_f32_e64 v9, v1, v9
	v_exp_f32_e32 v8, v8
	v_exp_f32_e32 v9, v9
	v_mfma_f32_16x16x32_bf16 v[4:7], v[16:19], v[88:91], v[4:7]
	v_add_f32_e64 v8, v8, 1.0
	v_add_f32_e64 v9, v9, 1.0
	v_rcp_f32_e32 v8, v8
	v_rcp_f32_e32 v9, v9
	v_mfma_f32_16x16x32_bf16 v[4:7], v[20:23], v[92:95], v[4:7]
	v_mul_f32_e64 v0, v0, v8
	v_mul_f32_e64 v1, v1, v9
	v_cvt_pk_bf16_f32 v0, v0, v1
	ds_read_u16 v8, v214 offset:128
	ds_read_u16 v9, v214 offset:160
	ds_write_b16 v215, v0
	ds_write_b16_d16_hi v215, v0 offset:32
	ds_read_u16 v0, v214 offset:64
	ds_read_u16 v1, v214 offset:96
	ds_read_u16 v10, v214 offset:192
	ds_read_u16 v11, v214 offset:224
	v_mfma_f32_32x32x16_bf16 v[16:31], v[116:119], v[76:79], 0
	s_waitcnt lgkmcnt(3)
	v_lshlrev_b32_e32 v0, 16, v0
	s_waitcnt lgkmcnt(2)
	v_lshlrev_b32_e32 v1, 16, v1
	v_fma_f32 v0, v176, v0, v2
	v_fma_f32 v1, v177, v1, v3
	v_pk_mul_f32 v[2:3], v[0:1], v[0:1]
	s_nop 4
	v_pk_fma_f32 v[16:17], v[174:175], v[122:123], v[16:17]
	v_pk_fma_f32 v[2:3], v[2:3], s[20:21], v[128:129] op_sel_hi:[1,0,0] neg_lo:[1,0,0] neg_hi:[1,0,0]
	v_pk_fma_f32 v[16:17], v[170:171], v[132:133], v[16:17]
	v_pk_mul_f32 v[2:3], v[0:1], v[2:3]
	s_nop 0
	v_exp_f32_e32 v2, v2
	v_exp_f32_e32 v3, v3
	s_nop 0
	v_pk_add_f32 v[2:3], v[2:3], 1.0 op_sel_hi:[1,0]
	s_nop 0
	v_rcp_f32_e32 v2, v2
	v_rcp_f32_e32 v3, v3
	s_nop 0
	v_pk_mul_f32 v[0:1], v[0:1], v[2:3]
	s_nop 0
	v_cvt_pk_bf16_f32 v0, v0, v1
	ds_write_b16 v215, v0 offset:64
	ds_write_b16_d16_hi v215, v0 offset:96
	v_lshlrev_b32_e32 v1, 16, v9
	v_lshlrev_b32_e32 v0, 16, v8
	v_pk_fma_f32 v[0:1], v[176:177], v[0:1], v[4:5]
	v_add_u32_e32 v4, v139, v148
	v_pk_mul_f32 v[2:3], v[0:1], v[0:1]
	v_ashrrev_i32_e32 v5, 31, v4
	v_pk_fma_f32 v[2:3], v[2:3], s[20:21], v[128:129] op_sel_hi:[1,0,0] neg_lo:[1,0,0] neg_hi:[1,0,0]
	v_lshlrev_b64 v[4:5], 11, v[4:5]
	v_pk_mul_f32 v[2:3], v[0:1], v[2:3]
	v_lshl_add_u64 v[4:5], v[126:127], 0, v[4:5]
	v_exp_f32_e32 v2, v2
	v_exp_f32_e32 v3, v3
	s_nop 0
	v_pk_add_f32 v[2:3], v[2:3], 1.0 op_sel_hi:[1,0]
	s_nop 0
	v_rcp_f32_e32 v2, v2
	v_rcp_f32_e32 v3, v3
	s_nop 0
	v_pk_mul_f32 v[0:1], v[0:1], v[2:3]
	s_nop 0
	v_cvt_pk_bf16_f32 v0, v0, v1
	ds_write_b16 v215, v0 offset:512
	ds_write_b16_d16_hi v215, v0 offset:544
	s_waitcnt lgkmcnt(4)
	v_lshlrev_b32_e32 v1, 16, v11
	v_lshlrev_b32_e32 v0, 16, v10
	v_pk_fma_f32 v[0:1], v[176:177], v[0:1], v[6:7]
	s_nop 0
	v_pk_mul_f32 v[2:3], v[0:1], v[0:1]
	s_nop 0
	v_pk_fma_f32 v[2:3], v[2:3], s[20:21], v[128:129] op_sel_hi:[1,0,0] neg_lo:[1,0,0] neg_hi:[1,0,0]
	s_nop 0
	v_pk_mul_f32 v[2:3], v[0:1], v[2:3]
	s_nop 0
	v_exp_f32_e32 v2, v2
	v_exp_f32_e32 v3, v3
	s_nop 0
	v_pk_add_f32 v[2:3], v[2:3], 1.0 op_sel_hi:[1,0]
	s_nop 0
	v_rcp_f32_e32 v2, v2
	v_rcp_f32_e32 v3, v3
	s_nop 0
	v_pk_mul_f32 v[0:1], v[0:1], v[2:3]
	s_nop 0
	v_cvt_pk_bf16_f32 v0, v0, v1
	ds_write_b16 v215, v0 offset:576
	ds_write_b16_d16_hi v215, v0 offset:608
	s_waitcnt lgkmcnt(0)
; #define LAS __attribute__((address_space(3)))
; #define LDS_WAIT() asm volatile("s_waitcnt lgkmcnt(0)" ::: "memory")
; __device__ __forceinline__ void ssm_phase(Frame& F) {
;     ...
; #pragma unroll
;             for (int s = 0; s < 8; ++s) {
;                 *(LAS bf16x8*)(ut + l31 * 32 + 16 * h) = afr[s];
;                 const f32x16 D0 = __builtin_amdgcn_mfma_f32_32x32x16_bf16(afr[s], bfrag[0], z, 0, 0, 0), D1 = __builtin_amdgcn_mfma_f32_32x32x16_bf16(afr[s], bfrag[1], z, 0, 0, 0),
;                              D2 = __builtin_amdgcn_mfma_f32_32x32x16_bf16(afr[s], bfrag[2], z, 0, 0, 0), D3 = __builtin_amdgcn_mfma_f32_32x32x16_bf16(afr[s], bfrag[3], z, 0, 0, 0);
; #pragma unroll
;                 for (int t = 0; t < 8; ++t) {
;                     const f2v d0 = {D0[2 * t], D0[2 * t + 1]}, d1 = {D1[2 * t], D1[2 * t + 1]}, d2 = {D2[2 * t], D2[2 * t + 1]}, d3 = {D3[2 * t], D3[2 * t + 1]};
;                     const f2v nr0 = fma2(AR0, Sre0, fma2(NAI0, Sim0, d0)), ni0 = fma2(AR0, Sim0, fma2(AI0, Sre0, d2));
;                     const f2v nr1 = fma2(AR1, Sre1, fma2(NAI1, Sim1, d1)), ni1 = fma2(AR1, Sim1, fma2(AI1, Sre1, d3));
;                     Sre0 = nr0; Sim0 = ni0; Sre1 = nr1; Sim1 = ni1;
; #pragma unroll
;                     for (int e = 0; e < 2; ++e) { v2u w; w.x = cvt2(nr0[e], nr1[e]); w.y = cvt2(ni0[e], ni1[e]); *(LAS v2u*)(st + (16 * h + 2 * t + e) * 272 + 8 * l31) = w; }
;                 }
;                 LDS_WAIT(); asm volatile("" ::: "memory");
;                 f32x4 acc0 = (f32x4){0.f, 0.f, 0.f, 0.f}, acc1 = (f32x4){0.f, 0.f, 0.f, 0.f};
; #pragma unroll
;                 for (int ks = 0; ks < 4; ++ks) {
;                     const bf16x8 s0 = *(const LAS bf16x8*)(st + l15 * 272 + 64 * ks + 16 * qq), s1 = *(const LAS bf16x8*)(st + (16 + l15) * 272 + 64 * ks + 16 * qq);
;                     acc0 = __builtin_amdgcn_mfma_f32_16x16x32_bf16(s0, cfrag[ks], acc0, 0, 0, 0); acc1 = __builtin_amdgcn_mfma_f32_16x16x32_bf16(s1, cfrag[ks], acc1, 0, 0, 0); }
;                 float uu[2][4];
; #pragma unroll
;                 for (int rb = 0; rb < 2; ++rb)
; #pragma unroll
;                     for (int i2 = 0; i2 < 4; ++i2) uu[rb][i2] = bf1(*(const LAS bf16*)(ut + (i2 + 4 * rb + 8 * qq) * 32 + 2 * l15));
; #pragma unroll
;                 for (int rb = 0; rb < 2; ++rb)
; #pragma unroll
;                     for (int i2 = 0; i2 < 4; i2 += 2) {
	ds_read_b128 v[0:3], v147
	s_waitcnt lgkmcnt(0)
	global_store_dwordx4 v[4:5], v[0:3], off
	s_nop 1
	v_mfma_f32_32x32x16_bf16 v[0:15], v[116:119], v[68:71], 0
	s_waitcnt lgkmcnt(0)
	ds_write_b128 v212, v[116:119]
	v_cvt_pk_bf16_f32 v117, v48, v16
	v_cvt_pk_bf16_f32 v119, v49, v17
	s_nop 8
	v_pk_fma_f32 v[0:1], v[180:181], v[132:133], v[0:1]
	s_nop 0
	v_pk_fma_f32 v[0:1], v[170:171], v[122:123], v[0:1]
	v_pk_fma_f32 v[2:3], v[180:181], v[16:17], v[2:3]
	v_cvt_pk_bf16_f32 v116, v32, v0
	v_cvt_pk_bf16_f32 v118, v33, v1
	v_pk_fma_f32 v[32:33], v[172:173], v[32:33], v[50:51]
	v_pk_fma_f32 v[2:3], v[170:171], v[0:1], v[2:3]
	v_pk_fma_f32 v[0:1], v[174:175], v[0:1], v[18:19]
	v_pk_fma_f32 v[32:33], v[168:169], v[48:49], v[32:33]
	v_pk_fma_f32 v[0:1], v[170:171], v[16:17], v[0:1]
	v_cvt_pk_bf16_f32 v16, v34, v2
	v_cvt_pk_bf16_f32 v17, v32, v0
	v_cvt_pk_bf16_f32 v18, v35, v3
	v_cvt_pk_bf16_f32 v19, v33, v1
	v_pk_fma_f32 v[4:5], v[180:181], v[0:1], v[4:5]
	ds_write2_b64 v149, v[16:17], v[18:19] offset0:68 offset1:102
	v_pk_fma_f32 v[16:17], v[178:179], v[32:33], v[36:37]
	v_pk_fma_f32 v[18:19], v[172:173], v[34:35], v[52:53]
	v_pk_fma_f32 v[4:5], v[170:171], v[2:3], v[4:5]
	v_pk_fma_f32 v[2:3], v[174:175], v[2:3], v[20:21]
	v_pk_fma_f32 v[16:17], v[168:169], v[34:35], v[16:17]
	v_pk_fma_f32 v[18:19], v[168:169], v[32:33], v[18:19]
	v_pk_fma_f32 v[0:1], v[170:171], v[0:1], v[2:3]
	v_cvt_pk_bf16_f32 v2, v16, v4
	v_cvt_pk_bf16_f32 v3, v18, v0
	v_cvt_pk_bf16_f32 v20, v17, v5
	v_cvt_pk_bf16_f32 v21, v19, v1
	ds_write2_b64 v149, v[2:3], v[20:21] offset0:136 offset1:170
	v_pk_fma_f32 v[2:3], v[178:179], v[18:19], v[38:39]
	v_pk_fma_f32 v[6:7], v[180:181], v[0:1], v[6:7]
	v_pk_fma_f32 v[2:3], v[168:169], v[16:17], v[2:3]
	v_pk_fma_f32 v[16:17], v[172:173], v[16:17], v[54:55]
	v_pk_fma_f32 v[6:7], v[170:171], v[4:5], v[6:7]
	v_pk_fma_f32 v[4:5], v[174:175], v[4:5], v[22:23]
	v_pk_fma_f32 v[16:17], v[168:169], v[18:19], v[16:17]
	v_pk_fma_f32 v[0:1], v[170:171], v[0:1], v[4:5]
	v_cvt_pk_bf16_f32 v4, v2, v6
	v_cvt_pk_bf16_f32 v5, v16, v0
	v_cvt_pk_bf16_f32 v18, v3, v7
	v_cvt_pk_bf16_f32 v19, v17, v1
	ds_write2_b64 v149, v[4:5], v[18:19] offset0:204 offset1:238
	v_pk_fma_f32 v[4:5], v[178:179], v[16:17], v[40:41]
	v_pk_fma_f32 v[8:9], v[180:181], v[0:1], v[8:9]
	v_pk_fma_f32 v[4:5], v[168:169], v[2:3], v[4:5]
	v_pk_fma_f32 v[2:3], v[172:173], v[2:3], v[56:57]
	v_pk_fma_f32 v[8:9], v[170:171], v[6:7], v[8:9]
	v_pk_fma_f32 v[6:7], v[174:175], v[6:7], v[24:25]
	v_pk_fma_f32 v[2:3], v[168:169], v[16:17], v[2:3]
	v_pk_fma_f32 v[0:1], v[170:171], v[0:1], v[6:7]
	v_cvt_pk_bf16_f32 v6, v4, v8
	v_cvt_pk_bf16_f32 v7, v2, v0
	v_cvt_pk_bf16_f32 v16, v5, v9
	v_cvt_pk_bf16_f32 v17, v3, v1
	ds_write2_b64 v146, v[6:7], v[16:17] offset0:16 offset1:50
	v_pk_fma_f32 v[6:7], v[178:179], v[2:3], v[42:43]
	ds_write2_b64 v149, v[116:117], v[118:119] offset1:34
	v_pk_fma_f32 v[6:7], v[168:169], v[4:5], v[6:7]
	v_pk_fma_f32 v[4:5], v[172:173], v[4:5], v[58:59]
	s_nop 0
	v_pk_fma_f32 v[2:3], v[168:169], v[2:3], v[4:5]
	v_pk_fma_f32 v[4:5], v[180:181], v[0:1], v[10:11]
	s_nop 0
	v_pk_fma_f32 v[4:5], v[170:171], v[8:9], v[4:5]
	v_pk_fma_f32 v[8:9], v[174:175], v[8:9], v[26:27]
	v_cvt_pk_bf16_f32 v10, v7, v5
	v_pk_fma_f32 v[0:1], v[170:171], v[0:1], v[8:9]
	v_cvt_pk_bf16_f32 v8, v6, v4
	v_cvt_pk_bf16_f32 v9, v2, v0
	v_cvt_pk_bf16_f32 v11, v3, v1
	ds_write2_b64 v146, v[8:9], v[10:11] offset0:84 offset1:118
	v_pk_fma_f32 v[8:9], v[178:179], v[2:3], v[44:45]
	s_nop 0
	v_pk_fma_f32 v[8:9], v[168:169], v[6:7], v[8:9]
	v_pk_fma_f32 v[6:7], v[172:173], v[6:7], v[60:61]
	s_nop 0
	v_pk_fma_f32 v[2:3], v[168:169], v[2:3], v[6:7]
	v_pk_fma_f32 v[6:7], v[180:181], v[0:1], v[12:13]
	s_nop 0
	v_pk_fma_f32 v[6:7], v[170:171], v[4:5], v[6:7]
	v_pk_fma_f32 v[4:5], v[174:175], v[4:5], v[28:29]
	v_cvt_pk_bf16_f32 v10, v9, v7
	v_pk_fma_f32 v[0:1], v[170:171], v[0:1], v[4:5]
	v_cvt_pk_bf16_f32 v4, v8, v6
	v_cvt_pk_bf16_f32 v5, v2, v0
	v_cvt_pk_bf16_f32 v11, v3, v1
	ds_write2_b64 v146, v[4:5], v[10:11] offset0:152 offset1:186
	v_pk_fma_f32 v[4:5], v[178:179], v[2:3], v[46:47]
	v_mfma_f32_32x32x16_bf16 v[32:47], v[112:115], v[72:75], 0
	v_fma_f32 v116, v168, v8, v4
	v_fma_f32 v117, v169, v9, v5
	v_fma_f32 v4, v172, v8, v62
	v_fma_f32 v5, v173, v9, v63
	v_fma_f32 v120, v168, v2, v4
	v_fma_f32 v121, v169, v3, v5
	v_pk_fma_f32 v[2:3], v[180:181], v[0:1], v[14:15]
	s_nop 4
	v_pk_fma_f32 v[32:33], v[172:173], v[116:117], v[32:33]
	v_pk_fma_f32 v[118:119], v[170:171], v[6:7], v[2:3]
	v_pk_fma_f32 v[2:3], v[174:175], v[6:7], v[30:31]
	v_mfma_f32_32x32x16_bf16 v[48:63], v[112:115], v[64:67], 0
	v_fma_f32 v122, v170, v0, v2
	v_fma_f32 v123, v171, v1, v3
	v_cvt_pk_bf16_f32 v0, v116, v118
	v_cvt_pk_bf16_f32 v1, v120, v122
	v_cvt_pk_bf16_f32 v2, v117, v119
	v_cvt_pk_bf16_f32 v3, v121, v123
	ds_write2_b64 v146, v[0:1], v[2:3] offset0:220 offset1:254
	s_waitcnt lgkmcnt(0)
	ds_read_b128 v[0:3], v213 offset:32768
	ds_read_b128 v[4:7], v213 offset:37120
	s_waitcnt lgkmcnt(1)
	v_mfma_f32_16x16x32_bf16 v[0:3], v[0:3], v[80:83], 0
	ds_read_b128 v[8:11], v213 offset:32832
	ds_read_b128 v[12:15], v213 offset:37184
	v_pk_fma_f32 v[48:49], v[178:179], v[120:121], v[48:49]
	v_pk_fma_f32 v[32:33], v[168:169], v[120:121], v[32:33]
	s_waitcnt lgkmcnt(1)
	v_mfma_f32_16x16x32_bf16 v[0:3], v[8:11], v[84:87], v[0:3]
	ds_read_b128 v[8:11], v213 offset:32896
	ds_read_b128 v[16:19], v213 offset:37248
	v_pk_fma_f32 v[48:49], v[168:169], v[116:117], v[48:49]
	v_pk_fma_f32 v[50:51], v[178:179], v[32:33], v[50:51]
	s_waitcnt lgkmcnt(1)
; #define LAS __attribute__((address_space(3)))
; #define LDS_WAIT() asm volatile("s_waitcnt lgkmcnt(0)" ::: "memory")
; __device__ __forceinline__ void ssm_phase(Frame& F) {
;     ...
; #pragma unroll
;             for (int s = 0; s < 8; ++s) {
;                 *(LAS bf16x8*)(ut + l31 * 32 + 16 * h) = afr[s];
;                 const f32x16 D0 = __builtin_amdgcn_mfma_f32_32x32x16_bf16(afr[s], bfrag[0], z, 0, 0, 0), D1 = __builtin_amdgcn_mfma_f32_32x32x16_bf16(afr[s], bfrag[1], z, 0, 0, 0),
;                              D2 = __builtin_amdgcn_mfma_f32_32x32x16_bf16(afr[s], bfrag[2], z, 0, 0, 0), D3 = __builtin_amdgcn_mfma_f32_32x32x16_bf16(afr[s], bfrag[3], z, 0, 0, 0);
; #pragma unroll
;                 for (int t = 0; t < 8; ++t) {
;                     const f2v d0 = {D0[2 * t], D0[2 * t + 1]}, d1 = {D1[2 * t], D1[2 * t + 1]}, d2 = {D2[2 * t], D2[2 * t + 1]}, d3 = {D3[2 * t], D3[2 * t + 1]};
;                     const f2v nr0 = fma2(AR0, Sre0, fma2(NAI0, Sim0, d0)), ni0 = fma2(AR0, Sim0, fma2(AI0, Sre0, d2));
;                     const f2v nr1 = fma2(AR1, Sre1, fma2(NAI1, Sim1, d1)), ni1 = fma2(AR1, Sim1, fma2(AI1, Sre1, d3));
;                     Sre0 = nr0; Sim0 = ni0; Sre1 = nr1; Sim1 = ni1;
; #pragma unroll
;                     for (int e = 0; e < 2; ++e) { v2u w; w.x = cvt2(nr0[e], nr1[e]); w.y = cvt2(ni0[e], ni1[e]); *(LAS v2u*)(st + (16 * h + 2 * t + e) * 272 + 8 * l31) = w; }
;                 }
;                 LDS_WAIT(); asm volatile("" ::: "memory");
;                 f32x4 acc0 = (f32x4){0.f, 0.f, 0.f, 0.f}, acc1 = (f32x4){0.f, 0.f, 0.f, 0.f};
; #pragma unroll
;                 for (int ks = 0; ks < 4; ++ks) {
;                     const bf16x8 s0 = *(const LAS bf16x8*)(st + l15 * 272 + 64 * ks + 16 * qq), s1 = *(const LAS bf16x8*)(st + (16 + l15) * 272 + 64 * ks + 16 * qq);
;                     acc0 = __builtin_amdgcn_mfma_f32_16x16x32_bf16(s0, cfrag[ks], acc0, 0, 0, 0); acc1 = __builtin_amdgcn_mfma_f32_16x16x32_bf16(s1, cfrag[ks], acc1, 0, 0, 0); }
;                 float uu[2][4];
; #pragma unroll
;                 for (int rb = 0; rb < 2; ++rb)
; #pragma unroll
;                     for (int i2 = 0; i2 < 4; ++i2) uu[rb][i2] = bf1(*(const LAS bf16*)(ut + (i2 + 4 * rb + 8 * qq) * 32 + 2 * l15));
; #pragma unroll
;                 for (int rb = 0; rb < 2; ++rb)
; #pragma unroll
;                     for (int i2 = 0; i2 < 4; i2 += 2) {
	v_mfma_f32_16x16x32_bf16 v[0:3], v[8:11], v[88:91], v[0:3]
	ds_read_b128 v[8:11], v213 offset:32960
	ds_read_b128 v[20:23], v213 offset:37312
	v_pk_fma_f32 v[34:35], v[172:173], v[48:49], v[34:35]
	v_pk_fma_f32 v[50:51], v[168:169], v[48:49], v[50:51]
	s_waitcnt lgkmcnt(1)
	v_mfma_f32_16x16x32_bf16 v[0:3], v[8:11], v[92:95], v[0:3]
	ds_read_u16 v8, v214
	ds_read_u16 v9, v214 offset:32
	s_waitcnt lgkmcnt(1)
	v_lshlrev_b32_e32 v8, 16, v8
	s_waitcnt lgkmcnt(0)
	v_lshlrev_b32_e32 v9, 16, v9
	s_nop 1
	v_pk_fma_f32 v[0:1], v[176:177], v[8:9], v[0:1]
	v_mfma_f32_16x16x32_bf16 v[4:7], v[4:7], v[80:83], 0
	v_mul_f32_e64 v8, v0, v0
	v_mul_f32_e64 v9, v1, v1
	v_pk_fma_f32 v[8:9], v[8:9], s[20:21], v[128:129] op_sel_hi:[1,0,0] neg_lo:[1,0,0] neg_hi:[1,0,0]
	v_mfma_f32_16x16x32_bf16 v[4:7], v[12:15], v[84:87], v[4:7]
	v_mul_f32_e64 v8, v0, v8
	v_mul_f32_e64 v9, v1, v9
	v_exp_f32_e32 v8, v8
	v_exp_f32_e32 v9, v9
	v_mfma_f32_16x16x32_bf16 v[4:7], v[16:19], v[88:91], v[4:7]
	v_add_f32_e64 v8, v8, 1.0
	v_add_f32_e64 v9, v9, 1.0
	v_rcp_f32_e32 v8, v8
	v_rcp_f32_e32 v9, v9
	v_mfma_f32_16x16x32_bf16 v[4:7], v[20:23], v[92:95], v[4:7]
	v_mul_f32_e64 v0, v0, v8
	v_mul_f32_e64 v1, v1, v9
	v_cvt_pk_bf16_f32 v0, v0, v1
	ds_read_u16 v8, v214 offset:128
	ds_read_u16 v9, v214 offset:160
	ds_write_b16 v215, v0
	ds_write_b16_d16_hi v215, v0 offset:32
	ds_read_u16 v0, v214 offset:64
	ds_read_u16 v1, v214 offset:96
	ds_read_u16 v10, v214 offset:192
	ds_read_u16 v11, v214 offset:224
	v_mfma_f32_32x32x16_bf16 v[16:31], v[112:115], v[68:71], 0
	s_waitcnt lgkmcnt(3)
	v_lshlrev_b32_e32 v0, 16, v0
	s_waitcnt lgkmcnt(2)
	v_lshlrev_b32_e32 v1, 16, v1
	v_fma_f32 v0, v176, v0, v2
	v_fma_f32 v1, v177, v1, v3
	v_pk_mul_f32 v[2:3], v[0:1], v[0:1]
	s_nop 4
	v_pk_fma_f32 v[16:17], v[180:181], v[122:123], v[16:17]
	v_pk_fma_f32 v[2:3], v[2:3], s[20:21], v[128:129] op_sel_hi:[1,0,0] neg_lo:[1,0,0] neg_hi:[1,0,0]
	v_pk_fma_f32 v[16:17], v[170:171], v[118:119], v[16:17]
	v_pk_mul_f32 v[2:3], v[0:1], v[2:3]
	s_nop 0
	v_exp_f32_e32 v2, v2
	v_exp_f32_e32 v3, v3
	s_nop 0
	v_pk_add_f32 v[2:3], v[2:3], 1.0 op_sel_hi:[1,0]
	s_nop 0
	v_rcp_f32_e32 v2, v2
	v_rcp_f32_e32 v3, v3
	s_nop 0
	v_pk_mul_f32 v[0:1], v[0:1], v[2:3]
	s_nop 0
	v_cvt_pk_bf16_f32 v0, v0, v1
	ds_write_b16 v215, v0 offset:64
	ds_write_b16_d16_hi v215, v0 offset:96
	v_lshlrev_b32_e32 v1, 16, v9
	v_lshlrev_b32_e32 v0, 16, v8
	v_pk_fma_f32 v[0:1], v[176:177], v[0:1], v[4:5]
	v_add_u32_e32 v4, v140, v148
	v_pk_mul_f32 v[2:3], v[0:1], v[0:1]
	v_ashrrev_i32_e32 v5, 31, v4
	v_pk_fma_f32 v[2:3], v[2:3], s[20:21], v[128:129] op_sel_hi:[1,0,0] neg_lo:[1,0,0] neg_hi:[1,0,0]
	v_lshlrev_b64 v[4:5], 11, v[4:5]
	v_pk_mul_f32 v[2:3], v[0:1], v[2:3]
	v_lshl_add_u64 v[4:5], v[126:127], 0, v[4:5]
	v_exp_f32_e32 v2, v2
	v_exp_f32_e32 v3, v3
	s_nop 0
	v_pk_add_f32 v[2:3], v[2:3], 1.0 op_sel_hi:[1,0]
	s_nop 0
	v_rcp_f32_e32 v2, v2
	v_rcp_f32_e32 v3, v3
	s_nop 0
	v_pk_mul_f32 v[0:1], v[0:1], v[2:3]
	s_nop 0
	v_cvt_pk_bf16_f32 v0, v0, v1
	ds_write_b16 v215, v0 offset:512
	ds_write_b16_d16_hi v215, v0 offset:544
	s_waitcnt lgkmcnt(4)
	v_lshlrev_b32_e32 v1, 16, v11
	v_lshlrev_b32_e32 v0, 16, v10
	v_pk_fma_f32 v[0:1], v[176:177], v[0:1], v[6:7]
	s_nop 0
	v_pk_mul_f32 v[2:3], v[0:1], v[0:1]
	s_nop 0
	v_pk_fma_f32 v[2:3], v[2:3], s[20:21], v[128:129] op_sel_hi:[1,0,0] neg_lo:[1,0,0] neg_hi:[1,0,0]
	s_nop 0
	v_pk_mul_f32 v[2:3], v[0:1], v[2:3]
	s_nop 0
	v_exp_f32_e32 v2, v2
	v_exp_f32_e32 v3, v3
	s_nop 0
	v_pk_add_f32 v[2:3], v[2:3], 1.0 op_sel_hi:[1,0]
	s_nop 0
	v_rcp_f32_e32 v2, v2
	v_rcp_f32_e32 v3, v3
	s_nop 0
	v_pk_mul_f32 v[0:1], v[0:1], v[2:3]
	s_nop 0
	v_cvt_pk_bf16_f32 v0, v0, v1
	ds_write_b16 v215, v0 offset:576
	ds_write_b16_d16_hi v215, v0 offset:608
	s_waitcnt lgkmcnt(0)
	ds_read_b128 v[0:3], v147
	s_waitcnt lgkmcnt(0)
	global_store_dwordx4 v[4:5], v[0:3], off
	s_nop 1
	v_mfma_f32_32x32x16_bf16 v[0:15], v[112:115], v[76:79], 0
	s_waitcnt lgkmcnt(0)
	ds_write_b128 v212, v[112:115]
	v_cvt_pk_bf16_f32 v112, v48, v16
	v_cvt_pk_bf16_f32 v114, v49, v17
	s_nop 8
	v_pk_fma_f32 v[0:1], v[174:175], v[118:119], v[0:1]
	s_nop 0
	v_pk_fma_f32 v[0:1], v[170:171], v[122:123], v[0:1]
	v_pk_fma_f32 v[2:3], v[174:175], v[16:17], v[2:3]
	v_pk_fma_f32 v[18:19], v[180:181], v[0:1], v[18:19]
	v_cvt_pk_bf16_f32 v113, v32, v0
	v_cvt_pk_bf16_f32 v115, v33, v1
	v_pk_fma_f32 v[32:33], v[168:169], v[32:33], v[34:35]
	v_pk_fma_f32 v[18:19], v[170:171], v[16:17], v[18:19]
	v_pk_fma_f32 v[0:1], v[170:171], v[0:1], v[2:3]
	v_cvt_pk_bf16_f32 v2, v50, v18
	v_cvt_pk_bf16_f32 v3, v32, v0
	v_cvt_pk_bf16_f32 v16, v51, v19
	v_cvt_pk_bf16_f32 v17, v33, v1
	ds_write2_b64 v149, v[2:3], v[16:17] offset0:68 offset1:102
	v_pk_fma_f32 v[2:3], v[178:179], v[32:33], v[52:53]
	v_pk_fma_f32 v[16:17], v[172:173], v[50:51], v[36:37]
	v_pk_fma_f32 v[20:21], v[180:181], v[0:1], v[20:21]
	v_pk_fma_f32 v[4:5], v[174:175], v[18:19], v[4:5]
	v_pk_fma_f32 v[2:3], v[168:169], v[50:51], v[2:3]
	v_pk_fma_f32 v[16:17], v[168:169], v[32:33], v[16:17]
	v_pk_fma_f32 v[20:21], v[170:171], v[18:19], v[20:21]
	v_pk_fma_f32 v[0:1], v[170:171], v[0:1], v[4:5]
	v_cvt_pk_bf16_f32 v4, v2, v20
	v_cvt_pk_bf16_f32 v5, v16, v0
	v_cvt_pk_bf16_f32 v18, v3, v21
	v_cvt_pk_bf16_f32 v19, v17, v1
	ds_write2_b64 v149, v[4:5], v[18:19] offset0:136 offset1:170
	v_pk_fma_f32 v[4:5], v[178:179], v[16:17], v[54:55]
	v_pk_fma_f32 v[6:7], v[174:175], v[20:21], v[6:7]
	v_pk_fma_f32 v[4:5], v[168:169], v[2:3], v[4:5]
	v_pk_fma_f32 v[2:3], v[172:173], v[2:3], v[38:39]
	ds_write2_b64 v149, v[112:113], v[114:115] offset1:34
	v_pk_fma_f32 v[2:3], v[168:169], v[16:17], v[2:3]
	v_pk_fma_f32 v[16:17], v[180:181], v[0:1], v[22:23]
; #define LAS __attribute__((address_space(3)))
; #define LDS_WAIT() asm volatile("s_waitcnt lgkmcnt(0)" ::: "memory")
; __device__ __forceinline__ void ssm_phase(Frame& F) {
;     ...
; #pragma unroll
;             for (int s = 0; s < 8; ++s) {
;                 *(LAS bf16x8*)(ut + l31 * 32 + 16 * h) = afr[s];
;                 const f32x16 D0 = __builtin_amdgcn_mfma_f32_32x32x16_bf16(afr[s], bfrag[0], z, 0, 0, 0), D1 = __builtin_amdgcn_mfma_f32_32x32x16_bf16(afr[s], bfrag[1], z, 0, 0, 0),
;                              D2 = __builtin_amdgcn_mfma_f32_32x32x16_bf16(afr[s], bfrag[2], z, 0, 0, 0), D3 = __builtin_amdgcn_mfma_f32_32x32x16_bf16(afr[s], bfrag[3], z, 0, 0, 0);
; #pragma unroll
;                 for (int t = 0; t < 8; ++t) {
;                     const f2v d0 = {D0[2 * t], D0[2 * t + 1]}, d1 = {D1[2 * t], D1[2 * t + 1]}, d2 = {D2[2 * t], D2[2 * t + 1]}, d3 = {D3[2 * t], D3[2 * t + 1]};
;                     const f2v nr0 = fma2(AR0, Sre0, fma2(NAI0, Sim0, d0)), ni0 = fma2(AR0, Sim0, fma2(AI0, Sre0, d2));
;                     const f2v nr1 = fma2(AR1, Sre1, fma2(NAI1, Sim1, d1)), ni1 = fma2(AR1, Sim1, fma2(AI1, Sre1, d3));
;                     Sre0 = nr0; Sim0 = ni0; Sre1 = nr1; Sim1 = ni1;
; #pragma unroll
;                     for (int e = 0; e < 2; ++e) { v2u w; w.x = cvt2(nr0[e], nr1[e]); w.y = cvt2(ni0[e], ni1[e]); *(LAS v2u*)(st + (16 * h + 2 * t + e) * 272 + 8 * l31) = w; }
;                 }
;                 LDS_WAIT(); asm volatile("" ::: "memory");
;                 f32x4 acc0 = (f32x4){0.f, 0.f, 0.f, 0.f}, acc1 = (f32x4){0.f, 0.f, 0.f, 0.f};
; #pragma unroll
;                 for (int ks = 0; ks < 4; ++ks) {
;                     const bf16x8 s0 = *(const LAS bf16x8*)(st + l15 * 272 + 64 * ks + 16 * qq), s1 = *(const LAS bf16x8*)(st + (16 + l15) * 272 + 64 * ks + 16 * qq);
;                     acc0 = __builtin_amdgcn_mfma_f32_16x16x32_bf16(s0, cfrag[ks], acc0, 0, 0, 0); acc1 = __builtin_amdgcn_mfma_f32_16x16x32_bf16(s1, cfrag[ks], acc1, 0, 0, 0); }
;                 float uu[2][4];
; #pragma unroll
;                 for (int rb = 0; rb < 2; ++rb)
; #pragma unroll
;                     for (int i2 = 0; i2 < 4; ++i2) uu[rb][i2] = bf1(*(const LAS bf16*)(ut + (i2 + 4 * rb + 8 * qq) * 32 + 2 * l15));
; #pragma unroll
;                 for (int rb = 0; rb < 2; ++rb)
; #pragma unroll
;                     for (int i2 = 0; i2 < 4; i2 += 2) {
	v_pk_fma_f32 v[0:1], v[170:171], v[0:1], v[6:7]
	v_pk_fma_f32 v[16:17], v[170:171], v[20:21], v[16:17]
	v_cvt_pk_bf16_f32 v7, v2, v0
	v_cvt_pk_bf16_f32 v6, v4, v16
	v_cvt_pk_bf16_f32 v18, v5, v17
	v_cvt_pk_bf16_f32 v19, v3, v1
	ds_write2_b64 v149, v[6:7], v[18:19] offset0:204 offset1:238
	v_pk_fma_f32 v[6:7], v[178:179], v[2:3], v[56:57]
	v_pk_fma_f32 v[8:9], v[174:175], v[16:17], v[8:9]
	v_pk_fma_f32 v[6:7], v[168:169], v[4:5], v[6:7]
	v_pk_fma_f32 v[4:5], v[172:173], v[4:5], v[40:41]
	s_nop 0
	v_pk_fma_f32 v[2:3], v[168:169], v[2:3], v[4:5]
	v_pk_fma_f32 v[4:5], v[180:181], v[0:1], v[24:25]
	v_pk_fma_f32 v[0:1], v[170:171], v[0:1], v[8:9]
	v_pk_fma_f32 v[4:5], v[170:171], v[16:17], v[4:5]
	v_cvt_pk_bf16_f32 v9, v2, v0
	v_cvt_pk_bf16_f32 v8, v6, v4
	v_cvt_pk_bf16_f32 v16, v7, v5
	v_cvt_pk_bf16_f32 v17, v3, v1
	ds_write2_b64 v146, v[8:9], v[16:17] offset0:16 offset1:50
	v_pk_fma_f32 v[8:9], v[178:179], v[2:3], v[58:59]
	s_nop 0
	v_pk_fma_f32 v[8:9], v[168:169], v[6:7], v[8:9]
	v_pk_fma_f32 v[6:7], v[172:173], v[6:7], v[42:43]
	s_nop 0
	v_pk_fma_f32 v[2:3], v[168:169], v[2:3], v[6:7]
	v_pk_fma_f32 v[6:7], v[180:181], v[0:1], v[26:27]
	s_nop 0
	v_pk_fma_f32 v[16:17], v[170:171], v[4:5], v[6:7]
	v_pk_fma_f32 v[4:5], v[174:175], v[4:5], v[10:11]
	s_nop 0
	v_pk_fma_f32 v[10:11], v[170:171], v[0:1], v[4:5]
	v_cvt_pk_bf16_f32 v0, v8, v16
	v_cvt_pk_bf16_f32 v1, v2, v10
	v_cvt_pk_bf16_f32 v4, v9, v17
	v_cvt_pk_bf16_f32 v5, v3, v11
	ds_write2_b64 v146, v[0:1], v[4:5] offset0:84 offset1:118
	v_pk_fma_f32 v[0:1], v[178:179], v[2:3], v[60:61]
	s_nop 0
	v_pk_fma_f32 v[4:5], v[168:169], v[8:9], v[0:1]
	v_pk_fma_f32 v[0:1], v[172:173], v[8:9], v[44:45]
	s_nop 0
	v_pk_fma_f32 v[6:7], v[168:169], v[2:3], v[0:1]
	v_pk_fma_f32 v[0:1], v[180:181], v[10:11], v[28:29]
	v_pk_fma_f32 v[2:3], v[174:175], v[16:17], v[12:13]
	v_pk_fma_f32 v[0:1], v[170:171], v[16:17], v[0:1]
	v_pk_fma_f32 v[2:3], v[170:171], v[10:11], v[2:3]
	v_cvt_pk_bf16_f32 v8, v4, v0
	v_cvt_pk_bf16_f32 v9, v6, v2
	v_cvt_pk_bf16_f32 v10, v5, v1
	v_cvt_pk_bf16_f32 v11, v7, v3
	ds_write2_b64 v146, v[8:9], v[10:11] offset0:152 offset1:186
	v_pk_fma_f32 v[8:9], v[178:179], v[6:7], v[62:63]
	v_mfma_f32_32x32x16_bf16 v[48:63], v[108:111], v[64:67], 0
	v_fma_f32 v112, v168, v4, v8
	v_fma_f32 v113, v169, v5, v9
	v_fma_f32 v4, v172, v4, v46
	v_fma_f32 v5, v173, v5, v47
	v_fma_f32 v114, v168, v6, v4
	v_fma_f32 v115, v169, v7, v5
	v_pk_fma_f32 v[4:5], v[180:181], v[2:3], v[30:31]
	s_nop 4
	v_pk_fma_f32 v[48:49], v[178:179], v[114:115], v[48:49]
	v_pk_fma_f32 v[116:117], v[170:171], v[0:1], v[4:5]
	v_pk_fma_f32 v[0:1], v[174:175], v[0:1], v[14:15]
	v_mfma_f32_32x32x16_bf16 v[32:47], v[108:111], v[72:75], 0
	v_fma_f32 v118, v170, v2, v0
	v_fma_f32 v119, v171, v3, v1
	v_cvt_pk_bf16_f32 v0, v112, v116
	v_cvt_pk_bf16_f32 v1, v114, v118
	v_cvt_pk_bf16_f32 v2, v113, v117
	v_cvt_pk_bf16_f32 v3, v115, v119
	ds_write2_b64 v146, v[0:1], v[2:3] offset0:220 offset1:254
	s_waitcnt lgkmcnt(0)
	ds_read_b128 v[0:3], v213 offset:32768
	ds_read_b128 v[4:7], v213 offset:37120
	s_waitcnt lgkmcnt(1)
	v_mfma_f32_16x16x32_bf16 v[0:3], v[0:3], v[80:83], 0
	ds_read_b128 v[8:11], v213 offset:32832
	ds_read_b128 v[12:15], v213 offset:37184
	v_pk_fma_f32 v[32:33], v[172:173], v[112:113], v[32:33]
	v_pk_fma_f32 v[48:49], v[168:169], v[112:113], v[48:49]
	s_waitcnt lgkmcnt(1)
	v_mfma_f32_16x16x32_bf16 v[0:3], v[8:11], v[84:87], v[0:3]
	ds_read_b128 v[8:11], v213 offset:32896
	ds_read_b128 v[16:19], v213 offset:37248
	v_pk_fma_f32 v[32:33], v[168:169], v[114:115], v[32:33]
	v_pk_fma_f32 v[34:35], v[172:173], v[48:49], v[34:35]
	s_waitcnt lgkmcnt(1)
	v_mfma_f32_16x16x32_bf16 v[0:3], v[8:11], v[88:91], v[0:3]
	ds_read_b128 v[8:11], v213 offset:32960
	ds_read_b128 v[20:23], v213 offset:37312
	v_pk_fma_f32 v[50:51], v[178:179], v[32:33], v[50:51]
	s_waitcnt lgkmcnt(1)
	v_mfma_f32_16x16x32_bf16 v[0:3], v[8:11], v[92:95], v[0:3]
	ds_read_u16 v8, v214
	ds_read_u16 v9, v214 offset:32
	v_pk_fma_f32 v[50:51], v[168:169], v[48:49], v[50:51]
	s_waitcnt lgkmcnt(1)
	v_lshlrev_b32_e32 v8, 16, v8
	s_waitcnt lgkmcnt(0)
	v_lshlrev_b32_e32 v9, 16, v9
	s_nop 0
	v_pk_fma_f32 v[0:1], v[176:177], v[8:9], v[0:1]
	v_mfma_f32_16x16x32_bf16 v[4:7], v[4:7], v[80:83], 0
	v_mul_f32_e64 v8, v0, v0
	v_mul_f32_e64 v9, v1, v1
	v_pk_fma_f32 v[8:9], v[8:9], s[20:21], v[128:129] op_sel_hi:[1,0,0] neg_lo:[1,0,0] neg_hi:[1,0,0]
	v_mfma_f32_16x16x32_bf16 v[4:7], v[12:15], v[84:87], v[4:7]
	v_mul_f32_e64 v8, v0, v8
	v_mul_f32_e64 v9, v1, v9
	v_exp_f32_e32 v8, v8
	v_exp_f32_e32 v9, v9
	v_mfma_f32_16x16x32_bf16 v[4:7], v[16:19], v[88:91], v[4:7]
	v_add_f32_e64 v8, v8, 1.0
	v_add_f32_e64 v9, v9, 1.0
	v_rcp_f32_e32 v8, v8
	v_rcp_f32_e32 v9, v9
	v_mfma_f32_16x16x32_bf16 v[4:7], v[20:23], v[92:95], v[4:7]
	v_mul_f32_e64 v0, v0, v8
	v_mul_f32_e64 v1, v1, v9
	v_cvt_pk_bf16_f32 v0, v0, v1
	ds_read_u16 v8, v214 offset:128
	ds_read_u16 v9, v214 offset:160
	ds_write_b16 v215, v0
	ds_write_b16_d16_hi v215, v0 offset:32
	ds_read_u16 v0, v214 offset:64
	ds_read_u16 v1, v214 offset:96
	ds_read_u16 v10, v214 offset:192
	ds_read_u16 v11, v214 offset:224
	v_mfma_f32_32x32x16_bf16 v[16:31], v[108:111], v[68:71], 0
	s_waitcnt lgkmcnt(3)
	v_lshlrev_b32_e32 v0, 16, v0
	s_waitcnt lgkmcnt(2)
; #define LAS __attribute__((address_space(3)))
; #define LDS_WAIT() asm volatile("s_waitcnt lgkmcnt(0)" ::: "memory")
; __device__ __forceinline__ void ssm_phase(Frame& F) {
;     ...
; #pragma unroll
;             for (int s = 0; s < 8; ++s) {
;                 *(LAS bf16x8*)(ut + l31 * 32 + 16 * h) = afr[s];
;                 const f32x16 D0 = __builtin_amdgcn_mfma_f32_32x32x16_bf16(afr[s], bfrag[0], z, 0, 0, 0), D1 = __builtin_amdgcn_mfma_f32_32x32x16_bf16(afr[s], bfrag[1], z, 0, 0, 0),
;                              D2 = __builtin_amdgcn_mfma_f32_32x32x16_bf16(afr[s], bfrag[2], z, 0, 0, 0), D3 = __builtin_amdgcn_mfma_f32_32x32x16_bf16(afr[s], bfrag[3], z, 0, 0, 0);
; #pragma unroll
;                 for (int t = 0; t < 8; ++t) {
;                     const f2v d0 = {D0[2 * t], D0[2 * t + 1]}, d1 = {D1[2 * t], D1[2 * t + 1]}, d2 = {D2[2 * t], D2[2 * t + 1]}, d3 = {D3[2 * t], D3[2 * t + 1]};
;                     const f2v nr0 = fma2(AR0, Sre0, fma2(NAI0, Sim0, d0)), ni0 = fma2(AR0, Sim0, fma2(AI0, Sre0, d2));
;                     const f2v nr1 = fma2(AR1, Sre1, fma2(NAI1, Sim1, d1)), ni1 = fma2(AR1, Sim1, fma2(AI1, Sre1, d3));
;                     Sre0 = nr0; Sim0 = ni0; Sre1 = nr1; Sim1 = ni1;
; #pragma unroll
;                     for (int e = 0; e < 2; ++e) { v2u w; w.x = cvt2(nr0[e], nr1[e]); w.y = cvt2(ni0[e], ni1[e]); *(LAS v2u*)(st + (16 * h + 2 * t + e) * 272 + 8 * l31) = w; }
;                 }
;                 LDS_WAIT(); asm volatile("" ::: "memory");
;                 f32x4 acc0 = (f32x4){0.f, 0.f, 0.f, 0.f}, acc1 = (f32x4){0.f, 0.f, 0.f, 0.f};
; #pragma unroll
;                 for (int ks = 0; ks < 4; ++ks) {
;                     const bf16x8 s0 = *(const LAS bf16x8*)(st + l15 * 272 + 64 * ks + 16 * qq), s1 = *(const LAS bf16x8*)(st + (16 + l15) * 272 + 64 * ks + 16 * qq);
;                     acc0 = __builtin_amdgcn_mfma_f32_16x16x32_bf16(s0, cfrag[ks], acc0, 0, 0, 0); acc1 = __builtin_amdgcn_mfma_f32_16x16x32_bf16(s1, cfrag[ks], acc1, 0, 0, 0); }
;                 float uu[2][4];
; #pragma unroll
;                 for (int rb = 0; rb < 2; ++rb)
; #pragma unroll
;                     for (int i2 = 0; i2 < 4; ++i2) uu[rb][i2] = bf1(*(const LAS bf16*)(ut + (i2 + 4 * rb + 8 * qq) * 32 + 2 * l15));
; #pragma unroll
;                 for (int rb = 0; rb < 2; ++rb)
; #pragma unroll
;                     for (int i2 = 0; i2 < 4; i2 += 2) {
	v_lshlrev_b32_e32 v1, 16, v1
	v_fma_f32 v0, v176, v0, v2
	v_fma_f32 v1, v177, v1, v3
	v_pk_mul_f32 v[2:3], v[0:1], v[0:1]
	s_nop 4
	v_pk_fma_f32 v[16:17], v[180:181], v[118:119], v[16:17]
	v_pk_fma_f32 v[2:3], v[2:3], s[20:21], v[128:129] op_sel_hi:[1,0,0] neg_lo:[1,0,0] neg_hi:[1,0,0]
	v_pk_fma_f32 v[16:17], v[170:171], v[116:117], v[16:17]
	v_pk_mul_f32 v[2:3], v[0:1], v[2:3]
	s_nop 0
	v_exp_f32_e32 v2, v2
	v_exp_f32_e32 v3, v3
	s_nop 0
	v_pk_add_f32 v[2:3], v[2:3], 1.0 op_sel_hi:[1,0]
	s_nop 0
	v_rcp_f32_e32 v2, v2
	v_rcp_f32_e32 v3, v3
	s_nop 0
	v_pk_mul_f32 v[0:1], v[0:1], v[2:3]
	s_nop 0
	v_cvt_pk_bf16_f32 v0, v0, v1
	ds_write_b16 v215, v0 offset:64
	ds_write_b16_d16_hi v215, v0 offset:96
	v_lshlrev_b32_e32 v1, 16, v9
	v_lshlrev_b32_e32 v0, 16, v8
	v_pk_fma_f32 v[0:1], v[176:177], v[0:1], v[4:5]
	v_add_u32_e32 v4, v141, v148
	v_pk_mul_f32 v[2:3], v[0:1], v[0:1]
	v_ashrrev_i32_e32 v5, 31, v4
	v_pk_fma_f32 v[2:3], v[2:3], s[20:21], v[128:129] op_sel_hi:[1,0,0] neg_lo:[1,0,0] neg_hi:[1,0,0]
	v_lshlrev_b64 v[4:5], 11, v[4:5]
	v_pk_mul_f32 v[2:3], v[0:1], v[2:3]
	v_lshl_add_u64 v[4:5], v[126:127], 0, v[4:5]
	v_exp_f32_e32 v2, v2
	v_exp_f32_e32 v3, v3
	s_nop 0
	v_pk_add_f32 v[2:3], v[2:3], 1.0 op_sel_hi:[1,0]
	s_nop 0
	v_rcp_f32_e32 v2, v2
	v_rcp_f32_e32 v3, v3
	s_nop 0
	v_pk_mul_f32 v[0:1], v[0:1], v[2:3]
	s_nop 0
	v_cvt_pk_bf16_f32 v0, v0, v1
	ds_write_b16 v215, v0 offset:512
	ds_write_b16_d16_hi v215, v0 offset:544
	s_waitcnt lgkmcnt(4)
	v_lshlrev_b32_e32 v1, 16, v11
	v_lshlrev_b32_e32 v0, 16, v10
	v_pk_fma_f32 v[0:1], v[176:177], v[0:1], v[6:7]
	s_nop 0
	v_pk_mul_f32 v[2:3], v[0:1], v[0:1]
	s_nop 0
	v_pk_fma_f32 v[2:3], v[2:3], s[20:21], v[128:129] op_sel_hi:[1,0,0] neg_lo:[1,0,0] neg_hi:[1,0,0]
	s_nop 0
	v_pk_mul_f32 v[2:3], v[0:1], v[2:3]
	s_nop 0
	v_exp_f32_e32 v2, v2
	v_exp_f32_e32 v3, v3
	s_nop 0
	v_pk_add_f32 v[2:3], v[2:3], 1.0 op_sel_hi:[1,0]
	s_nop 0
	v_rcp_f32_e32 v2, v2
	v_rcp_f32_e32 v3, v3
	s_nop 0
	v_pk_mul_f32 v[0:1], v[0:1], v[2:3]
	s_nop 0
	v_cvt_pk_bf16_f32 v0, v0, v1
	ds_write_b16 v215, v0 offset:576
	ds_write_b16_d16_hi v215, v0 offset:608
	s_waitcnt lgkmcnt(0)
	ds_read_b128 v[0:3], v147
	s_waitcnt lgkmcnt(0)
	global_store_dwordx4 v[4:5], v[0:3], off
	s_nop 1
	v_mfma_f32_32x32x16_bf16 v[0:15], v[108:111], v[76:79], 0
	s_waitcnt lgkmcnt(0)
	ds_write_b128 v212, v[108:111]
	v_cvt_pk_bf16_f32 v108, v48, v16
	v_cvt_pk_bf16_f32 v110, v49, v17
	s_nop 8
	v_pk_fma_f32 v[0:1], v[174:175], v[116:117], v[0:1]
	s_nop 0
	v_pk_fma_f32 v[0:1], v[170:171], v[118:119], v[0:1]
	v_pk_fma_f32 v[2:3], v[174:175], v[16:17], v[2:3]
	v_pk_fma_f32 v[18:19], v[180:181], v[0:1], v[18:19]
	v_cvt_pk_bf16_f32 v109, v32, v0
	v_cvt_pk_bf16_f32 v111, v33, v1
	v_pk_fma_f32 v[32:33], v[168:169], v[32:33], v[34:35]
	v_pk_fma_f32 v[18:19], v[170:171], v[16:17], v[18:19]
	v_pk_fma_f32 v[0:1], v[170:171], v[0:1], v[2:3]
	v_cvt_pk_bf16_f32 v2, v50, v18
	v_cvt_pk_bf16_f32 v3, v32, v0
	v_cvt_pk_bf16_f32 v16, v51, v19
	v_cvt_pk_bf16_f32 v17, v33, v1
	ds_write2_b64 v149, v[2:3], v[16:17] offset0:68 offset1:102
	v_pk_fma_f32 v[2:3], v[178:179], v[32:33], v[52:53]
	v_pk_fma_f32 v[16:17], v[172:173], v[50:51], v[36:37]
	v_pk_fma_f32 v[20:21], v[180:181], v[0:1], v[20:21]
	v_pk_fma_f32 v[4:5], v[174:175], v[18:19], v[4:5]
	v_pk_fma_f32 v[2:3], v[168:169], v[50:51], v[2:3]
	v_pk_fma_f32 v[16:17], v[168:169], v[32:33], v[16:17]
	v_pk_fma_f32 v[20:21], v[170:171], v[18:19], v[20:21]
	v_pk_fma_f32 v[0:1], v[170:171], v[0:1], v[4:5]
	v_cvt_pk_bf16_f32 v4, v2, v20
	v_cvt_pk_bf16_f32 v5, v16, v0
	v_cvt_pk_bf16_f32 v18, v3, v21
	v_cvt_pk_bf16_f32 v19, v17, v1
	ds_write2_b64 v149, v[4:5], v[18:19] offset0:136 offset1:170
	v_pk_fma_f32 v[4:5], v[178:179], v[16:17], v[54:55]
	v_pk_fma_f32 v[6:7], v[174:175], v[20:21], v[6:7]
	v_pk_fma_f32 v[4:5], v[168:169], v[2:3], v[4:5]
	v_pk_fma_f32 v[2:3], v[172:173], v[2:3], v[38:39]
	ds_write2_b64 v149, v[108:109], v[110:111] offset1:34
	v_pk_fma_f32 v[2:3], v[168:169], v[16:17], v[2:3]
	v_pk_fma_f32 v[16:17], v[180:181], v[0:1], v[22:23]
	v_pk_fma_f32 v[0:1], v[170:171], v[0:1], v[6:7]
	v_pk_fma_f32 v[16:17], v[170:171], v[20:21], v[16:17]
	v_cvt_pk_bf16_f32 v7, v2, v0
	v_cvt_pk_bf16_f32 v6, v4, v16
	v_cvt_pk_bf16_f32 v18, v5, v17
	v_cvt_pk_bf16_f32 v19, v3, v1
	ds_write2_b64 v149, v[6:7], v[18:19] offset0:204 offset1:238
	v_pk_fma_f32 v[6:7], v[178:179], v[2:3], v[56:57]
	v_pk_fma_f32 v[8:9], v[174:175], v[16:17], v[8:9]
	v_pk_fma_f32 v[6:7], v[168:169], v[4:5], v[6:7]
	v_pk_fma_f32 v[4:5], v[172:173], v[4:5], v[40:41]
	s_nop 0
	v_pk_fma_f32 v[2:3], v[168:169], v[2:3], v[4:5]
	v_pk_fma_f32 v[4:5], v[180:181], v[0:1], v[24:25]
	v_pk_fma_f32 v[0:1], v[170:171], v[0:1], v[8:9]
	v_pk_fma_f32 v[4:5], v[170:171], v[16:17], v[4:5]
	v_cvt_pk_bf16_f32 v9, v2, v0
	v_cvt_pk_bf16_f32 v8, v6, v4
	v_cvt_pk_bf16_f32 v16, v7, v5
	v_cvt_pk_bf16_f32 v17, v3, v1
	ds_write2_b64 v146, v[8:9], v[16:17] offset0:16 offset1:50
	v_pk_fma_f32 v[8:9], v[178:179], v[2:3], v[58:59]
	s_nop 0
	v_pk_fma_f32 v[8:9], v[168:169], v[6:7], v[8:9]
	v_pk_fma_f32 v[6:7], v[172:173], v[6:7], v[42:43]
	s_nop 0
	v_pk_fma_f32 v[2:3], v[168:169], v[2:3], v[6:7]
	v_pk_fma_f32 v[6:7], v[180:181], v[0:1], v[26:27]
	s_nop 0
	v_pk_fma_f32 v[6:7], v[170:171], v[4:5], v[6:7]
	v_pk_fma_f32 v[4:5], v[174:175], v[4:5], v[10:11]
	v_cvt_pk_bf16_f32 v10, v9, v7
	v_pk_fma_f32 v[0:1], v[170:171], v[0:1], v[4:5]
	v_cvt_pk_bf16_f32 v4, v8, v6
	v_cvt_pk_bf16_f32 v5, v2, v0
	v_cvt_pk_bf16_f32 v11, v3, v1
	ds_write2_b64 v146, v[4:5], v[10:11] offset0:84 offset1:118
	v_pk_fma_f32 v[4:5], v[178:179], v[2:3], v[60:61]
	s_nop 0
	v_pk_fma_f32 v[4:5], v[168:169], v[8:9], v[4:5]
	v_pk_fma_f32 v[8:9], v[172:173], v[8:9], v[44:45]
	s_nop 0
	v_pk_fma_f32 v[2:3], v[168:169], v[2:3], v[8:9]
	v_pk_fma_f32 v[8:9], v[180:181], v[0:1], v[28:29]
	s_nop 0
	v_pk_fma_f32 v[8:9], v[170:171], v[6:7], v[8:9]
	v_pk_fma_f32 v[6:7], v[174:175], v[6:7], v[12:13]
	v_cvt_pk_bf16_f32 v10, v5, v9
	v_pk_fma_f32 v[0:1], v[170:171], v[0:1], v[6:7]
	v_cvt_pk_bf16_f32 v6, v4, v8
	v_cvt_pk_bf16_f32 v7, v2, v0
	v_cvt_pk_bf16_f32 v11, v3, v1
	ds_write2_b64 v146, v[6:7], v[10:11] offset0:152 offset1:186
	v_pk_fma_f32 v[6:7], v[178:179], v[2:3], v[62:63]
	v_mfma_f32_32x32x16_bf16 v[48:63], v[104:107], v[64:67], 0
	v_fma_f32 v108, v168, v4, v6
	v_fma_f32 v109, v169, v5, v7
	v_fma_f32 v4, v172, v4, v46
	v_fma_f32 v5, v173, v5, v47
	v_fma_f32 v110, v168, v2, v4
	v_fma_f32 v111, v169, v3, v5
	v_pk_fma_f32 v[2:3], v[180:181], v[0:1], v[30:31]
	s_nop 4
	v_pk_fma_f32 v[48:49], v[178:179], v[110:111], v[48:49]
	v_pk_fma_f32 v[112:113], v[170:171], v[8:9], v[2:3]
	v_pk_fma_f32 v[2:3], v[174:175], v[8:9], v[14:15]
	v_mfma_f32_32x32x16_bf16 v[32:47], v[104:107], v[72:75], 0
	v_fma_f32 v114, v170, v0, v2
	v_fma_f32 v115, v171, v1, v3
	v_cvt_pk_bf16_f32 v0, v108, v112
	v_cvt_pk_bf16_f32 v1, v110, v114
	v_cvt_pk_bf16_f32 v2, v109, v113
	v_cvt_pk_bf16_f32 v3, v111, v115
	ds_write2_b64 v146, v[0:1], v[2:3] offset0:220 offset1:254
	s_waitcnt lgkmcnt(0)
; #define LAS __attribute__((address_space(3)))
; #define LDS_WAIT() asm volatile("s_waitcnt lgkmcnt(0)" ::: "memory")
; __device__ __forceinline__ void ssm_phase(Frame& F) {
;     ...
; #pragma unroll
;             for (int s = 0; s < 8; ++s) {
;                 *(LAS bf16x8*)(ut + l31 * 32 + 16 * h) = afr[s];
;                 const f32x16 D0 = __builtin_amdgcn_mfma_f32_32x32x16_bf16(afr[s], bfrag[0], z, 0, 0, 0), D1 = __builtin_amdgcn_mfma_f32_32x32x16_bf16(afr[s], bfrag[1], z, 0, 0, 0),
;                              D2 = __builtin_amdgcn_mfma_f32_32x32x16_bf16(afr[s], bfrag[2], z, 0, 0, 0), D3 = __builtin_amdgcn_mfma_f32_32x32x16_bf16(afr[s], bfrag[3], z, 0, 0, 0);
; #pragma unroll
;                 for (int t = 0; t < 8; ++t) {
;                     const f2v d0 = {D0[2 * t], D0[2 * t + 1]}, d1 = {D1[2 * t], D1[2 * t + 1]}, d2 = {D2[2 * t], D2[2 * t + 1]}, d3 = {D3[2 * t], D3[2 * t + 1]};
;                     const f2v nr0 = fma2(AR0, Sre0, fma2(NAI0, Sim0, d0)), ni0 = fma2(AR0, Sim0, fma2(AI0, Sre0, d2));
;                     const f2v nr1 = fma2(AR1, Sre1, fma2(NAI1, Sim1, d1)), ni1 = fma2(AR1, Sim1, fma2(AI1, Sre1, d3));
;                     Sre0 = nr0; Sim0 = ni0; Sre1 = nr1; Sim1 = ni1;
; #pragma unroll
;                     for (int e = 0; e < 2; ++e) { v2u w; w.x = cvt2(nr0[e], nr1[e]); w.y = cvt2(ni0[e], ni1[e]); *(LAS v2u*)(st + (16 * h + 2 * t + e) * 272 + 8 * l31) = w; }
;                 }
;                 LDS_WAIT(); asm volatile("" ::: "memory");
;                 f32x4 acc0 = (f32x4){0.f, 0.f, 0.f, 0.f}, acc1 = (f32x4){0.f, 0.f, 0.f, 0.f};
; #pragma unroll
;                 for (int ks = 0; ks < 4; ++ks) {
;                     const bf16x8 s0 = *(const LAS bf16x8*)(st + l15 * 272 + 64 * ks + 16 * qq), s1 = *(const LAS bf16x8*)(st + (16 + l15) * 272 + 64 * ks + 16 * qq);
;                     acc0 = __builtin_amdgcn_mfma_f32_16x16x32_bf16(s0, cfrag[ks], acc0, 0, 0, 0); acc1 = __builtin_amdgcn_mfma_f32_16x16x32_bf16(s1, cfrag[ks], acc1, 0, 0, 0); }
;                 float uu[2][4];
; #pragma unroll
;                 for (int rb = 0; rb < 2; ++rb)
; #pragma unroll
;                     for (int i2 = 0; i2 < 4; ++i2) uu[rb][i2] = bf1(*(const LAS bf16*)(ut + (i2 + 4 * rb + 8 * qq) * 32 + 2 * l15));
; #pragma unroll
;                 for (int rb = 0; rb < 2; ++rb)
; #pragma unroll
;                     for (int i2 = 0; i2 < 4; i2 += 2) {
	ds_read_b128 v[0:3], v213 offset:32768
	ds_read_b128 v[4:7], v213 offset:37120
	s_waitcnt lgkmcnt(1)
	v_mfma_f32_16x16x32_bf16 v[0:3], v[0:3], v[80:83], 0
	ds_read_b128 v[8:11], v213 offset:32832
	ds_read_b128 v[12:15], v213 offset:37184
	v_pk_fma_f32 v[32:33], v[172:173], v[108:109], v[32:33]
	v_pk_fma_f32 v[48:49], v[168:169], v[108:109], v[48:49]
	s_waitcnt lgkmcnt(1)
	v_mfma_f32_16x16x32_bf16 v[0:3], v[8:11], v[84:87], v[0:3]
	ds_read_b128 v[8:11], v213 offset:32896
	ds_read_b128 v[16:19], v213 offset:37248
	v_pk_fma_f32 v[32:33], v[168:169], v[110:111], v[32:33]
	v_pk_fma_f32 v[34:35], v[172:173], v[48:49], v[34:35]
	s_waitcnt lgkmcnt(1)
	v_mfma_f32_16x16x32_bf16 v[0:3], v[8:11], v[88:91], v[0:3]
	ds_read_b128 v[8:11], v213 offset:32960
	ds_read_b128 v[20:23], v213 offset:37312
	v_pk_fma_f32 v[50:51], v[178:179], v[32:33], v[50:51]
	s_waitcnt lgkmcnt(1)
	v_mfma_f32_16x16x32_bf16 v[0:3], v[8:11], v[92:95], v[0:3]
	ds_read_u16 v8, v214
	ds_read_u16 v9, v214 offset:32
	v_pk_fma_f32 v[50:51], v[168:169], v[48:49], v[50:51]
	s_waitcnt lgkmcnt(1)
	v_lshlrev_b32_e32 v8, 16, v8
	s_waitcnt lgkmcnt(0)
	v_lshlrev_b32_e32 v9, 16, v9
	s_nop 0
	v_pk_fma_f32 v[0:1], v[176:177], v[8:9], v[0:1]
	v_mfma_f32_16x16x32_bf16 v[4:7], v[4:7], v[80:83], 0
	v_mul_f32_e64 v8, v0, v0
	v_mul_f32_e64 v9, v1, v1
	v_pk_fma_f32 v[8:9], v[8:9], s[20:21], v[128:129] op_sel_hi:[1,0,0] neg_lo:[1,0,0] neg_hi:[1,0,0]
	v_mfma_f32_16x16x32_bf16 v[4:7], v[12:15], v[84:87], v[4:7]
	v_mul_f32_e64 v8, v0, v8
	v_mul_f32_e64 v9, v1, v9
	v_exp_f32_e32 v8, v8
	v_exp_f32_e32 v9, v9
	v_mfma_f32_16x16x32_bf16 v[4:7], v[16:19], v[88:91], v[4:7]
	v_add_f32_e64 v8, v8, 1.0
	v_add_f32_e64 v9, v9, 1.0
	v_rcp_f32_e32 v8, v8
	v_rcp_f32_e32 v9, v9
	v_mfma_f32_16x16x32_bf16 v[4:7], v[20:23], v[92:95], v[4:7]
	v_mul_f32_e64 v0, v0, v8
	v_mul_f32_e64 v1, v1, v9
	v_cvt_pk_bf16_f32 v0, v0, v1
	ds_read_u16 v8, v214 offset:128
	ds_read_u16 v9, v214 offset:160
	ds_write_b16 v215, v0
	ds_write_b16_d16_hi v215, v0 offset:32
	ds_read_u16 v0, v214 offset:64
	ds_read_u16 v1, v214 offset:96
	ds_read_u16 v10, v214 offset:192
	ds_read_u16 v11, v214 offset:224
	v_mfma_f32_32x32x16_bf16 v[16:31], v[104:107], v[76:79], 0
	s_waitcnt lgkmcnt(3)
	v_lshlrev_b32_e32 v0, 16, v0
	s_waitcnt lgkmcnt(2)
	v_lshlrev_b32_e32 v1, 16, v1
	v_fma_f32 v0, v176, v0, v2
	v_fma_f32 v1, v177, v1, v3
	v_pk_mul_f32 v[2:3], v[0:1], v[0:1]
	s_nop 4
	v_pk_fma_f32 v[16:17], v[174:175], v[112:113], v[16:17]
	v_pk_fma_f32 v[2:3], v[2:3], s[20:21], v[128:129] op_sel_hi:[1,0,0] neg_lo:[1,0,0] neg_hi:[1,0,0]
	v_pk_fma_f32 v[16:17], v[170:171], v[114:115], v[16:17]
	v_pk_mul_f32 v[2:3], v[0:1], v[2:3]
	s_nop 0
	v_exp_f32_e32 v2, v2
	v_exp_f32_e32 v3, v3
	s_nop 0
	v_pk_add_f32 v[2:3], v[2:3], 1.0 op_sel_hi:[1,0]
	s_nop 0
	v_rcp_f32_e32 v2, v2
	v_rcp_f32_e32 v3, v3
	s_nop 0
	v_pk_mul_f32 v[0:1], v[0:1], v[2:3]
	s_nop 0
	v_cvt_pk_bf16_f32 v0, v0, v1
	ds_write_b16 v215, v0 offset:64
	ds_write_b16_d16_hi v215, v0 offset:96
	v_lshlrev_b32_e32 v1, 16, v9
	v_lshlrev_b32_e32 v0, 16, v8
	v_pk_fma_f32 v[0:1], v[176:177], v[0:1], v[4:5]
	v_add_u32_e32 v4, v142, v148
	v_pk_mul_f32 v[2:3], v[0:1], v[0:1]
	v_ashrrev_i32_e32 v5, 31, v4
	v_pk_fma_f32 v[2:3], v[2:3], s[20:21], v[128:129] op_sel_hi:[1,0,0] neg_lo:[1,0,0] neg_hi:[1,0,0]
	v_lshlrev_b64 v[4:5], 11, v[4:5]
	v_pk_mul_f32 v[2:3], v[0:1], v[2:3]
	v_lshl_add_u64 v[4:5], v[126:127], 0, v[4:5]
	v_exp_f32_e32 v2, v2
	v_exp_f32_e32 v3, v3
	s_nop 0
	v_pk_add_f32 v[2:3], v[2:3], 1.0 op_sel_hi:[1,0]
	s_nop 0
	v_rcp_f32_e32 v2, v2
	v_rcp_f32_e32 v3, v3
	s_nop 0
	v_pk_mul_f32 v[0:1], v[0:1], v[2:3]
	s_nop 0
	v_cvt_pk_bf16_f32 v0, v0, v1
	ds_write_b16 v215, v0 offset:512
	ds_write_b16_d16_hi v215, v0 offset:544
	s_waitcnt lgkmcnt(4)
	v_lshlrev_b32_e32 v1, 16, v11
	v_lshlrev_b32_e32 v0, 16, v10
	v_pk_fma_f32 v[0:1], v[176:177], v[0:1], v[6:7]
	s_nop 0
	v_pk_mul_f32 v[2:3], v[0:1], v[0:1]
	s_nop 0
	v_pk_fma_f32 v[2:3], v[2:3], s[20:21], v[128:129] op_sel_hi:[1,0,0] neg_lo:[1,0,0] neg_hi:[1,0,0]
	s_nop 0
	v_pk_mul_f32 v[2:3], v[0:1], v[2:3]
	s_nop 0
	v_exp_f32_e32 v2, v2
	v_exp_f32_e32 v3, v3
	s_nop 0
	v_pk_add_f32 v[2:3], v[2:3], 1.0 op_sel_hi:[1,0]
	s_nop 0
	v_rcp_f32_e32 v2, v2
	v_rcp_f32_e32 v3, v3
	s_nop 0
	v_pk_mul_f32 v[0:1], v[0:1], v[2:3]
	s_nop 0
	v_cvt_pk_bf16_f32 v0, v0, v1
	ds_write_b16 v215, v0 offset:576
	ds_write_b16_d16_hi v215, v0 offset:608
	s_waitcnt lgkmcnt(0)
	ds_read_b128 v[0:3], v147
	s_waitcnt lgkmcnt(0)
	global_store_dwordx4 v[4:5], v[0:3], off
	s_nop 1
	v_mfma_f32_32x32x16_bf16 v[0:15], v[104:107], v[68:71], 0
	s_waitcnt lgkmcnt(0)
; #define LAS __attribute__((address_space(3)))
; #define LDS_WAIT() asm volatile("s_waitcnt lgkmcnt(0)" ::: "memory")
; __device__ __forceinline__ void ssm_phase(Frame& F) {
;     ...
; #pragma unroll
;             for (int s = 0; s < 8; ++s) {
;                 *(LAS bf16x8*)(ut + l31 * 32 + 16 * h) = afr[s];
;                 const f32x16 D0 = __builtin_amdgcn_mfma_f32_32x32x16_bf16(afr[s], bfrag[0], z, 0, 0, 0), D1 = __builtin_amdgcn_mfma_f32_32x32x16_bf16(afr[s], bfrag[1], z, 0, 0, 0),
;                              D2 = __builtin_amdgcn_mfma_f32_32x32x16_bf16(afr[s], bfrag[2], z, 0, 0, 0), D3 = __builtin_amdgcn_mfma_f32_32x32x16_bf16(afr[s], bfrag[3], z, 0, 0, 0);
; #pragma unroll
;                 for (int t = 0; t < 8; ++t) {
;                     const f2v d0 = {D0[2 * t], D0[2 * t + 1]}, d1 = {D1[2 * t], D1[2 * t + 1]}, d2 = {D2[2 * t], D2[2 * t + 1]}, d3 = {D3[2 * t], D3[2 * t + 1]};
;                     const f2v nr0 = fma2(AR0, Sre0, fma2(NAI0, Sim0, d0)), ni0 = fma2(AR0, Sim0, fma2(AI0, Sre0, d2));
;                     const f2v nr1 = fma2(AR1, Sre1, fma2(NAI1, Sim1, d1)), ni1 = fma2(AR1, Sim1, fma2(AI1, Sre1, d3));
;                     Sre0 = nr0; Sim0 = ni0; Sre1 = nr1; Sim1 = ni1;
; #pragma unroll
;                     for (int e = 0; e < 2; ++e) { v2u w; w.x = cvt2(nr0[e], nr1[e]); w.y = cvt2(ni0[e], ni1[e]); *(LAS v2u*)(st + (16 * h + 2 * t + e) * 272 + 8 * l31) = w; }
;                 }
;                 LDS_WAIT(); asm volatile("" ::: "memory");
;                 f32x4 acc0 = (f32x4){0.f, 0.f, 0.f, 0.f}, acc1 = (f32x4){0.f, 0.f, 0.f, 0.f};
; #pragma unroll
;                 for (int ks = 0; ks < 4; ++ks) {
;                     const bf16x8 s0 = *(const LAS bf16x8*)(st + l15 * 272 + 64 * ks + 16 * qq), s1 = *(const LAS bf16x8*)(st + (16 + l15) * 272 + 64 * ks + 16 * qq);
;                     acc0 = __builtin_amdgcn_mfma_f32_16x16x32_bf16(s0, cfrag[ks], acc0, 0, 0, 0); acc1 = __builtin_amdgcn_mfma_f32_16x16x32_bf16(s1, cfrag[ks], acc1, 0, 0, 0); }
;                 float uu[2][4];
; #pragma unroll
;                 for (int rb = 0; rb < 2; ++rb)
; #pragma unroll
;                     for (int i2 = 0; i2 < 4; ++i2) uu[rb][i2] = bf1(*(const LAS bf16*)(ut + (i2 + 4 * rb + 8 * qq) * 32 + 2 * l15));
; #pragma unroll
;                 for (int rb = 0; rb < 2; ++rb)
; #pragma unroll
;                     for (int i2 = 0; i2 < 4; i2 += 2) {
	ds_write_b128 v212, v[104:107]
	v_cvt_pk_bf16_f32 v105, v32, v16
	v_cvt_pk_bf16_f32 v107, v33, v17
	v_fma_f32 v32, v168, v32, v34
	v_fma_f32 v33, v169, v33, v35
	s_nop 6
	v_pk_fma_f32 v[0:1], v[180:181], v[114:115], v[0:1]
	s_nop 0
	v_pk_fma_f32 v[0:1], v[170:171], v[112:113], v[0:1]
	v_pk_fma_f32 v[2:3], v[180:181], v[16:17], v[2:3]
	v_cvt_pk_bf16_f32 v104, v48, v0
	v_cvt_pk_bf16_f32 v106, v49, v1
	v_pk_fma_f32 v[2:3], v[170:171], v[0:1], v[2:3]
	v_pk_fma_f32 v[0:1], v[174:175], v[0:1], v[18:19]
	v_cvt_pk_bf16_f32 v18, v51, v3
	v_pk_fma_f32 v[0:1], v[170:171], v[16:17], v[0:1]
	v_cvt_pk_bf16_f32 v16, v50, v2
	v_cvt_pk_bf16_f32 v17, v32, v0
	v_cvt_pk_bf16_f32 v19, v33, v1
	v_pk_fma_f32 v[4:5], v[180:181], v[0:1], v[4:5]
	ds_write2_b64 v149, v[16:17], v[18:19] offset0:68 offset1:102
	v_pk_fma_f32 v[16:17], v[178:179], v[32:33], v[52:53]
	v_pk_fma_f32 v[18:19], v[172:173], v[50:51], v[36:37]
	v_pk_fma_f32 v[4:5], v[170:171], v[2:3], v[4:5]
	v_pk_fma_f32 v[2:3], v[174:175], v[2:3], v[20:21]
	v_pk_fma_f32 v[16:17], v[168:169], v[50:51], v[16:17]
	v_pk_fma_f32 v[18:19], v[168:169], v[32:33], v[18:19]
	v_pk_fma_f32 v[0:1], v[170:171], v[0:1], v[2:3]
	v_cvt_pk_bf16_f32 v2, v16, v4
	v_cvt_pk_bf16_f32 v3, v18, v0
	v_cvt_pk_bf16_f32 v20, v17, v5
	v_cvt_pk_bf16_f32 v21, v19, v1
	ds_write2_b64 v149, v[2:3], v[20:21] offset0:136 offset1:170
	v_pk_fma_f32 v[2:3], v[178:179], v[18:19], v[54:55]
	v_pk_fma_f32 v[6:7], v[180:181], v[0:1], v[6:7]
	v_pk_fma_f32 v[2:3], v[168:169], v[16:17], v[2:3]
	v_pk_fma_f32 v[16:17], v[172:173], v[16:17], v[38:39]
	v_pk_fma_f32 v[6:7], v[170:171], v[4:5], v[6:7]
	v_pk_fma_f32 v[4:5], v[174:175], v[4:5], v[22:23]
	v_pk_fma_f32 v[16:17], v[168:169], v[18:19], v[16:17]
	v_pk_fma_f32 v[0:1], v[170:171], v[0:1], v[4:5]
	v_cvt_pk_bf16_f32 v4, v2, v6
	v_cvt_pk_bf16_f32 v5, v16, v0
	v_cvt_pk_bf16_f32 v18, v3, v7
	v_cvt_pk_bf16_f32 v19, v17, v1
	ds_write2_b64 v149, v[4:5], v[18:19] offset0:204 offset1:238
	v_pk_fma_f32 v[4:5], v[178:179], v[16:17], v[56:57]
	v_pk_fma_f32 v[8:9], v[180:181], v[0:1], v[8:9]
	v_pk_fma_f32 v[4:5], v[168:169], v[2:3], v[4:5]
	v_pk_fma_f32 v[2:3], v[172:173], v[2:3], v[40:41]
	v_pk_fma_f32 v[8:9], v[170:171], v[6:7], v[8:9]
	v_pk_fma_f32 v[6:7], v[174:175], v[6:7], v[24:25]
	v_pk_fma_f32 v[2:3], v[168:169], v[16:17], v[2:3]
	v_pk_fma_f32 v[0:1], v[170:171], v[0:1], v[6:7]
	v_cvt_pk_bf16_f32 v6, v4, v8
	v_cvt_pk_bf16_f32 v7, v2, v0
	v_cvt_pk_bf16_f32 v16, v5, v9
	v_cvt_pk_bf16_f32 v17, v3, v1
	ds_write2_b64 v146, v[6:7], v[16:17] offset0:16 offset1:50
	v_pk_fma_f32 v[6:7], v[178:179], v[2:3], v[58:59]
	ds_write2_b64 v149, v[104:105], v[106:107] offset1:34
	v_pk_fma_f32 v[6:7], v[168:169], v[4:5], v[6:7]
	v_pk_fma_f32 v[4:5], v[172:173], v[4:5], v[42:43]
	s_nop 0
	v_pk_fma_f32 v[2:3], v[168:169], v[2:3], v[4:5]
	v_pk_fma_f32 v[4:5], v[180:181], v[0:1], v[10:11]
	s_nop 0
	v_pk_fma_f32 v[4:5], v[170:171], v[8:9], v[4:5]
	v_pk_fma_f32 v[8:9], v[174:175], v[8:9], v[26:27]
	v_cvt_pk_bf16_f32 v10, v7, v5
	v_pk_fma_f32 v[0:1], v[170:171], v[0:1], v[8:9]
	v_cvt_pk_bf16_f32 v8, v6, v4
	v_cvt_pk_bf16_f32 v9, v2, v0
	v_cvt_pk_bf16_f32 v11, v3, v1
	ds_write2_b64 v146, v[8:9], v[10:11] offset0:84 offset1:118
	v_pk_fma_f32 v[8:9], v[178:179], v[2:3], v[60:61]
	s_nop 0
	v_pk_fma_f32 v[8:9], v[168:169], v[6:7], v[8:9]
	v_pk_fma_f32 v[6:7], v[172:173], v[6:7], v[44:45]
	s_nop 0
	v_pk_fma_f32 v[2:3], v[168:169], v[2:3], v[6:7]
	v_pk_fma_f32 v[6:7], v[180:181], v[0:1], v[12:13]
	s_nop 0
	v_pk_fma_f32 v[6:7], v[170:171], v[4:5], v[6:7]
	v_pk_fma_f32 v[4:5], v[174:175], v[4:5], v[28:29]
	v_cvt_pk_bf16_f32 v10, v9, v7
	v_pk_fma_f32 v[0:1], v[170:171], v[0:1], v[4:5]
	v_cvt_pk_bf16_f32 v4, v8, v6
	v_cvt_pk_bf16_f32 v5, v2, v0
	v_cvt_pk_bf16_f32 v11, v3, v1
	ds_write2_b64 v146, v[4:5], v[10:11] offset0:152 offset1:186
	v_pk_fma_f32 v[4:5], v[178:179], v[2:3], v[62:63]
	v_mfma_f32_32x32x16_bf16 v[48:63], v[100:103], v[64:67], 0
	v_fma_f32 v104, v168, v8, v4
	v_fma_f32 v105, v169, v9, v5
	v_fma_f32 v4, v172, v8, v46
	v_fma_f32 v5, v173, v9, v47
	v_fma_f32 v108, v168, v2, v4
	v_fma_f32 v109, v169, v3, v5
	v_pk_fma_f32 v[2:3], v[180:181], v[0:1], v[14:15]
	s_nop 4
	v_pk_fma_f32 v[48:49], v[178:179], v[108:109], v[48:49]
	v_pk_fma_f32 v[106:107], v[170:171], v[6:7], v[2:3]
	v_pk_fma_f32 v[2:3], v[174:175], v[6:7], v[30:31]
	v_mfma_f32_32x32x16_bf16 v[32:47], v[100:103], v[72:75], 0
	v_fma_f32 v110, v170, v0, v2
	v_fma_f32 v111, v171, v1, v3
	v_cvt_pk_bf16_f32 v0, v104, v106
	v_cvt_pk_bf16_f32 v1, v108, v110
	v_cvt_pk_bf16_f32 v2, v105, v107
	v_cvt_pk_bf16_f32 v3, v109, v111
	ds_write2_b64 v146, v[0:1], v[2:3] offset0:220 offset1:254
	s_waitcnt lgkmcnt(0)
	ds_read_b128 v[0:3], v213 offset:32768
	ds_read_b128 v[4:7], v213 offset:37120
	s_waitcnt lgkmcnt(1)
	v_mfma_f32_16x16x32_bf16 v[0:3], v[0:3], v[80:83], 0
	ds_read_b128 v[8:11], v213 offset:32832
	ds_read_b128 v[12:15], v213 offset:37184
	v_pk_fma_f32 v[32:33], v[172:173], v[104:105], v[32:33]
	v_pk_fma_f32 v[48:49], v[168:169], v[104:105], v[48:49]
	s_waitcnt lgkmcnt(1)
	v_mfma_f32_16x16x32_bf16 v[0:3], v[8:11], v[84:87], v[0:3]
	ds_read_b128 v[8:11], v213 offset:32896
	ds_read_b128 v[16:19], v213 offset:37248
	v_pk_fma_f32 v[32:33], v[168:169], v[108:109], v[32:33]
	v_pk_fma_f32 v[34:35], v[172:173], v[48:49], v[34:35]
	s_waitcnt lgkmcnt(1)
	v_mfma_f32_16x16x32_bf16 v[0:3], v[8:11], v[88:91], v[0:3]
	ds_read_b128 v[8:11], v213 offset:32960
	ds_read_b128 v[20:23], v213 offset:37312
	v_pk_fma_f32 v[50:51], v[178:179], v[32:33], v[50:51]
	s_waitcnt lgkmcnt(1)
	v_mfma_f32_16x16x32_bf16 v[0:3], v[8:11], v[92:95], v[0:3]
	ds_read_u16 v8, v214
	ds_read_u16 v9, v214 offset:32
	v_pk_fma_f32 v[50:51], v[168:169], v[48:49], v[50:51]
	s_waitcnt lgkmcnt(1)
; #define LAS __attribute__((address_space(3)))
; #define LDS_WAIT() asm volatile("s_waitcnt lgkmcnt(0)" ::: "memory")
; __device__ __forceinline__ void ssm_phase(Frame& F) {
;     ...
; #pragma unroll
;             for (int s = 0; s < 8; ++s) {
;                 *(LAS bf16x8*)(ut + l31 * 32 + 16 * h) = afr[s];
;                 const f32x16 D0 = __builtin_amdgcn_mfma_f32_32x32x16_bf16(afr[s], bfrag[0], z, 0, 0, 0), D1 = __builtin_amdgcn_mfma_f32_32x32x16_bf16(afr[s], bfrag[1], z, 0, 0, 0),
;                              D2 = __builtin_amdgcn_mfma_f32_32x32x16_bf16(afr[s], bfrag[2], z, 0, 0, 0), D3 = __builtin_amdgcn_mfma_f32_32x32x16_bf16(afr[s], bfrag[3], z, 0, 0, 0);
; #pragma unroll
;                 for (int t = 0; t < 8; ++t) {
;                     const f2v d0 = {D0[2 * t], D0[2 * t + 1]}, d1 = {D1[2 * t], D1[2 * t + 1]}, d2 = {D2[2 * t], D2[2 * t + 1]}, d3 = {D3[2 * t], D3[2 * t + 1]};
;                     const f2v nr0 = fma2(AR0, Sre0, fma2(NAI0, Sim0, d0)), ni0 = fma2(AR0, Sim0, fma2(AI0, Sre0, d2));
;                     const f2v nr1 = fma2(AR1, Sre1, fma2(NAI1, Sim1, d1)), ni1 = fma2(AR1, Sim1, fma2(AI1, Sre1, d3));
;                     Sre0 = nr0; Sim0 = ni0; Sre1 = nr1; Sim1 = ni1;
; #pragma unroll
;                     for (int e = 0; e < 2; ++e) { v2u w; w.x = cvt2(nr0[e], nr1[e]); w.y = cvt2(ni0[e], ni1[e]); *(LAS v2u*)(st + (16 * h + 2 * t + e) * 272 + 8 * l31) = w; }
;                 }
;                 LDS_WAIT(); asm volatile("" ::: "memory");
;                 f32x4 acc0 = (f32x4){0.f, 0.f, 0.f, 0.f}, acc1 = (f32x4){0.f, 0.f, 0.f, 0.f};
; #pragma unroll
;                 for (int ks = 0; ks < 4; ++ks) {
;                     const bf16x8 s0 = *(const LAS bf16x8*)(st + l15 * 272 + 64 * ks + 16 * qq), s1 = *(const LAS bf16x8*)(st + (16 + l15) * 272 + 64 * ks + 16 * qq);
;                     acc0 = __builtin_amdgcn_mfma_f32_16x16x32_bf16(s0, cfrag[ks], acc0, 0, 0, 0); acc1 = __builtin_amdgcn_mfma_f32_16x16x32_bf16(s1, cfrag[ks], acc1, 0, 0, 0); }
;                 float uu[2][4];
; #pragma unroll
;                 for (int rb = 0; rb < 2; ++rb)
; #pragma unroll
;                     for (int i2 = 0; i2 < 4; ++i2) uu[rb][i2] = bf1(*(const LAS bf16*)(ut + (i2 + 4 * rb + 8 * qq) * 32 + 2 * l15));
; #pragma unroll
;                 for (int rb = 0; rb < 2; ++rb)
; #pragma unroll
;                     for (int i2 = 0; i2 < 4; i2 += 2) {
	v_lshlrev_b32_e32 v8, 16, v8
	s_waitcnt lgkmcnt(0)
	v_lshlrev_b32_e32 v9, 16, v9
	s_nop 0
	v_pk_fma_f32 v[0:1], v[176:177], v[8:9], v[0:1]
	v_mfma_f32_16x16x32_bf16 v[4:7], v[4:7], v[80:83], 0
	v_mul_f32_e64 v8, v0, v0
	v_mul_f32_e64 v9, v1, v1
	v_pk_fma_f32 v[8:9], v[8:9], s[20:21], v[128:129] op_sel_hi:[1,0,0] neg_lo:[1,0,0] neg_hi:[1,0,0]
	v_mfma_f32_16x16x32_bf16 v[4:7], v[12:15], v[84:87], v[4:7]
	v_mul_f32_e64 v8, v0, v8
	v_mul_f32_e64 v9, v1, v9
	v_exp_f32_e32 v8, v8
	v_exp_f32_e32 v9, v9
	v_mfma_f32_16x16x32_bf16 v[4:7], v[16:19], v[88:91], v[4:7]
	v_add_f32_e64 v8, v8, 1.0
	v_add_f32_e64 v9, v9, 1.0
	v_rcp_f32_e32 v8, v8
	v_rcp_f32_e32 v9, v9
	v_mfma_f32_16x16x32_bf16 v[4:7], v[20:23], v[92:95], v[4:7]
	v_mul_f32_e64 v0, v0, v8
	v_mul_f32_e64 v1, v1, v9
	v_cvt_pk_bf16_f32 v0, v0, v1
	ds_read_u16 v8, v214 offset:128
	ds_read_u16 v9, v214 offset:160
	ds_write_b16 v215, v0
	ds_write_b16_d16_hi v215, v0 offset:32
	ds_read_u16 v0, v214 offset:64
	ds_read_u16 v1, v214 offset:96
	ds_read_u16 v10, v214 offset:192
	ds_read_u16 v11, v214 offset:224
	v_mfma_f32_32x32x16_bf16 v[16:31], v[100:103], v[68:71], 0
	s_waitcnt lgkmcnt(3)
	v_lshlrev_b32_e32 v0, 16, v0
	s_waitcnt lgkmcnt(2)
	v_lshlrev_b32_e32 v1, 16, v1
	v_fma_f32 v0, v176, v0, v2
	v_fma_f32 v1, v177, v1, v3
	v_pk_mul_f32 v[2:3], v[0:1], v[0:1]
	s_nop 4
	v_pk_fma_f32 v[16:17], v[180:181], v[110:111], v[16:17]
	v_pk_fma_f32 v[2:3], v[2:3], s[20:21], v[128:129] op_sel_hi:[1,0,0] neg_lo:[1,0,0] neg_hi:[1,0,0]
	v_pk_fma_f32 v[16:17], v[170:171], v[106:107], v[16:17]
	v_pk_mul_f32 v[2:3], v[0:1], v[2:3]
	s_nop 0
	v_exp_f32_e32 v2, v2
	v_exp_f32_e32 v3, v3
	s_nop 0
	v_pk_add_f32 v[2:3], v[2:3], 1.0 op_sel_hi:[1,0]
	s_nop 0
	v_rcp_f32_e32 v2, v2
	v_rcp_f32_e32 v3, v3
	s_nop 0
	v_pk_mul_f32 v[0:1], v[0:1], v[2:3]
	s_nop 0
	v_cvt_pk_bf16_f32 v0, v0, v1
	ds_write_b16 v215, v0 offset:64
	ds_write_b16_d16_hi v215, v0 offset:96
	v_lshlrev_b32_e32 v1, 16, v9
	v_lshlrev_b32_e32 v0, 16, v8
	v_pk_fma_f32 v[0:1], v[176:177], v[0:1], v[4:5]
	v_add_u32_e32 v4, v143, v148
	v_pk_mul_f32 v[2:3], v[0:1], v[0:1]
	v_ashrrev_i32_e32 v5, 31, v4
	v_pk_fma_f32 v[2:3], v[2:3], s[20:21], v[128:129] op_sel_hi:[1,0,0] neg_lo:[1,0,0] neg_hi:[1,0,0]
	v_lshlrev_b64 v[4:5], 11, v[4:5]
	v_pk_mul_f32 v[2:3], v[0:1], v[2:3]
	v_lshl_add_u64 v[4:5], v[126:127], 0, v[4:5]
	v_exp_f32_e32 v2, v2
	v_exp_f32_e32 v3, v3
	s_nop 0
	v_pk_add_f32 v[2:3], v[2:3], 1.0 op_sel_hi:[1,0]
	s_nop 0
	v_rcp_f32_e32 v2, v2
	v_rcp_f32_e32 v3, v3
	s_nop 0
	v_pk_mul_f32 v[0:1], v[0:1], v[2:3]
	s_nop 0
	v_cvt_pk_bf16_f32 v0, v0, v1
	ds_write_b16 v215, v0 offset:512
	ds_write_b16_d16_hi v215, v0 offset:544
	s_waitcnt lgkmcnt(4)
	v_lshlrev_b32_e32 v1, 16, v11
	v_lshlrev_b32_e32 v0, 16, v10
	v_pk_fma_f32 v[0:1], v[176:177], v[0:1], v[6:7]
	s_nop 0
	v_pk_mul_f32 v[2:3], v[0:1], v[0:1]
	s_nop 0
	v_pk_fma_f32 v[2:3], v[2:3], s[20:21], v[128:129] op_sel_hi:[1,0,0] neg_lo:[1,0,0] neg_hi:[1,0,0]
	s_nop 0
	v_pk_mul_f32 v[2:3], v[0:1], v[2:3]
	s_nop 0
	v_exp_f32_e32 v2, v2
	v_exp_f32_e32 v3, v3
	s_nop 0
	v_pk_add_f32 v[2:3], v[2:3], 1.0 op_sel_hi:[1,0]
	s_nop 0
	v_rcp_f32_e32 v2, v2
	v_rcp_f32_e32 v3, v3
	s_nop 0
	v_pk_mul_f32 v[0:1], v[0:1], v[2:3]
	s_nop 0
	v_cvt_pk_bf16_f32 v0, v0, v1
	ds_write_b16 v215, v0 offset:576
	ds_write_b16_d16_hi v215, v0 offset:608
	s_waitcnt lgkmcnt(0)
	ds_read_b128 v[0:3], v147
	s_waitcnt lgkmcnt(0)
	global_store_dwordx4 v[4:5], v[0:3], off
	s_nop 1
	v_mfma_f32_32x32x16_bf16 v[0:15], v[100:103], v[76:79], 0
	s_waitcnt lgkmcnt(0)
	ds_write_b128 v212, v[100:103]
	v_cvt_pk_bf16_f32 v100, v48, v16
	v_cvt_pk_bf16_f32 v102, v49, v17
	s_nop 8
	v_pk_fma_f32 v[0:1], v[174:175], v[106:107], v[0:1]
	s_nop 0
	v_pk_fma_f32 v[0:1], v[170:171], v[110:111], v[0:1]
	v_pk_fma_f32 v[2:3], v[174:175], v[16:17], v[2:3]
	v_pk_fma_f32 v[18:19], v[180:181], v[0:1], v[18:19]
	v_cvt_pk_bf16_f32 v101, v32, v0
	v_cvt_pk_bf16_f32 v103, v33, v1
	v_pk_fma_f32 v[32:33], v[168:169], v[32:33], v[34:35]
	v_pk_fma_f32 v[18:19], v[170:171], v[16:17], v[18:19]
	v_pk_fma_f32 v[0:1], v[170:171], v[0:1], v[2:3]
	v_cvt_pk_bf16_f32 v2, v50, v18
	v_cvt_pk_bf16_f32 v3, v32, v0
	v_cvt_pk_bf16_f32 v16, v51, v19
	v_cvt_pk_bf16_f32 v17, v33, v1
	ds_write2_b64 v149, v[2:3], v[16:17] offset0:68 offset1:102
	v_pk_fma_f32 v[2:3], v[178:179], v[32:33], v[52:53]
	v_pk_fma_f32 v[16:17], v[172:173], v[50:51], v[36:37]
	v_pk_fma_f32 v[20:21], v[180:181], v[0:1], v[20:21]
	v_pk_fma_f32 v[4:5], v[174:175], v[18:19], v[4:5]
	v_pk_fma_f32 v[2:3], v[168:169], v[50:51], v[2:3]
	v_pk_fma_f32 v[16:17], v[168:169], v[32:33], v[16:17]
	v_pk_fma_f32 v[20:21], v[170:171], v[18:19], v[20:21]
	v_pk_fma_f32 v[0:1], v[170:171], v[0:1], v[4:5]
	v_cvt_pk_bf16_f32 v4, v2, v20
	v_cvt_pk_bf16_f32 v5, v16, v0
	v_cvt_pk_bf16_f32 v18, v3, v21
	v_cvt_pk_bf16_f32 v19, v17, v1
	ds_write2_b64 v149, v[4:5], v[18:19] offset0:136 offset1:170
	v_pk_fma_f32 v[4:5], v[178:179], v[16:17], v[54:55]
	v_pk_fma_f32 v[6:7], v[174:175], v[20:21], v[6:7]
	v_pk_fma_f32 v[4:5], v[168:169], v[2:3], v[4:5]
	v_pk_fma_f32 v[2:3], v[172:173], v[2:3], v[38:39]
	ds_write2_b64 v149, v[100:101], v[102:103] offset1:34
	v_pk_fma_f32 v[2:3], v[168:169], v[16:17], v[2:3]
	v_pk_fma_f32 v[16:17], v[180:181], v[0:1], v[22:23]
	v_pk_fma_f32 v[0:1], v[170:171], v[0:1], v[6:7]
	v_pk_fma_f32 v[16:17], v[170:171], v[20:21], v[16:17]
	v_cvt_pk_bf16_f32 v7, v2, v0
	v_cvt_pk_bf16_f32 v6, v4, v16
	v_cvt_pk_bf16_f32 v18, v5, v17
	v_cvt_pk_bf16_f32 v19, v3, v1
	ds_write2_b64 v149, v[6:7], v[18:19] offset0:204 offset1:238
	v_pk_fma_f32 v[6:7], v[178:179], v[2:3], v[56:57]
	v_pk_fma_f32 v[8:9], v[174:175], v[16:17], v[8:9]
	v_pk_fma_f32 v[6:7], v[168:169], v[4:5], v[6:7]
; #define LAS __attribute__((address_space(3)))
; #define LDS_WAIT() asm volatile("s_waitcnt lgkmcnt(0)" ::: "memory")
; __device__ __forceinline__ void ssm_phase(Frame& F) {
;     ...
; #pragma unroll
;             for (int s = 0; s < 8; ++s) {
;                 *(LAS bf16x8*)(ut + l31 * 32 + 16 * h) = afr[s];
;                 const f32x16 D0 = __builtin_amdgcn_mfma_f32_32x32x16_bf16(afr[s], bfrag[0], z, 0, 0, 0), D1 = __builtin_amdgcn_mfma_f32_32x32x16_bf16(afr[s], bfrag[1], z, 0, 0, 0),
;                              D2 = __builtin_amdgcn_mfma_f32_32x32x16_bf16(afr[s], bfrag[2], z, 0, 0, 0), D3 = __builtin_amdgcn_mfma_f32_32x32x16_bf16(afr[s], bfrag[3], z, 0, 0, 0);
; #pragma unroll
;                 for (int t = 0; t < 8; ++t) {
;                     const f2v d0 = {D0[2 * t], D0[2 * t + 1]}, d1 = {D1[2 * t], D1[2 * t + 1]}, d2 = {D2[2 * t], D2[2 * t + 1]}, d3 = {D3[2 * t], D3[2 * t + 1]};
;                     const f2v nr0 = fma2(AR0, Sre0, fma2(NAI0, Sim0, d0)), ni0 = fma2(AR0, Sim0, fma2(AI0, Sre0, d2));
;                     const f2v nr1 = fma2(AR1, Sre1, fma2(NAI1, Sim1, d1)), ni1 = fma2(AR1, Sim1, fma2(AI1, Sre1, d3));
;                     Sre0 = nr0; Sim0 = ni0; Sre1 = nr1; Sim1 = ni1;
; #pragma unroll
;                     for (int e = 0; e < 2; ++e) { v2u w; w.x = cvt2(nr0[e], nr1[e]); w.y = cvt2(ni0[e], ni1[e]); *(LAS v2u*)(st + (16 * h + 2 * t + e) * 272 + 8 * l31) = w; }
;                 }
;                 LDS_WAIT(); asm volatile("" ::: "memory");
;                 f32x4 acc0 = (f32x4){0.f, 0.f, 0.f, 0.f}, acc1 = (f32x4){0.f, 0.f, 0.f, 0.f};
; #pragma unroll
;                 for (int ks = 0; ks < 4; ++ks) {
;                     const bf16x8 s0 = *(const LAS bf16x8*)(st + l15 * 272 + 64 * ks + 16 * qq), s1 = *(const LAS bf16x8*)(st + (16 + l15) * 272 + 64 * ks + 16 * qq);
;                     acc0 = __builtin_amdgcn_mfma_f32_16x16x32_bf16(s0, cfrag[ks], acc0, 0, 0, 0); acc1 = __builtin_amdgcn_mfma_f32_16x16x32_bf16(s1, cfrag[ks], acc1, 0, 0, 0); }
;                 float uu[2][4];
; #pragma unroll
;                 for (int rb = 0; rb < 2; ++rb)
; #pragma unroll
;                     for (int i2 = 0; i2 < 4; ++i2) uu[rb][i2] = bf1(*(const LAS bf16*)(ut + (i2 + 4 * rb + 8 * qq) * 32 + 2 * l15));
; #pragma unroll
;                 for (int rb = 0; rb < 2; ++rb)
; #pragma unroll
;                     for (int i2 = 0; i2 < 4; i2 += 2) {
	v_pk_fma_f32 v[4:5], v[172:173], v[4:5], v[40:41]
	s_nop 0
	v_pk_fma_f32 v[2:3], v[168:169], v[2:3], v[4:5]
	v_pk_fma_f32 v[4:5], v[180:181], v[0:1], v[24:25]
	v_pk_fma_f32 v[0:1], v[170:171], v[0:1], v[8:9]
	v_pk_fma_f32 v[4:5], v[170:171], v[16:17], v[4:5]
	v_cvt_pk_bf16_f32 v9, v2, v0
	v_cvt_pk_bf16_f32 v8, v6, v4
	v_cvt_pk_bf16_f32 v16, v7, v5
	v_cvt_pk_bf16_f32 v17, v3, v1
	ds_write2_b64 v146, v[8:9], v[16:17] offset0:16 offset1:50
	v_pk_fma_f32 v[8:9], v[178:179], v[2:3], v[58:59]
	s_nop 0
	v_pk_fma_f32 v[8:9], v[168:169], v[6:7], v[8:9]
	v_pk_fma_f32 v[6:7], v[172:173], v[6:7], v[42:43]
	s_nop 0
	v_pk_fma_f32 v[2:3], v[168:169], v[2:3], v[6:7]
	v_pk_fma_f32 v[6:7], v[180:181], v[0:1], v[26:27]
	s_nop 0
	v_pk_fma_f32 v[6:7], v[170:171], v[4:5], v[6:7]
	v_pk_fma_f32 v[4:5], v[174:175], v[4:5], v[10:11]
	v_cvt_pk_bf16_f32 v10, v9, v7
	v_pk_fma_f32 v[0:1], v[170:171], v[0:1], v[4:5]
	v_cvt_pk_bf16_f32 v4, v8, v6
	v_cvt_pk_bf16_f32 v5, v2, v0
	v_cvt_pk_bf16_f32 v11, v3, v1
	ds_write2_b64 v146, v[4:5], v[10:11] offset0:84 offset1:118
	v_pk_fma_f32 v[4:5], v[178:179], v[2:3], v[60:61]
	s_nop 0
	v_pk_fma_f32 v[4:5], v[168:169], v[8:9], v[4:5]
	v_pk_fma_f32 v[8:9], v[172:173], v[8:9], v[44:45]
	s_nop 0
	v_pk_fma_f32 v[2:3], v[168:169], v[2:3], v[8:9]
	v_pk_fma_f32 v[8:9], v[180:181], v[0:1], v[28:29]
	s_nop 0
	v_pk_fma_f32 v[8:9], v[170:171], v[6:7], v[8:9]
	v_pk_fma_f32 v[6:7], v[174:175], v[6:7], v[12:13]
	v_cvt_pk_bf16_f32 v10, v5, v9
	v_pk_fma_f32 v[0:1], v[170:171], v[0:1], v[6:7]
	v_cvt_pk_bf16_f32 v6, v4, v8
	v_cvt_pk_bf16_f32 v7, v2, v0
	v_cvt_pk_bf16_f32 v11, v3, v1
	ds_write2_b64 v146, v[6:7], v[10:11] offset0:152 offset1:186
	v_pk_fma_f32 v[6:7], v[178:179], v[2:3], v[62:63]
	v_mfma_f32_32x32x16_bf16 v[48:63], v[96:99], v[64:67], 0
	v_fma_f32 v100, v168, v4, v6
	v_fma_f32 v101, v169, v5, v7
	v_fma_f32 v4, v172, v4, v46
	v_fma_f32 v5, v173, v5, v47
	v_fma_f32 v102, v168, v2, v4
	v_fma_f32 v103, v169, v3, v5
	v_pk_fma_f32 v[2:3], v[180:181], v[0:1], v[30:31]
	s_nop 4
	v_pk_fma_f32 v[48:49], v[178:179], v[102:103], v[48:49]
	v_pk_fma_f32 v[104:105], v[170:171], v[8:9], v[2:3]
	v_pk_fma_f32 v[2:3], v[174:175], v[8:9], v[14:15]
	v_mfma_f32_32x32x16_bf16 v[32:47], v[96:99], v[72:75], 0
	v_fma_f32 v106, v170, v0, v2
	v_fma_f32 v107, v171, v1, v3
	v_cvt_pk_bf16_f32 v0, v100, v104
	v_cvt_pk_bf16_f32 v1, v102, v106
	v_cvt_pk_bf16_f32 v2, v101, v105
	v_cvt_pk_bf16_f32 v3, v103, v107
	ds_write2_b64 v146, v[0:1], v[2:3] offset0:220 offset1:254
	s_waitcnt lgkmcnt(0)
	ds_read_b128 v[0:3], v213 offset:32768
	ds_read_b128 v[4:7], v213 offset:37120
	s_waitcnt lgkmcnt(1)
	v_mfma_f32_16x16x32_bf16 v[0:3], v[0:3], v[80:83], 0
	ds_read_b128 v[8:11], v213 offset:32832
	ds_read_b128 v[12:15], v213 offset:37184
	v_pk_fma_f32 v[32:33], v[172:173], v[100:101], v[32:33]
	v_pk_fma_f32 v[48:49], v[168:169], v[100:101], v[48:49]
	s_waitcnt lgkmcnt(1)
	v_mfma_f32_16x16x32_bf16 v[0:3], v[8:11], v[84:87], v[0:3]
	ds_read_b128 v[8:11], v213 offset:32896
	ds_read_b128 v[16:19], v213 offset:37248
	v_pk_fma_f32 v[32:33], v[168:169], v[102:103], v[32:33]
	v_pk_fma_f32 v[34:35], v[172:173], v[48:49], v[34:35]
	s_waitcnt lgkmcnt(1)
	v_mfma_f32_16x16x32_bf16 v[0:3], v[8:11], v[88:91], v[0:3]
	ds_read_b128 v[8:11], v213 offset:32960
	ds_read_b128 v[20:23], v213 offset:37312
	v_pk_fma_f32 v[50:51], v[178:179], v[32:33], v[50:51]
	s_waitcnt lgkmcnt(1)
	v_mfma_f32_16x16x32_bf16 v[0:3], v[8:11], v[92:95], v[0:3]
	ds_read_u16 v8, v214
	ds_read_u16 v9, v214 offset:32
	v_pk_fma_f32 v[50:51], v[168:169], v[48:49], v[50:51]
	s_waitcnt lgkmcnt(1)
	v_lshlrev_b32_e32 v8, 16, v8
	s_waitcnt lgkmcnt(0)
	v_lshlrev_b32_e32 v9, 16, v9
	s_nop 0
	v_pk_fma_f32 v[0:1], v[176:177], v[8:9], v[0:1]
	v_mfma_f32_16x16x32_bf16 v[4:7], v[4:7], v[80:83], 0
	v_mul_f32_e64 v8, v0, v0
	v_mul_f32_e64 v9, v1, v1
	v_pk_fma_f32 v[8:9], v[8:9], s[20:21], v[128:129] op_sel_hi:[1,0,0] neg_lo:[1,0,0] neg_hi:[1,0,0]
	v_mfma_f32_16x16x32_bf16 v[4:7], v[12:15], v[84:87], v[4:7]
	v_mul_f32_e64 v8, v0, v8
	v_mul_f32_e64 v9, v1, v9
	v_exp_f32_e32 v8, v8
	v_exp_f32_e32 v9, v9
	v_mfma_f32_16x16x32_bf16 v[4:7], v[16:19], v[88:91], v[4:7]
	v_add_f32_e64 v8, v8, 1.0
	v_add_f32_e64 v9, v9, 1.0
	v_rcp_f32_e32 v8, v8
	v_rcp_f32_e32 v9, v9
	v_mfma_f32_16x16x32_bf16 v[4:7], v[20:23], v[92:95], v[4:7]
	v_mul_f32_e64 v0, v0, v8
	v_mul_f32_e64 v1, v1, v9
	v_cvt_pk_bf16_f32 v0, v0, v1
	ds_read_u16 v8, v214 offset:128
	ds_read_u16 v9, v214 offset:160
	ds_write_b16 v215, v0
	ds_write_b16_d16_hi v215, v0 offset:32
	ds_read_u16 v0, v214 offset:64
	ds_read_u16 v1, v214 offset:96
	ds_read_u16 v10, v214 offset:192
	ds_read_u16 v11, v214 offset:224
	v_mfma_f32_32x32x16_bf16 v[16:31], v[96:99], v[68:71], 0
	s_waitcnt lgkmcnt(3)
	v_lshlrev_b32_e32 v0, 16, v0
	s_waitcnt lgkmcnt(2)
	v_lshlrev_b32_e32 v1, 16, v1
	v_fma_f32 v0, v176, v0, v2
	v_fma_f32 v1, v177, v1, v3
	v_pk_mul_f32 v[2:3], v[0:1], v[0:1]
	s_nop 4
	v_pk_fma_f32 v[16:17], v[180:181], v[106:107], v[16:17]
	v_pk_fma_f32 v[2:3], v[2:3], s[20:21], v[128:129] op_sel_hi:[1,0,0] neg_lo:[1,0,0] neg_hi:[1,0,0]
	v_pk_fma_f32 v[16:17], v[170:171], v[104:105], v[16:17]
	v_pk_mul_f32 v[2:3], v[0:1], v[2:3]
	s_nop 0
	v_exp_f32_e32 v2, v2
	v_exp_f32_e32 v3, v3
	s_nop 0
	v_pk_add_f32 v[2:3], v[2:3], 1.0 op_sel_hi:[1,0]
	s_nop 0
	v_rcp_f32_e32 v2, v2
	v_rcp_f32_e32 v3, v3
	s_nop 0
	v_pk_mul_f32 v[0:1], v[0:1], v[2:3]
	s_nop 0
	v_cvt_pk_bf16_f32 v0, v0, v1
	ds_write_b16 v215, v0 offset:64
	ds_write_b16_d16_hi v215, v0 offset:96
	v_lshlrev_b32_e32 v1, 16, v9
	v_lshlrev_b32_e32 v0, 16, v8
	v_pk_fma_f32 v[0:1], v[176:177], v[0:1], v[4:5]
	v_add_u32_e32 v4, v144, v148
	v_pk_mul_f32 v[2:3], v[0:1], v[0:1]
	v_ashrrev_i32_e32 v5, 31, v4
	v_pk_fma_f32 v[2:3], v[2:3], s[20:21], v[128:129] op_sel_hi:[1,0,0] neg_lo:[1,0,0] neg_hi:[1,0,0]
	v_lshlrev_b64 v[4:5], 11, v[4:5]
	v_pk_mul_f32 v[2:3], v[0:1], v[2:3]
	v_lshl_add_u64 v[4:5], v[126:127], 0, v[4:5]
	v_exp_f32_e32 v2, v2
	v_exp_f32_e32 v3, v3
	s_nop 0
	v_pk_add_f32 v[2:3], v[2:3], 1.0 op_sel_hi:[1,0]
	s_nop 0
	v_rcp_f32_e32 v2, v2
	v_rcp_f32_e32 v3, v3
	s_nop 0
	v_pk_mul_f32 v[0:1], v[0:1], v[2:3]
	s_nop 0
	v_cvt_pk_bf16_f32 v0, v0, v1
	ds_write_b16 v215, v0 offset:512
	ds_write_b16_d16_hi v215, v0 offset:544
	s_waitcnt lgkmcnt(4)
; #define LAS __attribute__((address_space(3)))
; #define LDS_WAIT() asm volatile("s_waitcnt lgkmcnt(0)" ::: "memory")
; __device__ __forceinline__ void ssm_phase(Frame& F) {
;     ...
; #pragma unroll
;             for (int s = 0; s < 8; ++s) {
;                 *(LAS bf16x8*)(ut + l31 * 32 + 16 * h) = afr[s];
;                 const f32x16 D0 = __builtin_amdgcn_mfma_f32_32x32x16_bf16(afr[s], bfrag[0], z, 0, 0, 0), D1 = __builtin_amdgcn_mfma_f32_32x32x16_bf16(afr[s], bfrag[1], z, 0, 0, 0),
;                              D2 = __builtin_amdgcn_mfma_f32_32x32x16_bf16(afr[s], bfrag[2], z, 0, 0, 0), D3 = __builtin_amdgcn_mfma_f32_32x32x16_bf16(afr[s], bfrag[3], z, 0, 0, 0);
; #pragma unroll
;                 for (int t = 0; t < 8; ++t) {
;                     const f2v d0 = {D0[2 * t], D0[2 * t + 1]}, d1 = {D1[2 * t], D1[2 * t + 1]}, d2 = {D2[2 * t], D2[2 * t + 1]}, d3 = {D3[2 * t], D3[2 * t + 1]};
;                     const f2v nr0 = fma2(AR0, Sre0, fma2(NAI0, Sim0, d0)), ni0 = fma2(AR0, Sim0, fma2(AI0, Sre0, d2));
;                     const f2v nr1 = fma2(AR1, Sre1, fma2(NAI1, Sim1, d1)), ni1 = fma2(AR1, Sim1, fma2(AI1, Sre1, d3));
;                     Sre0 = nr0; Sim0 = ni0; Sre1 = nr1; Sim1 = ni1;
; #pragma unroll
;                     for (int e = 0; e < 2; ++e) { v2u w; w.x = cvt2(nr0[e], nr1[e]); w.y = cvt2(ni0[e], ni1[e]); *(LAS v2u*)(st + (16 * h + 2 * t + e) * 272 + 8 * l31) = w; }
;                 }
;                 LDS_WAIT(); asm volatile("" ::: "memory");
;                 f32x4 acc0 = (f32x4){0.f, 0.f, 0.f, 0.f}, acc1 = (f32x4){0.f, 0.f, 0.f, 0.f};
; #pragma unroll
;                 for (int ks = 0; ks < 4; ++ks) {
;                     const bf16x8 s0 = *(const LAS bf16x8*)(st + l15 * 272 + 64 * ks + 16 * qq), s1 = *(const LAS bf16x8*)(st + (16 + l15) * 272 + 64 * ks + 16 * qq);
;                     acc0 = __builtin_amdgcn_mfma_f32_16x16x32_bf16(s0, cfrag[ks], acc0, 0, 0, 0); acc1 = __builtin_amdgcn_mfma_f32_16x16x32_bf16(s1, cfrag[ks], acc1, 0, 0, 0); }
;                 float uu[2][4];
; #pragma unroll
;                 for (int rb = 0; rb < 2; ++rb)
; #pragma unroll
;                     for (int i2 = 0; i2 < 4; ++i2) uu[rb][i2] = bf1(*(const LAS bf16*)(ut + (i2 + 4 * rb + 8 * qq) * 32 + 2 * l15));
; #pragma unroll
;                 for (int rb = 0; rb < 2; ++rb)
; #pragma unroll
;                     for (int i2 = 0; i2 < 4; i2 += 2) {
	v_lshlrev_b32_e32 v1, 16, v11
	v_lshlrev_b32_e32 v0, 16, v10
	v_pk_fma_f32 v[0:1], v[176:177], v[0:1], v[6:7]
	s_nop 0
	v_pk_mul_f32 v[2:3], v[0:1], v[0:1]
	s_nop 0
	v_pk_fma_f32 v[2:3], v[2:3], s[20:21], v[128:129] op_sel_hi:[1,0,0] neg_lo:[1,0,0] neg_hi:[1,0,0]
	s_nop 0
	v_pk_mul_f32 v[2:3], v[0:1], v[2:3]
	s_nop 0
	v_exp_f32_e32 v2, v2
	v_exp_f32_e32 v3, v3
	s_nop 0
	v_pk_add_f32 v[2:3], v[2:3], 1.0 op_sel_hi:[1,0]
	s_nop 0
	v_rcp_f32_e32 v2, v2
	v_rcp_f32_e32 v3, v3
	s_nop 0
	v_pk_mul_f32 v[0:1], v[0:1], v[2:3]
	s_nop 0
	v_cvt_pk_bf16_f32 v0, v0, v1
	ds_write_b16 v215, v0 offset:576
	ds_write_b16_d16_hi v215, v0 offset:608
	s_waitcnt lgkmcnt(0)
	ds_read_b128 v[0:3], v147
	s_waitcnt lgkmcnt(0)
	global_store_dwordx4 v[4:5], v[0:3], off
	s_nop 1
	v_mfma_f32_32x32x16_bf16 v[0:15], v[96:99], v[76:79], 0
	s_waitcnt lgkmcnt(0)
	ds_write_b128 v212, v[96:99]
	v_cvt_pk_bf16_f32 v96, v48, v16
	v_cvt_pk_bf16_f32 v98, v49, v17
	s_nop 8
	v_pk_fma_f32 v[0:1], v[174:175], v[104:105], v[0:1]
	s_nop 0
	v_pk_fma_f32 v[0:1], v[170:171], v[106:107], v[0:1]
	v_pk_fma_f32 v[2:3], v[174:175], v[16:17], v[2:3]
	v_pk_fma_f32 v[18:19], v[180:181], v[0:1], v[18:19]
	v_cvt_pk_bf16_f32 v97, v32, v0
	v_cvt_pk_bf16_f32 v99, v33, v1
	v_pk_fma_f32 v[32:33], v[168:169], v[32:33], v[34:35]
	v_pk_fma_f32 v[18:19], v[170:171], v[16:17], v[18:19]
	v_pk_fma_f32 v[0:1], v[170:171], v[0:1], v[2:3]
	v_cvt_pk_bf16_f32 v2, v50, v18
	v_cvt_pk_bf16_f32 v3, v32, v0
	v_cvt_pk_bf16_f32 v16, v51, v19
	v_cvt_pk_bf16_f32 v17, v33, v1
	ds_write2_b64 v149, v[2:3], v[16:17] offset0:68 offset1:102
	v_pk_fma_f32 v[2:3], v[178:179], v[32:33], v[52:53]
	v_pk_fma_f32 v[16:17], v[172:173], v[50:51], v[36:37]
	v_pk_fma_f32 v[20:21], v[180:181], v[0:1], v[20:21]
	v_pk_fma_f32 v[4:5], v[174:175], v[18:19], v[4:5]
	v_pk_fma_f32 v[2:3], v[168:169], v[50:51], v[2:3]
	v_pk_fma_f32 v[16:17], v[168:169], v[32:33], v[16:17]
	v_pk_fma_f32 v[20:21], v[170:171], v[18:19], v[20:21]
	v_pk_fma_f32 v[0:1], v[170:171], v[0:1], v[4:5]
	v_cvt_pk_bf16_f32 v4, v2, v20
	v_cvt_pk_bf16_f32 v5, v16, v0
	v_cvt_pk_bf16_f32 v18, v3, v21
	v_cvt_pk_bf16_f32 v19, v17, v1
	ds_write2_b64 v149, v[4:5], v[18:19] offset0:136 offset1:170
	v_pk_fma_f32 v[4:5], v[178:179], v[16:17], v[54:55]
	v_pk_fma_f32 v[6:7], v[174:175], v[20:21], v[6:7]
	v_pk_fma_f32 v[4:5], v[168:169], v[2:3], v[4:5]
	v_pk_fma_f32 v[2:3], v[172:173], v[2:3], v[38:39]
	ds_write2_b64 v149, v[96:97], v[98:99] offset1:34
	v_pk_fma_f32 v[2:3], v[168:169], v[16:17], v[2:3]
	v_pk_fma_f32 v[16:17], v[180:181], v[0:1], v[22:23]
	v_pk_fma_f32 v[0:1], v[170:171], v[0:1], v[6:7]
	v_pk_fma_f32 v[16:17], v[170:171], v[20:21], v[16:17]
	v_cvt_pk_bf16_f32 v7, v2, v0
	v_cvt_pk_bf16_f32 v6, v4, v16
	v_cvt_pk_bf16_f32 v18, v5, v17
	v_cvt_pk_bf16_f32 v19, v3, v1
	ds_write2_b64 v149, v[6:7], v[18:19] offset0:204 offset1:238
	v_pk_fma_f32 v[6:7], v[178:179], v[2:3], v[56:57]
	v_pk_fma_f32 v[8:9], v[174:175], v[16:17], v[8:9]
	v_pk_fma_f32 v[6:7], v[168:169], v[4:5], v[6:7]
	v_pk_fma_f32 v[4:5], v[172:173], v[4:5], v[40:41]
	s_nop 0
	v_pk_fma_f32 v[2:3], v[168:169], v[2:3], v[4:5]
	v_pk_fma_f32 v[4:5], v[180:181], v[0:1], v[24:25]
	v_pk_fma_f32 v[0:1], v[170:171], v[0:1], v[8:9]
	v_pk_fma_f32 v[4:5], v[170:171], v[16:17], v[4:5]
	v_cvt_pk_bf16_f32 v9, v2, v0
	v_cvt_pk_bf16_f32 v8, v6, v4
	v_cvt_pk_bf16_f32 v16, v7, v5
	v_cvt_pk_bf16_f32 v17, v3, v1
	ds_write2_b64 v146, v[8:9], v[16:17] offset0:16 offset1:50
	v_pk_fma_f32 v[8:9], v[178:179], v[2:3], v[58:59]
	s_nop 0
	v_pk_fma_f32 v[8:9], v[168:169], v[6:7], v[8:9]
	v_pk_fma_f32 v[6:7], v[172:173], v[6:7], v[42:43]
	s_nop 0
	v_pk_fma_f32 v[2:3], v[168:169], v[2:3], v[6:7]
	v_pk_fma_f32 v[6:7], v[180:181], v[0:1], v[26:27]
	s_nop 0
	v_pk_fma_f32 v[6:7], v[170:171], v[4:5], v[6:7]
	v_pk_fma_f32 v[4:5], v[174:175], v[4:5], v[10:11]
	v_cvt_pk_bf16_f32 v10, v9, v7
	v_pk_fma_f32 v[0:1], v[170:171], v[0:1], v[4:5]
	v_cvt_pk_bf16_f32 v4, v8, v6
	v_cvt_pk_bf16_f32 v5, v2, v0
	v_cvt_pk_bf16_f32 v11, v3, v1
	ds_write2_b64 v146, v[4:5], v[10:11] offset0:84 offset1:118
	v_pk_fma_f32 v[4:5], v[178:179], v[2:3], v[60:61]
	s_nop 0
	v_pk_fma_f32 v[4:5], v[168:169], v[8:9], v[4:5]
	v_pk_fma_f32 v[8:9], v[172:173], v[8:9], v[44:45]
	s_nop 0
	v_pk_fma_f32 v[2:3], v[168:169], v[2:3], v[8:9]
	v_pk_fma_f32 v[8:9], v[180:181], v[0:1], v[28:29]
	s_nop 0
	v_pk_fma_f32 v[8:9], v[170:171], v[6:7], v[8:9]
	v_pk_fma_f32 v[6:7], v[174:175], v[6:7], v[12:13]
	v_cvt_pk_bf16_f32 v10, v5, v9
	v_pk_fma_f32 v[0:1], v[170:171], v[0:1], v[6:7]
	v_cvt_pk_bf16_f32 v6, v4, v8
	v_cvt_pk_bf16_f32 v7, v2, v0
	v_cvt_pk_bf16_f32 v11, v3, v1
	ds_write2_b64 v146, v[6:7], v[10:11] offset0:152 offset1:186
	v_pk_fma_f32 v[6:7], v[178:179], v[2:3], v[62:63]
	s_nop 0
	v_pk_fma_f32 v[6:7], v[168:169], v[4:5], v[6:7]
	v_pk_fma_f32 v[4:5], v[172:173], v[4:5], v[46:47]
	s_nop 0
	v_pk_fma_f32 v[2:3], v[168:169], v[2:3], v[4:5]
	v_pk_fma_f32 v[4:5], v[180:181], v[0:1], v[30:31]
	s_nop 0
	v_pk_fma_f32 v[4:5], v[170:171], v[8:9], v[4:5]
	v_pk_fma_f32 v[8:9], v[174:175], v[8:9], v[14:15]
	s_nop 0
	v_pk_fma_f32 v[0:1], v[170:171], v[0:1], v[8:9]
	v_cvt_pk_bf16_f32 v8, v6, v4
	v_cvt_pk_bf16_f32 v9, v2, v0
	v_cvt_pk_bf16_f32 v0, v7, v5
	v_cvt_pk_bf16_f32 v1, v3, v1
	ds_write2_b64 v146, v[8:9], v[0:1] offset0:220 offset1:254
	s_waitcnt lgkmcnt(0)
; #define GAS __attribute__((address_space(1)))
; #define LAS __attribute__((address_space(3)))
; #define LDS_WAIT() asm volatile("s_waitcnt lgkmcnt(0)" ::: "memory")
; __device__ __forceinline__ float bf1(bf16 v) { return __uint_as_float((unsigned)v << 16); }
; __device__ __forceinline__ unsigned cvt2(float lo, float hi) { const f2_t v = {lo, hi}; return __builtin_bit_cast(unsigned, __builtin_convertvector(v, bf2_t)); }
; __device__ __forceinline__ void ssm_phase(Frame& F) {
;     ...
;                 f32x4 acc0 = (f32x4){0.f, 0.f, 0.f, 0.f}, acc1 = (f32x4){0.f, 0.f, 0.f, 0.f};
; #pragma unroll
;                 for (int ks = 0; ks < 4; ++ks) {
;                     const bf16x8 s0 = *(const LAS bf16x8*)(st + l15 * 272 + 64 * ks + 16 * qq), s1 = *(const LAS bf16x8*)(st + (16 + l15) * 272 + 64 * ks + 16 * qq);
;                     acc0 = __builtin_amdgcn_mfma_f32_16x16x32_bf16(s0, cfrag[ks], acc0, 0, 0, 0); acc1 = __builtin_amdgcn_mfma_f32_16x16x32_bf16(s1, cfrag[ks], acc1, 0, 0, 0); }
;                 float uu[2][4];
; #pragma unroll
;                 for (int rb = 0; rb < 2; ++rb)
; #pragma unroll
;                     for (int i2 = 0; i2 < 4; ++i2) uu[rb][i2] = bf1(*(const LAS bf16*)(ut + (i2 + 4 * rb + 8 * qq) * 32 + 2 * l15));
; #pragma unroll
;                 for (int rb = 0; rb < 2; ++rb)
; #pragma unroll
;                     for (int i2 = 0; i2 < 4; i2 += 2) {
;                         f2v y; y.x = (rb == 0 ? acc0[i2] : acc1[i2]) + dsk * uu[rb][i2]; y.y = (rb == 0 ? acc0[i2 + 1] : acc1[i2 + 1]) + dsk * uu[rb][i2 + 1];
;                         const f2v gq = gelu_tanh2(y); const unsigned w = cvt2(gq.x, gq.y);
;                         *(LAS bf16*)(yt + (16 * rb + 4 * qq + i2) * 32 + 2 * l15) = (bf16)(w & 0xffffu); *(LAS bf16*)(yt + (16 * rb + 4 * qq + i2 + 1) * 32 + 2 * l15) = (bf16)(w >> 16); }
;                 LDS_WAIT(); asm volatile("" ::: "memory");
;                 { const int R = lane >> 1, hf = lane & 1; const v4u yv = *(const LAS v4u*)(yt + lane * 16);
;                   const int chunk = F.wave + 8 * (2 * (R >> 4) + (R & 1)) + 32 * it, tok = 8 * s + ((R & 15) >> 1);
;                   *(GAS v4u*)(gb + ((size_t)(b * SEQ + chunk * 64 + tok)) * SW + g * SG + 8 * hf) = yv; }
;                 LDS_WAIT(); asm volatile("" ::: "memory");
;             }
;         }
;         __syncthreads();
;     }
	ds_read_b128 v[0:3], v213 offset:32768
	ds_read_b128 v[4:7], v213 offset:37120
	s_waitcnt lgkmcnt(1)
	v_mfma_f32_16x16x32_bf16 v[0:3], v[0:3], v[80:83], 0
	ds_read_b128 v[8:11], v213 offset:32832
	ds_read_b128 v[12:15], v213 offset:37184
	s_waitcnt lgkmcnt(1)
	v_mfma_f32_16x16x32_bf16 v[0:3], v[8:11], v[84:87], v[0:3]
	ds_read_b128 v[8:11], v213 offset:32896
	ds_read_b128 v[16:19], v213 offset:37248
	s_waitcnt lgkmcnt(1)
	v_mfma_f32_16x16x32_bf16 v[0:3], v[8:11], v[88:91], v[0:3]
	ds_read_b128 v[8:11], v213 offset:32960
	ds_read_b128 v[20:23], v213 offset:37312
	s_waitcnt lgkmcnt(1)
	v_mfma_f32_16x16x32_bf16 v[0:3], v[8:11], v[92:95], v[0:3]
	ds_read_u16 v8, v214
	ds_read_u16 v9, v214 offset:32
	s_waitcnt lgkmcnt(1)
	v_lshlrev_b32_e32 v8, 16, v8
	s_waitcnt lgkmcnt(0)
	v_lshlrev_b32_e32 v9, 16, v9
	s_nop 1
	v_pk_fma_f32 v[0:1], v[176:177], v[8:9], v[0:1]
	v_mfma_f32_16x16x32_bf16 v[4:7], v[4:7], v[80:83], 0
	v_mul_f32_e64 v8, v0, v0
	v_mul_f32_e64 v9, v1, v1
	v_pk_fma_f32 v[8:9], v[8:9], s[20:21], v[128:129] op_sel_hi:[1,0,0] neg_lo:[1,0,0] neg_hi:[1,0,0]
	v_mfma_f32_16x16x32_bf16 v[4:7], v[12:15], v[84:87], v[4:7]
	v_mul_f32_e64 v8, v0, v8
	v_mul_f32_e64 v9, v1, v9
	v_exp_f32_e32 v8, v8
	v_exp_f32_e32 v9, v9
	v_mfma_f32_16x16x32_bf16 v[4:7], v[16:19], v[88:91], v[4:7]
	v_add_f32_e64 v8, v8, 1.0
	v_add_f32_e64 v9, v9, 1.0
	v_rcp_f32_e32 v8, v8
	v_rcp_f32_e32 v9, v9
	v_mfma_f32_16x16x32_bf16 v[4:7], v[20:23], v[92:95], v[4:7]
	v_mul_f32_e64 v0, v0, v8
	v_mul_f32_e64 v1, v1, v9
	v_cvt_pk_bf16_f32 v0, v0, v1
	ds_read_u16 v8, v214 offset:128
	ds_read_u16 v9, v214 offset:160
	ds_write_b16 v215, v0
	ds_write_b16_d16_hi v215, v0 offset:32
	ds_read_u16 v0, v214 offset:64
	ds_read_u16 v1, v214 offset:96
	ds_read_u16 v10, v214 offset:192
	ds_read_u16 v11, v214 offset:224
	s_waitcnt lgkmcnt(3)
	v_lshlrev_b32_e32 v0, 16, v0
	s_waitcnt lgkmcnt(2)
	v_lshlrev_b32_e32 v1, 16, v1
	v_pk_fma_f32 v[0:1], v[176:177], v[0:1], v[2:3]
	s_nop 0
	v_pk_mul_f32 v[2:3], v[0:1], v[0:1]
	s_nop 0
	v_pk_fma_f32 v[2:3], v[2:3], s[20:21], v[128:129] op_sel_hi:[1,0,0] neg_lo:[1,0,0] neg_hi:[1,0,0]
	s_nop 0
	v_pk_mul_f32 v[2:3], v[0:1], v[2:3]
	s_nop 0
	v_exp_f32_e32 v2, v2
	v_exp_f32_e32 v3, v3
	s_nop 0
	v_pk_add_f32 v[2:3], v[2:3], 1.0 op_sel_hi:[1,0]
	s_nop 0
	v_rcp_f32_e32 v2, v2
	v_rcp_f32_e32 v3, v3
	s_nop 0
	v_pk_mul_f32 v[0:1], v[0:1], v[2:3]
	s_nop 0
	v_cvt_pk_bf16_f32 v0, v0, v1
	ds_write_b16 v215, v0 offset:64
	ds_write_b16_d16_hi v215, v0 offset:96
	v_lshlrev_b32_e32 v1, 16, v9
	v_lshlrev_b32_e32 v0, 16, v8
	v_pk_fma_f32 v[0:1], v[176:177], v[0:1], v[4:5]
	v_add_u32_e32 v4, v145, v148
	v_pk_mul_f32 v[2:3], v[0:1], v[0:1]
	v_ashrrev_i32_e32 v5, 31, v4
	v_pk_fma_f32 v[2:3], v[2:3], s[20:21], v[128:129] op_sel_hi:[1,0,0] neg_lo:[1,0,0] neg_hi:[1,0,0]
	v_lshlrev_b64 v[4:5], 11, v[4:5]
	v_pk_mul_f32 v[2:3], v[0:1], v[2:3]
	v_lshl_add_u64 v[4:5], v[126:127], 0, v[4:5]
	v_exp_f32_e32 v2, v2
	v_exp_f32_e32 v3, v3
	s_nop 0
	v_pk_add_f32 v[2:3], v[2:3], 1.0 op_sel_hi:[1,0]
	s_nop 0
	v_rcp_f32_e32 v2, v2
	v_rcp_f32_e32 v3, v3
	s_nop 0
	v_pk_mul_f32 v[0:1], v[0:1], v[2:3]
	s_nop 0
	v_cvt_pk_bf16_f32 v0, v0, v1
	ds_write_b16 v215, v0 offset:512
	ds_write_b16_d16_hi v215, v0 offset:544
	s_waitcnt lgkmcnt(4)
	v_lshlrev_b32_e32 v1, 16, v11
	v_lshlrev_b32_e32 v0, 16, v10
	v_pk_fma_f32 v[0:1], v[176:177], v[0:1], v[6:7]
	s_nop 0
	v_pk_mul_f32 v[2:3], v[0:1], v[0:1]
	s_nop 0
	v_pk_fma_f32 v[2:3], v[2:3], s[20:21], v[128:129] op_sel_hi:[1,0,0] neg_lo:[1,0,0] neg_hi:[1,0,0]
	s_nop 0
	v_pk_mul_f32 v[2:3], v[0:1], v[2:3]
	s_nop 0
	v_exp_f32_e32 v2, v2
	v_exp_f32_e32 v3, v3
	s_nop 0
	v_pk_add_f32 v[2:3], v[2:3], 1.0 op_sel_hi:[1,0]
	s_nop 0
	v_rcp_f32_e32 v2, v2
	v_rcp_f32_e32 v3, v3
	s_nop 0
	v_pk_mul_f32 v[0:1], v[0:1], v[2:3]
	s_nop 0
	v_cvt_pk_bf16_f32 v0, v0, v1
	ds_write_b16 v215, v0 offset:576
	ds_write_b16_d16_hi v215, v0 offset:608
	s_waitcnt lgkmcnt(0)
	ds_read_b128 v[0:3], v147
	s_waitcnt lgkmcnt(0)
	global_store_dwordx4 v[4:5], v[0:3], off
	s_waitcnt lgkmcnt(0)
	s_cbranch_vccz .LBB0_329
	s_add_i32 s0, s36, 0x80
	s_cmp_gt_i32 s36, -1
	s_mov_b32 s36, s0
	s_barrier
	s_cbranch_scc0 .LBB0_323
